# aux H-row loop hand-written with prefetch; P5 output stores sc1 instead of nt; GEMM1 epilogue stores write-through
# speedup vs baseline: 1.0165x; 1.0165x over previous
; #define LAS __attribute__((address_space(3)))
; __device__ __forceinline__ const float* h_xrow(const Args& a, int r) { return (r < NBATCH * SEQ) ? a.in[I_XP] + (size_t)r * DM : a.in[I_XS] + (size_t)(r - NBATCH * SEQ) * DM; }
; __device__ __forceinline__ void p3_aux(const Args& a, const Ctx& C, int x) {
;     unsigned* ready = g_ctl + CW_HRDY; bf16* H = (bf16*)(a.ws + WS_H); unsigned char* H8 = a.ws + WS_H8; float* XR = (float*)(a.ws + WS_XRMS);
;     const int aw = x * NWAVES + C.wave, lane = C.lane;
;     LAS f32x4* GSL = (LAS f32x4*)C.lds; LAS f32x4* SHL = GSL + 512; int cond_l = -1;
;     for (int p0 = H_FIRST_AUX_PANEL; p0 < 33; p0 += 4) {
;         if (p0 < 32 && (p0 >> 3) != cond_l) { cond_l = p0 >> 3;
;             const float* MOD = (const float*)(a.ws + WS_MOD);
;             const f32x4 g4 = ((const f32x4*)a.in[I_GPRE])[C.tid], sc4 = ((const f32x4*)(MOD + (size_t)cond_l * 6144 + DM))[C.tid], sh4 = ((const f32x4*)(MOD + (size_t)cond_l * 6144))[C.tid];
;             GSL[C.tid] = g4 * (sc4 + 1.0f); SHL[C.tid] = sh4;
;             __syncthreads(); }
;         if (aw < 256) {
;             if (p0 < 32) {
;                 HRow x0, x1, x2, x3;
;                 h_load_nt(x0, h_xrow(a, 256 * p0 + aw), lane); h_load_nt(x1, h_xrow(a, 256 * (p0 + 1) + aw), lane);
;                 h_load_nt(x2, h_xrow(a, 256 * (p0 + 2) + aw), lane); h_load_nt(x3, h_xrow(a, 256 * (p0 + 3) + aw), lane);
;                 h_pin(x0); h_pin(x1); h_pin(x2); h_pin(x3);
.LBB0_309:
	s_mov_b64 s[44:45], s[64:65]
	s_mov_b64 s[36:37], s[56:57]
	s_mov_b64 s[46:47], s[66:67]
	s_mov_b64 s[48:49], s[68:69]
	s_mov_b64 s[50:51], s[70:71]
	s_mov_b64 s[38:39], s[58:59]
	v_writelane_b32 v249, s36, 21
	s_cmp_lt_i32 s86, 4
	s_cselect_b64 s[0:1], -1, 0
	v_writelane_b32 v249, s37, 22
	v_writelane_b32 v249, s38, 23
	v_writelane_b32 v249, s39, 24
	v_writelane_b32 v249, s40, 25
	v_writelane_b32 v249, s41, 26
	v_writelane_b32 v249, s42, 27
	v_writelane_b32 v249, s43, 28
	v_writelane_b32 v249, s44, 29
	v_writelane_b32 v249, s45, 30
	v_writelane_b32 v249, s46, 31
	s_cmp_gt_i32 s87, 3
	v_writelane_b32 v249, s47, 32
	s_cselect_b64 s[4:5], -1, 0
	v_writelane_b32 v249, s48, 33
	s_and_b64 s[0:1], s[0:1], s[4:5]
	v_writelane_b32 v249, s49, 34
	s_andn2_b64 vcc, exec, s[0:1]
	v_writelane_b32 v249, s50, 35
	v_writelane_b32 v249, s51, 36
	s_cbranch_vccnz .LBB0_946
	s_cmpk_gt_i32 s83, 0xdb
	s_mov_b64 s[4:5], -1
	s_cbranch_scc0 .LBB0_357
	s_add_i32 s28, s83, 0xffffff24
	s_add_u32 s0, s94, 0x2400000
	s_addc_u32 s1, s95, 0
	s_add_u32 s14, s94, 0xe500000
	s_addc_u32 s15, s95, 0
	s_lshl_b32 s2, s28, 3
	s_add_i32 s6, s82, s2
	s_cmpk_lt_i32 s6, 0x100
	s_cselect_b64 s[8:9], -1, 0
	s_mov_b32 s7, 0
	s_cmpk_gt_i32 s6, 0x7f
	s_cselect_b64 s[10:11], -1, 0
	s_add_i32 s24, s6, 0x2000
	s_mov_b32 s25, s7
	v_mov_b32_e32 v131, 0
	v_lshlrev_b32_e32 v130, 3, v162
	s_lshl_b64 s[26:27], s[24:25], 11
	s_lshl_b64 s[24:25], s[24:25], 12
	v_lshl_add_u64 v[132:133], s[0:1], 0, v[130:131]
	s_add_u32 s0, s0, s24
	s_addc_u32 s1, s1, s25
	v_lshl_add_u64 v[136:137], s[0:1], 0, v[130:131]
	s_add_u32 s0, s14, s26
	v_lshlrev_b32_e32 v2, 2, v162
	v_mov_b32_e32 v3, v131
	s_addc_u32 s1, s15, s27
	v_lshl_add_u64 v[138:139], s[0:1], 0, v[2:3]
	s_add_i32 s0, s6, 4
	s_lshl_b64 s[24:25], s[6:7], 13
	s_mul_hi_u32 s2, s0, 0x6000
	s_mul_i32 s29, s0, 0x6000
	s_lshl_b64 s[0:1], s[6:7], 2
	s_add_u32 s6, s94, s0
	s_addc_u32 s33, s95, s1
	v_lshl_add_u64 v[134:135], s[14:15], 0, v[2:3]
	s_add_u32 s14, s6, 0x22c8000
	s_addc_u32 s15, s33, 0
	s_add_u32 s1, s94, 0x1f00000
	s_addc_u32 s0, s95, 0
	s_add_u32 s24, s58, s24
	s_addc_u32 s25, s59, s25
	s_add_u32 s36, s1, s29
	v_lshlrev_b32_e32 v164, 4, v162
	v_mov_b32_e32 v165, v131
	s_addc_u32 s37, s0, s2
	v_lshl_add_u64 v[168:169], s[36:37], 0, v[164:165]
	s_mov_b64 s[36:37], 0x2000
	v_lshl_add_u64 v[170:171], v[168:169], 0, s[36:37]
	s_mov_b64 s[36:37], 0x3000
	v_lshl_add_u64 v[144:145], s[24:25], 0, v[164:165]
	s_mov_b64 s[24:25], 0x1000
	v_lshl_add_u64 v[154:155], s[12:13], 0, v[164:165]
	v_lshl_add_u64 v[172:173], v[168:169], 0, s[36:37]
	s_mov_b64 s[36:37], 0x3400
	v_lshl_add_u64 v[146:147], v[144:145], 0, s[24:25]
	v_lshl_add_u64 v[156:157], v[154:155], 0, s[24:25]
	v_lshl_add_u64 v[174:175], v[168:169], 0, s[36:37]
	s_mov_b64 s[36:37], 0x3800
	v_lshl_add_u64 v[180:181], v[168:169], 0, s[24:25]
	s_add_u32 s24, s6, 0x22c4c00
	v_lshlrev_b32_e32 v130, 4, v0
	s_mov_b64 s[26:27], 0x1400
	s_mov_b64 s[30:31], 0x1800
	s_mov_b64 s[34:35], 0x1c00
	v_lshl_add_u64 v[176:177], v[168:169], 0, s[36:37]
	s_mov_b64 s[36:37], 0x3c00
	s_addc_u32 s25, s33, 0
	s_lshl_b32 s2, s83, 3
	v_mbcnt_lo_u32_b32 v2, -1, 0
	v_cmp_eq_u32_e64 s[4:5], 0, v162
	v_add_u32_e32 v193, 0, v164
	v_lshl_add_u64 v[140:141], s[56:57], 0, v[164:165]
	v_lshl_add_u64 v[142:143], s[12:13], 0, v[130:131]
	v_add_u32_e32 v163, 0, v130
	v_lshl_add_u64 v[148:149], v[144:145], 0, s[26:27]
	v_lshl_add_u64 v[150:151], v[144:145], 0, s[30:31]
	v_lshl_add_u64 v[152:153], v[144:145], 0, s[34:35]
	v_lshl_add_u64 v[158:159], v[154:155], 0, s[26:27]
	v_lshl_add_u64 v[160:161], v[154:155], 0, s[30:31]
	v_lshl_add_u64 v[166:167], v[154:155], 0, s[34:35]
	v_lshl_add_u64 v[178:179], v[168:169], 0, s[36:37]
	v_lshl_add_u64 v[182:183], v[168:169], 0, s[26:27]
	v_lshl_add_u64 v[184:185], v[168:169], 0, s[30:31]
	v_lshl_add_u64 v[186:187], v[168:169], 0, s[34:35]
	s_add_i32 s29, s82, s2
	s_mov_b32 s6, -1
	s_mov_b64 s[26:27], 0
	s_mov_b32 s42, 19
	s_movk_i32 s33, 0x1000
	v_lshlrev_b32_e32 v188, 4, v0
	v_lshlrev_b32_e32 v130, 4, v162
	v_mov_b32_e32 v165, 0x358637bd
	s_mov_b32 s43, 0xc3e00000
	v_mov_b64_e32 v[190:191], 0
	v_mov_b32_e32 v198, 0xb000
	v_mbcnt_hi_u32_b32 v199, -1, v2
	v_mov_b32_e32 v200, 0x43e00000
	s_andn2_b64 vcc, exec, s[8:9]
	s_cbranch_vccnz .Laux_noprefetch
	s_add_i32 s2, s29, 0x920
	s_lshl_b32 s31, s2, 13
	s_add_u32 s34, s56, s31
	s_addc_u32 s35, s57, 0
	s_add_u32 s36, s34, 0x1000
	s_addc_u32 s37, s35, 0
	global_load_dwordx4 v[2:5], v130, s[34:35] nt
	global_load_dwordx4 v[6:9], v130, s[34:35] offset:1024 nt
	global_load_dwordx4 v[10:13], v130, s[34:35] offset:2048 nt
	global_load_dwordx4 v[14:17], v130, s[34:35] offset:3072 nt
	global_load_dwordx4 v[18:21], v130, s[36:37] nt
	global_load_dwordx4 v[22:25], v130, s[36:37] offset:1024 nt
	global_load_dwordx4 v[26:29], v130, s[36:37] offset:2048 nt
	global_load_dwordx4 v[30:33], v130, s[36:37] offset:3072 nt
	s_add_i32 s30, s2, 256
	s_lshl_b32 s31, s30, 13
	s_add_u32 s34, s56, s31
	s_addc_u32 s35, s57, 0
	s_add_u32 s36, s34, 0x1000
	s_addc_u32 s37, s35, 0
	global_load_dwordx4 v[34:37], v130, s[34:35] nt
	global_load_dwordx4 v[38:41], v130, s[34:35] offset:1024 nt
	global_load_dwordx4 v[42:45], v130, s[34:35] offset:2048 nt
	global_load_dwordx4 v[46:49], v130, s[34:35] offset:3072 nt
	global_load_dwordx4 v[50:53], v130, s[36:37] nt
	global_load_dwordx4 v[54:57], v130, s[36:37] offset:1024 nt
	global_load_dwordx4 v[58:61], v130, s[36:37] offset:2048 nt
	global_load_dwordx4 v[62:65], v130, s[36:37] offset:3072 nt
	s_add_i32 s30, s2, 512
	s_lshl_b32 s31, s30, 13
	s_add_u32 s34, s56, s31
	s_addc_u32 s35, s57, 0
	s_add_u32 s36, s34, 0x1000
	s_addc_u32 s37, s35, 0
	global_load_dwordx4 v[66:69], v130, s[34:35] nt
	global_load_dwordx4 v[70:73], v130, s[34:35] offset:1024 nt
	global_load_dwordx4 v[74:77], v130, s[34:35] offset:2048 nt
	global_load_dwordx4 v[78:81], v130, s[34:35] offset:3072 nt
	global_load_dwordx4 v[82:85], v130, s[36:37] nt
	global_load_dwordx4 v[86:89], v130, s[36:37] offset:1024 nt
	global_load_dwordx4 v[90:93], v130, s[36:37] offset:2048 nt
	global_load_dwordx4 v[94:97], v130, s[36:37] offset:3072 nt
	s_add_i32 s30, s2, 768
	s_lshl_b32 s31, s30, 13
	s_add_u32 s34, s56, s31
	s_addc_u32 s35, s57, 0
	s_add_u32 s36, s34, 0x1000
	s_addc_u32 s37, s35, 0
	global_load_dwordx4 v[98:101], v130, s[34:35] nt
	global_load_dwordx4 v[102:105], v130, s[34:35] offset:1024 nt
	global_load_dwordx4 v[106:109], v130, s[34:35] offset:2048 nt
	global_load_dwordx4 v[110:113], v130, s[34:35] offset:3072 nt
	global_load_dwordx4 v[114:117], v130, s[36:37] nt
	global_load_dwordx4 v[118:121], v130, s[36:37] offset:1024 nt
	global_load_dwordx4 v[122:125], v130, s[36:37] offset:2048 nt
	global_load_dwordx4 v[126:129], v130, s[36:37] offset:3072 nt
; #define LAS __attribute__((address_space(3)))
; __device__ __forceinline__ const float* h_xrow(const Args& a, int r) { return (r < NBATCH * SEQ) ? a.in[I_XP] + (size_t)r * DM : a.in[I_XS] + (size_t)(r - NBATCH * SEQ) * DM; }
; template <bool WT = true> __device__ __forceinline__ void h_store_tab(const HRow& X, const LAS f32x4* GS, const LAS f32x4* SH, bf16* hrow, unsigned char* h8row, int lane, float* rms_slot) {
;     float ss = 0.f;
; #pragma unroll
;     for (int j = 0; j < 8; ++j) ss += (X.v[j][0] * X.v[j][0] + X.v[j][1] * X.v[j][1]) + (X.v[j][2] * X.v[j][2] + X.v[j][3] * X.v[j][3]);
;     const float ms = wave_sum(ss) * (1.0f / DM) + EPS, rr = __builtin_amdgcn_rsqf(ms);
; __device__ __forceinline__ void p3_aux(const Args& a, const Ctx& C, int x) {
;     ...
;     for (int p0 = H_FIRST_AUX_PANEL; p0 < 33; p0 += 4) {
;         if (p0 < 32 && (p0 >> 3) != cond_l) { cond_l = p0 >> 3;
;             const float* MOD = (const float*)(a.ws + WS_MOD);
;             const f32x4 g4 = ((const f32x4*)a.in[I_GPRE])[C.tid], sc4 = ((const f32x4*)(MOD + (size_t)cond_l * 6144 + DM))[C.tid], sh4 = ((const f32x4*)(MOD + (size_t)cond_l * 6144))[C.tid];
;             GSL[C.tid] = g4 * (sc4 + 1.0f); SHL[C.tid] = sh4;
;             __syncthreads(); }
;         if (aw < 256) {
;             if (p0 < 32) {
;                 HRow x0, x1, x2, x3;
;                 h_load_nt(x0, h_xrow(a, 256 * p0 + aw), lane); h_load_nt(x1, h_xrow(a, 256 * (p0 + 1) + aw), lane);
;                 h_load_nt(x2, h_xrow(a, 256 * (p0 + 2) + aw), lane); h_load_nt(x3, h_xrow(a, 256 * (p0 + 3) + aw), lane);
;                 h_pin(x0); h_pin(x1); h_pin(x2); h_pin(x3);
;                 h_store_tab(x0, GSL, SHL, H + (size_t)(256 * p0 + aw) * DM, H8 + (size_t)(256 * p0 + aw) * DM, lane, XR + 256 * p0 + aw);
.Laux_noprefetch:
	s_branch .LBB0_313
.LBB0_312:
	s_or_b64 exec, exec, s[30:31]
	s_add_u32 s24, s24, 0x1000
	s_addc_u32 s25, s25, 0
	s_add_u32 s26, s26, 0x400
	s_addc_u32 s27, s27, 0
	s_add_i32 s2, s42, 4
	s_add_i32 s30, s42, -3
	s_cmp_gt_u32 s30, 28
	s_mov_b32 s42, s2
	s_cbranch_scc1 .LBB0_348
.LBB0_313:
	s_cmpk_lg_i32 s26, 0x1000
	s_cselect_b64 s[30:31], -1, 0
	s_cmpk_eq_i32 s26, 0x1000
	s_cbranch_scc1 .LBB0_316
	s_add_i32 s2, s42, -3
	s_lshr_b32 s2, s2, 3
	s_cmp_eq_u32 s2, s6
	s_cbranch_scc1 .LBB0_316
	s_mul_i32 s6, s2, 0x1800
	s_lshl_b64 s[34:35], s[6:7], 2
	s_add_u32 s34, s1, s34
	s_addc_u32 s35, s0, s35
	v_mov_b32_e32 v189, v131
	v_lshl_add_u64 v[214:215], s[34:35], 0, v[188:189]
	v_add_co_u32_e32 v214, vcc, 0x2000, v214
	s_mov_b32 s6, s2
	s_nop 0
	v_addc_co_u32_e32 v215, vcc, 0, v215, vcc
	global_load_dwordx4 v[214:217], v[214:215], off
	s_nop 0
	global_load_dwordx4 v[218:221], v188, s[34:35]
	global_load_dwordx4 v[222:225], v[142:143], off
	s_waitcnt vmcnt(2)
	v_pk_add_f32 v[216:217], v[216:217], 1.0 op_sel_hi:[1,0]
	v_pk_add_f32 v[214:215], v[214:215], 1.0 op_sel_hi:[1,0]
	s_waitcnt vmcnt(0)
	v_pk_mul_f32 v[216:217], v[224:225], v[216:217]
	v_pk_mul_f32 v[214:215], v[222:223], v[214:215]
	ds_write_b128 v163, v[218:221] offset:8192
	ds_write_b128 v163, v[214:217]
	s_waitcnt lgkmcnt(0)
	s_barrier
.LBB0_316:
	s_andn2_b64 vcc, exec, s[8:9]
	s_cbranch_vccnz .LBB0_334
	s_andn2_b64 vcc, exec, s[30:31]
	s_mov_b64 s[30:31], -1
	s_cbranch_vccnz .LBB0_327
	s_add_i32 s2, s29, s26
	s_addk_i32 s2, 0x920
	v_lshrrev_b32_e32 v246, 1, v130
	v_lshrrev_b32_e32 v247, 2, v130
	s_lshl_b32 s31, s2, 12
	s_add_u32 s44, s94, s31
	s_addc_u32 s45, s95, 0
	s_add_u32 s44, s44, 0x2400000
	s_addc_u32 s45, s45, 0
	s_lshr_b32 s31, s31, 1
	s_add_u32 s52, s94, s31
	s_addc_u32 s53, s95, 0
	s_add_u32 s52, s52, 0xe500000
	s_addc_u32 s53, s53, 0
	s_add_i32 s30, s2, 256
	s_lshl_b32 s31, s30, 12
	s_add_u32 s46, s94, s31
	s_addc_u32 s47, s95, 0
	s_add_u32 s46, s46, 0x2400000
	s_addc_u32 s47, s47, 0
	s_lshr_b32 s31, s31, 1
	s_add_u32 s54, s94, s31
	s_addc_u32 s55, s95, 0
	s_add_u32 s54, s54, 0xe500000
	s_addc_u32 s55, s55, 0
	s_add_i32 s30, s2, 512
	s_lshl_b32 s31, s30, 12
	s_add_u32 s48, s94, s31
	s_addc_u32 s49, s95, 0
	s_add_u32 s48, s48, 0x2400000
	s_addc_u32 s49, s49, 0
	s_lshr_b32 s31, s31, 1
	s_add_u32 s60, s94, s31
	s_addc_u32 s61, s95, 0
	s_add_u32 s60, s60, 0xe500000
	s_addc_u32 s61, s61, 0
	s_add_i32 s30, s2, 768
	s_lshl_b32 s31, s30, 12
	s_add_u32 s50, s94, s31
	s_addc_u32 s51, s95, 0
	s_add_u32 s50, s50, 0x2400000
	s_addc_u32 s51, s51, 0
	s_lshr_b32 s31, s31, 1
	s_add_u32 s62, s94, s31
	s_addc_u32 s63, s95, 0
	s_add_u32 s62, s62, 0xe500000
	s_addc_u32 s63, s63, 0
	ds_read_b128 v[214:217], v193
	ds_read_b128 v[218:221], v193 offset:8192
	s_waitcnt vmcnt(24)
	v_mul_f32_e32 v202, v3, v3
	v_mul_f32_e32 v210, v5, v5
	v_fmac_f32_e32 v202, v2, v2
	v_fmac_f32_e32 v210, v4, v4
	v_add_f32_e32 v202, v202, v210
	v_mul_f32_e32 v203, v7, v7
	v_mul_f32_e32 v210, v9, v9
	v_fmac_f32_e32 v203, v6, v6
	v_fmac_f32_e32 v210, v8, v8
	v_add_f32_e32 v203, v203, v210
	v_add_f32_e32 v202, v202, v203
	v_mul_f32_e32 v203, v11, v11
	v_mul_f32_e32 v210, v13, v13
	v_fmac_f32_e32 v203, v10, v10
	v_fmac_f32_e32 v210, v12, v12
	v_add_f32_e32 v203, v203, v210
	v_add_f32_e32 v202, v202, v203
	v_mul_f32_e32 v203, v15, v15
	v_mul_f32_e32 v210, v17, v17
	v_fmac_f32_e32 v203, v14, v14
	v_fmac_f32_e32 v210, v16, v16
	v_add_f32_e32 v203, v203, v210
	v_add_f32_e32 v202, v202, v203
	v_mul_f32_e32 v203, v19, v19
	v_mul_f32_e32 v210, v21, v21
	v_fmac_f32_e32 v203, v18, v18
	v_fmac_f32_e32 v210, v20, v20
	v_add_f32_e32 v203, v203, v210
	v_add_f32_e32 v202, v202, v203
	v_mul_f32_e32 v203, v23, v23
	v_mul_f32_e32 v210, v25, v25
	v_fmac_f32_e32 v203, v22, v22
	v_fmac_f32_e32 v210, v24, v24
	v_add_f32_e32 v203, v203, v210
	v_add_f32_e32 v202, v202, v203
	v_mul_f32_e32 v203, v27, v27
	v_mul_f32_e32 v210, v29, v29
	v_fmac_f32_e32 v203, v26, v26
	v_fmac_f32_e32 v210, v28, v28
	v_add_f32_e32 v203, v203, v210
	v_add_f32_e32 v202, v202, v203
	v_mul_f32_e32 v203, v31, v31
	v_mul_f32_e32 v210, v33, v33
	v_fmac_f32_e32 v203, v30, v30
	v_fmac_f32_e32 v210, v32, v32
	v_add_f32_e32 v203, v203, v210
	v_add_f32_e32 v202, v202, v203
	s_waitcnt vmcnt(16)
	v_mul_f32_e32 v204, v35, v35
	v_mul_f32_e32 v211, v37, v37
	v_fmac_f32_e32 v204, v34, v34
	v_fmac_f32_e32 v211, v36, v36
	v_add_f32_e32 v204, v204, v211
	v_mul_f32_e32 v205, v39, v39
	v_mul_f32_e32 v211, v41, v41
	v_fmac_f32_e32 v205, v38, v38
	v_fmac_f32_e32 v211, v40, v40
	v_add_f32_e32 v205, v205, v211
	v_add_f32_e32 v204, v204, v205
	v_mul_f32_e32 v205, v43, v43
	v_mul_f32_e32 v211, v45, v45
	v_fmac_f32_e32 v205, v42, v42
	v_fmac_f32_e32 v211, v44, v44
	v_add_f32_e32 v205, v205, v211
	v_add_f32_e32 v204, v204, v205
	v_mul_f32_e32 v205, v47, v47
	v_mul_f32_e32 v211, v49, v49
	v_fmac_f32_e32 v205, v46, v46
	v_fmac_f32_e32 v211, v48, v48
	v_add_f32_e32 v205, v205, v211
	v_add_f32_e32 v204, v204, v205
	v_mul_f32_e32 v205, v51, v51
	v_mul_f32_e32 v211, v53, v53
	v_fmac_f32_e32 v205, v50, v50
	v_fmac_f32_e32 v211, v52, v52
	v_add_f32_e32 v205, v205, v211
	v_add_f32_e32 v204, v204, v205
	v_mul_f32_e32 v205, v55, v55
	v_mul_f32_e32 v211, v57, v57
	v_fmac_f32_e32 v205, v54, v54
	v_fmac_f32_e32 v211, v56, v56
	v_add_f32_e32 v205, v205, v211
	v_add_f32_e32 v204, v204, v205
	v_mul_f32_e32 v205, v59, v59
	v_mul_f32_e32 v211, v61, v61
	v_fmac_f32_e32 v205, v58, v58
	v_fmac_f32_e32 v211, v60, v60
	v_add_f32_e32 v205, v205, v211
	v_add_f32_e32 v204, v204, v205
	v_mul_f32_e32 v205, v63, v63
	v_mul_f32_e32 v211, v65, v65
	v_fmac_f32_e32 v205, v62, v62
	v_fmac_f32_e32 v211, v64, v64
	v_add_f32_e32 v205, v205, v211
	v_add_f32_e32 v204, v204, v205
	s_waitcnt vmcnt(8)
; #define LAS __attribute__((address_space(3)))
; __device__ __forceinline__ float wave_sum(float v) {
; #pragma unroll
;     for (int o = 1; o < 64; o <<= 1) v += __shfl_xor(v, o);
;     return v;
; }
; template <bool WT = true> __device__ __forceinline__ void h_store_tab(const HRow& X, const LAS f32x4* GS, const LAS f32x4* SH, bf16* hrow, unsigned char* h8row, int lane, float* rms_slot) {
;     float ss = 0.f;
; #pragma unroll
;     for (int j = 0; j < 8; ++j) ss += (X.v[j][0] * X.v[j][0] + X.v[j][1] * X.v[j][1]) + (X.v[j][2] * X.v[j][2] + X.v[j][3] * X.v[j][3]);
;     const float ms = wave_sum(ss) * (1.0f / DM) + EPS, rr = __builtin_amdgcn_rsqf(ms);
;     if (lane == 0) *rms_slot = ms * rr;
	v_mul_f32_e32 v206, v67, v67
	v_mul_f32_e32 v212, v69, v69
	v_fmac_f32_e32 v206, v66, v66
	v_fmac_f32_e32 v212, v68, v68
	v_add_f32_e32 v206, v206, v212
	v_mul_f32_e32 v207, v71, v71
	v_mul_f32_e32 v212, v73, v73
	v_fmac_f32_e32 v207, v70, v70
	v_fmac_f32_e32 v212, v72, v72
	v_add_f32_e32 v207, v207, v212
	v_add_f32_e32 v206, v206, v207
	v_mul_f32_e32 v207, v75, v75
	v_mul_f32_e32 v212, v77, v77
	v_fmac_f32_e32 v207, v74, v74
	v_fmac_f32_e32 v212, v76, v76
	v_add_f32_e32 v207, v207, v212
	v_add_f32_e32 v206, v206, v207
	v_mul_f32_e32 v207, v79, v79
	v_mul_f32_e32 v212, v81, v81
	v_fmac_f32_e32 v207, v78, v78
	v_fmac_f32_e32 v212, v80, v80
	v_add_f32_e32 v207, v207, v212
	v_add_f32_e32 v206, v206, v207
	v_mul_f32_e32 v207, v83, v83
	v_mul_f32_e32 v212, v85, v85
	v_fmac_f32_e32 v207, v82, v82
	v_fmac_f32_e32 v212, v84, v84
	v_add_f32_e32 v207, v207, v212
	v_add_f32_e32 v206, v206, v207
	v_mul_f32_e32 v207, v87, v87
	v_mul_f32_e32 v212, v89, v89
	v_fmac_f32_e32 v207, v86, v86
	v_fmac_f32_e32 v212, v88, v88
	v_add_f32_e32 v207, v207, v212
	v_add_f32_e32 v206, v206, v207
	v_mul_f32_e32 v207, v91, v91
	v_mul_f32_e32 v212, v93, v93
	v_fmac_f32_e32 v207, v90, v90
	v_fmac_f32_e32 v212, v92, v92
	v_add_f32_e32 v207, v207, v212
	v_add_f32_e32 v206, v206, v207
	v_mul_f32_e32 v207, v95, v95
	v_mul_f32_e32 v212, v97, v97
	v_fmac_f32_e32 v207, v94, v94
	v_fmac_f32_e32 v212, v96, v96
	v_add_f32_e32 v207, v207, v212
	v_add_f32_e32 v206, v206, v207
	s_waitcnt vmcnt(0)
	v_mul_f32_e32 v208, v99, v99
	v_mul_f32_e32 v213, v101, v101
	v_fmac_f32_e32 v208, v98, v98
	v_fmac_f32_e32 v213, v100, v100
	v_add_f32_e32 v208, v208, v213
	v_mul_f32_e32 v209, v103, v103
	v_mul_f32_e32 v213, v105, v105
	v_fmac_f32_e32 v209, v102, v102
	v_fmac_f32_e32 v213, v104, v104
	v_add_f32_e32 v209, v209, v213
	v_add_f32_e32 v208, v208, v209
	v_mul_f32_e32 v209, v107, v107
	v_mul_f32_e32 v213, v109, v109
	v_fmac_f32_e32 v209, v106, v106
	v_fmac_f32_e32 v213, v108, v108
	v_add_f32_e32 v209, v209, v213
	v_add_f32_e32 v208, v208, v209
	v_mul_f32_e32 v209, v111, v111
	v_mul_f32_e32 v213, v113, v113
	v_fmac_f32_e32 v209, v110, v110
	v_fmac_f32_e32 v213, v112, v112
	v_add_f32_e32 v209, v209, v213
	v_add_f32_e32 v208, v208, v209
	v_mul_f32_e32 v209, v115, v115
	v_mul_f32_e32 v213, v117, v117
	v_fmac_f32_e32 v209, v114, v114
	v_fmac_f32_e32 v213, v116, v116
	v_add_f32_e32 v209, v209, v213
	v_add_f32_e32 v208, v208, v209
	v_mul_f32_e32 v209, v119, v119
	v_mul_f32_e32 v213, v121, v121
	v_fmac_f32_e32 v209, v118, v118
	v_fmac_f32_e32 v213, v120, v120
	v_add_f32_e32 v209, v209, v213
	v_add_f32_e32 v208, v208, v209
	v_mul_f32_e32 v209, v123, v123
	v_mul_f32_e32 v213, v125, v125
	v_fmac_f32_e32 v209, v122, v122
	v_fmac_f32_e32 v213, v124, v124
	v_add_f32_e32 v209, v209, v213
	v_add_f32_e32 v208, v208, v209
	v_mul_f32_e32 v209, v127, v127
	v_mul_f32_e32 v213, v129, v129
	v_fmac_f32_e32 v209, v126, v126
	v_fmac_f32_e32 v213, v128, v128
	v_add_f32_e32 v209, v209, v213
	v_add_f32_e32 v208, v208, v209
	s_nop 1
	v_add_f32_dpp v202, v202, v202 quad_perm:[1,0,3,2] row_mask:0xf bank_mask:0xf
	v_add_f32_dpp v204, v204, v204 quad_perm:[1,0,3,2] row_mask:0xf bank_mask:0xf
	v_add_f32_dpp v206, v206, v206 quad_perm:[1,0,3,2] row_mask:0xf bank_mask:0xf
	v_add_f32_dpp v208, v208, v208 quad_perm:[1,0,3,2] row_mask:0xf bank_mask:0xf
	v_add_f32_dpp v202, v202, v202 quad_perm:[2,3,0,1] row_mask:0xf bank_mask:0xf
	v_add_f32_dpp v204, v204, v204 quad_perm:[2,3,0,1] row_mask:0xf bank_mask:0xf
	v_add_f32_dpp v206, v206, v206 quad_perm:[2,3,0,1] row_mask:0xf bank_mask:0xf
	v_add_f32_dpp v208, v208, v208 quad_perm:[2,3,0,1] row_mask:0xf bank_mask:0xf
	v_add_f32_dpp v202, v202, v202 row_half_mirror row_mask:0xf bank_mask:0xf
	v_add_f32_dpp v204, v204, v204 row_half_mirror row_mask:0xf bank_mask:0xf
	v_add_f32_dpp v206, v206, v206 row_half_mirror row_mask:0xf bank_mask:0xf
	v_add_f32_dpp v208, v208, v208 row_half_mirror row_mask:0xf bank_mask:0xf
	v_add_f32_dpp v202, v202, v202 row_mirror row_mask:0xf bank_mask:0xf
	v_add_f32_dpp v204, v204, v204 row_mirror row_mask:0xf bank_mask:0xf
	v_add_f32_dpp v206, v206, v206 row_mirror row_mask:0xf bank_mask:0xf
	v_add_f32_dpp v208, v208, v208 row_mirror row_mask:0xf bank_mask:0xf
	v_mov_b32_e32 v203, v202
	v_mov_b32_e32 v205, v204
	v_mov_b32_e32 v207, v206
	v_mov_b32_e32 v209, v208
	s_nop 1
	v_permlane16_swap_b32_e32 v203, v202
	v_permlane16_swap_b32_e32 v205, v204
	v_permlane16_swap_b32_e32 v207, v206
	v_permlane16_swap_b32_e32 v209, v208
	s_nop 1
	v_add_f32_e32 v202, v202, v203
	v_add_f32_e32 v204, v204, v205
	v_add_f32_e32 v206, v206, v207
	v_add_f32_e32 v208, v208, v209
	v_mov_b32_e32 v203, v202
	v_mov_b32_e32 v205, v204
	v_mov_b32_e32 v207, v206
	v_mov_b32_e32 v209, v208
	s_nop 1
	v_permlane32_swap_b32_e32 v203, v202
	v_permlane32_swap_b32_e32 v205, v204
	v_permlane32_swap_b32_e32 v207, v206
	v_permlane32_swap_b32_e32 v209, v208
	s_nop 1
	v_add_f32_e32 v202, v202, v203
	v_add_f32_e32 v204, v204, v205
	v_add_f32_e32 v206, v206, v207
	v_add_f32_e32 v208, v208, v209
	v_fmamk_f32 v210, v202, 0x3a000000, v165
	v_fmamk_f32 v211, v204, 0x3a000000, v165
	v_fmamk_f32 v212, v206, 0x3a000000, v165
	v_fmamk_f32 v213, v208, 0x3a000000, v165
	v_rsq_f32_e32 v202, v210
	v_rsq_f32_e32 v204, v211
	v_rsq_f32_e32 v206, v212
	v_rsq_f32_e32 v208, v213
	s_mov_b64 s[38:39], exec
	s_mov_b64 exec, s[4:5]
	v_mul_f32_e32 v235, v210, v202
	v_mul_f32_e32 v243, v211, v204
	v_mul_f32_e32 v189, v212, v206
	v_mul_f32_e32 v192, v213, v208
	global_store_dword v131, v235, s[24:25] offset:-3072
	global_store_dword v131, v243, s[24:25] offset:-2048
	global_store_dword v131, v189, s[24:25] offset:-1024
	global_store_dword v131, v192, s[24:25] offset:0
	s_mov_b64 exec, s[38:39]
	ds_read_b128 v[222:225], v193 offset:1024
	ds_read_b128 v[226:229], v193 offset:9216
	s_waitcnt lgkmcnt(2)
; #define GAS __attribute__((address_space(1)))
; __device__ __forceinline__ unsigned pk2(float lo, float hi) { return pg8::cvt_pk_bf16(lo, hi); }
; __device__ __forceinline__ unsigned pk4f8(float a, float b, float c, float d) { int p = __builtin_amdgcn_cvt_pk_fp8_f32(sat8(a), sat8(b), 0, false); p = __builtin_amdgcn_cvt_pk_fp8_f32(sat8(c), sat8(d), p, true); return (unsigned)p; }
; template <bool WT = true> __device__ __forceinline__ void h_store_tab(const HRow& X, const LAS f32x4* GS, const LAS f32x4* SH, bf16* hrow, unsigned char* h8row, int lane, float* rms_slot) {
;     ...
; #pragma unroll
;     for (int j = 0; j < 8; ++j) { const f32x4 h = X.v[j] * rr * GS[lane + 64 * j] + SH[lane + 64 * j]; const unsigned w0 = pk2(h[0], h[1]), w1 = pk2(h[2], h[3]);
;         const unsigned w8 = pk4f8(h[0], h[1], h[2], h[3]);
;         if (WT) { __hip_atomic_store((unsigned long long*)(hrow) + lane + 64 * j, ((unsigned long long)w1 << 32) | w0, RLX_AGENT); __hip_atomic_store((unsigned*)h8row + lane + 64 * j, w8, RLX_AGENT); }
;         else { ((GAS v2u*)hrow)[lane + 64 * j] = (v2u){w0, w1}; ((unsigned*)h8row)[lane + 64 * j] = w8; } }
	v_pk_mul_f32 v[2:3], v[2:3], v[202:203] op_sel_hi:[1,0]
	v_pk_mul_f32 v[4:5], v[4:5], v[202:203] op_sel_hi:[1,0]
	v_pk_fma_f32 v[2:3], v[2:3], v[214:215], v[218:219]
	v_pk_fma_f32 v[4:5], v[4:5], v[216:217], v[220:221]
	v_med3_f32 v230, v2, s43, v200
	v_med3_f32 v231, v3, s43, v200
	v_med3_f32 v232, v4, s43, v200
	v_med3_f32 v233, v5, s43, v200
	v_cvt_pk_fp8_f32 v234, v230, v231
	v_cvt_pk_bf16_f32 v236, v2, v3
	v_cvt_pk_bf16_f32 v237, v4, v5
	v_cvt_pk_fp8_f32 v234, v232, v233 op_sel:[0,0,1]
	global_store_dwordx2 v246, v[236:237], s[44:45] sc1
	global_store_dword v247, v234, s[52:53] sc1
	v_pk_mul_f32 v[34:35], v[34:35], v[204:205] op_sel_hi:[1,0]
	v_pk_mul_f32 v[36:37], v[36:37], v[204:205] op_sel_hi:[1,0]
	v_pk_fma_f32 v[34:35], v[34:35], v[214:215], v[218:219]
	v_pk_fma_f32 v[36:37], v[36:37], v[216:217], v[220:221]
	v_med3_f32 v238, v34, s43, v200
	v_med3_f32 v239, v35, s43, v200
	v_med3_f32 v240, v36, s43, v200
	v_med3_f32 v241, v37, s43, v200
	v_cvt_pk_fp8_f32 v242, v238, v239
	v_cvt_pk_bf16_f32 v244, v34, v35
	v_cvt_pk_bf16_f32 v245, v36, v37
	v_cvt_pk_fp8_f32 v242, v240, v241 op_sel:[0,0,1]
	global_store_dwordx2 v246, v[244:245], s[46:47] sc1
	global_store_dword v247, v242, s[54:55] sc1
	v_pk_mul_f32 v[66:67], v[66:67], v[206:207] op_sel_hi:[1,0]
	v_pk_mul_f32 v[68:69], v[68:69], v[206:207] op_sel_hi:[1,0]
	v_pk_fma_f32 v[66:67], v[66:67], v[214:215], v[218:219]
	v_pk_fma_f32 v[68:69], v[68:69], v[216:217], v[220:221]
	v_med3_f32 v230, v66, s43, v200
	v_med3_f32 v231, v67, s43, v200
	v_med3_f32 v232, v68, s43, v200
	v_med3_f32 v233, v69, s43, v200
	v_cvt_pk_fp8_f32 v234, v230, v231
	v_cvt_pk_bf16_f32 v236, v66, v67
	v_cvt_pk_bf16_f32 v237, v68, v69
	v_cvt_pk_fp8_f32 v234, v232, v233 op_sel:[0,0,1]
	global_store_dwordx2 v246, v[236:237], s[48:49] sc1
	global_store_dword v247, v234, s[60:61] sc1
	v_pk_mul_f32 v[98:99], v[98:99], v[208:209] op_sel_hi:[1,0]
	v_pk_mul_f32 v[100:101], v[100:101], v[208:209] op_sel_hi:[1,0]
	v_pk_fma_f32 v[98:99], v[98:99], v[214:215], v[218:219]
	v_pk_fma_f32 v[100:101], v[100:101], v[216:217], v[220:221]
	v_med3_f32 v238, v98, s43, v200
	v_med3_f32 v239, v99, s43, v200
	v_med3_f32 v240, v100, s43, v200
	v_med3_f32 v241, v101, s43, v200
	v_cvt_pk_fp8_f32 v242, v238, v239
	v_cvt_pk_bf16_f32 v244, v98, v99
	v_cvt_pk_bf16_f32 v245, v100, v101
	v_cvt_pk_fp8_f32 v242, v240, v241 op_sel:[0,0,1]
	global_store_dwordx2 v246, v[244:245], s[50:51] sc1
	global_store_dword v247, v242, s[62:63] sc1
	ds_read_b128 v[214:217], v193 offset:2048
	ds_read_b128 v[218:221], v193 offset:10240
	s_waitcnt lgkmcnt(2)
	v_pk_mul_f32 v[6:7], v[6:7], v[202:203] op_sel_hi:[1,0]
	v_pk_mul_f32 v[8:9], v[8:9], v[202:203] op_sel_hi:[1,0]
	v_pk_fma_f32 v[6:7], v[6:7], v[222:223], v[226:227]
	v_pk_fma_f32 v[8:9], v[8:9], v[224:225], v[228:229]
	v_med3_f32 v230, v6, s43, v200
	v_med3_f32 v231, v7, s43, v200
	v_med3_f32 v232, v8, s43, v200
	v_med3_f32 v233, v9, s43, v200
	v_cvt_pk_fp8_f32 v234, v230, v231
	v_cvt_pk_bf16_f32 v236, v6, v7
	v_cvt_pk_bf16_f32 v237, v8, v9
	v_cvt_pk_fp8_f32 v234, v232, v233 op_sel:[0,0,1]
	global_store_dwordx2 v246, v[236:237], s[44:45] offset:512 sc1
	global_store_dword v247, v234, s[52:53] offset:256 sc1
	v_pk_mul_f32 v[38:39], v[38:39], v[204:205] op_sel_hi:[1,0]
	v_pk_mul_f32 v[40:41], v[40:41], v[204:205] op_sel_hi:[1,0]
	v_pk_fma_f32 v[38:39], v[38:39], v[222:223], v[226:227]
	v_pk_fma_f32 v[40:41], v[40:41], v[224:225], v[228:229]
	v_med3_f32 v238, v38, s43, v200
	v_med3_f32 v239, v39, s43, v200
	v_med3_f32 v240, v40, s43, v200
	v_med3_f32 v241, v41, s43, v200
	v_cvt_pk_fp8_f32 v242, v238, v239
	v_cvt_pk_bf16_f32 v244, v38, v39
	v_cvt_pk_bf16_f32 v245, v40, v41
	v_cvt_pk_fp8_f32 v242, v240, v241 op_sel:[0,0,1]
	global_store_dwordx2 v246, v[244:245], s[46:47] offset:512 sc1
	global_store_dword v247, v242, s[54:55] offset:256 sc1
	v_pk_mul_f32 v[70:71], v[70:71], v[206:207] op_sel_hi:[1,0]
	v_pk_mul_f32 v[72:73], v[72:73], v[206:207] op_sel_hi:[1,0]
	v_pk_fma_f32 v[70:71], v[70:71], v[222:223], v[226:227]
	v_pk_fma_f32 v[72:73], v[72:73], v[224:225], v[228:229]
	v_med3_f32 v230, v70, s43, v200
	v_med3_f32 v231, v71, s43, v200
	v_med3_f32 v232, v72, s43, v200
	v_med3_f32 v233, v73, s43, v200
	v_cvt_pk_fp8_f32 v234, v230, v231
	v_cvt_pk_bf16_f32 v236, v70, v71
	v_cvt_pk_bf16_f32 v237, v72, v73
	v_cvt_pk_fp8_f32 v234, v232, v233 op_sel:[0,0,1]
	global_store_dwordx2 v246, v[236:237], s[48:49] offset:512 sc1
	global_store_dword v247, v234, s[60:61] offset:256 sc1
	v_pk_mul_f32 v[102:103], v[102:103], v[208:209] op_sel_hi:[1,0]
	v_pk_mul_f32 v[104:105], v[104:105], v[208:209] op_sel_hi:[1,0]
	v_pk_fma_f32 v[102:103], v[102:103], v[222:223], v[226:227]
	v_pk_fma_f32 v[104:105], v[104:105], v[224:225], v[228:229]
	v_med3_f32 v238, v102, s43, v200
	v_med3_f32 v239, v103, s43, v200
	v_med3_f32 v240, v104, s43, v200
	v_med3_f32 v241, v105, s43, v200
	v_cvt_pk_fp8_f32 v242, v238, v239
	v_cvt_pk_bf16_f32 v244, v102, v103
	v_cvt_pk_bf16_f32 v245, v104, v105
	v_cvt_pk_fp8_f32 v242, v240, v241 op_sel:[0,0,1]
	global_store_dwordx2 v246, v[244:245], s[50:51] offset:512 sc1
	global_store_dword v247, v242, s[62:63] offset:256 sc1
	ds_read_b128 v[222:225], v193 offset:3072
	ds_read_b128 v[226:229], v193 offset:11264
	s_waitcnt lgkmcnt(2)
; #define GAS __attribute__((address_space(1)))
; __device__ __forceinline__ unsigned pk2(float lo, float hi) { return pg8::cvt_pk_bf16(lo, hi); }
; __device__ __forceinline__ unsigned pk4f8(float a, float b, float c, float d) { int p = __builtin_amdgcn_cvt_pk_fp8_f32(sat8(a), sat8(b), 0, false); p = __builtin_amdgcn_cvt_pk_fp8_f32(sat8(c), sat8(d), p, true); return (unsigned)p; }
; template <bool WT = true> __device__ __forceinline__ void h_store_tab(const HRow& X, const LAS f32x4* GS, const LAS f32x4* SH, bf16* hrow, unsigned char* h8row, int lane, float* rms_slot) {
;     ...
; #pragma unroll
;     for (int j = 0; j < 8; ++j) { const f32x4 h = X.v[j] * rr * GS[lane + 64 * j] + SH[lane + 64 * j]; const unsigned w0 = pk2(h[0], h[1]), w1 = pk2(h[2], h[3]);
;         const unsigned w8 = pk4f8(h[0], h[1], h[2], h[3]);
;         if (WT) { __hip_atomic_store((unsigned long long*)(hrow) + lane + 64 * j, ((unsigned long long)w1 << 32) | w0, RLX_AGENT); __hip_atomic_store((unsigned*)h8row + lane + 64 * j, w8, RLX_AGENT); }
;         else { ((GAS v2u*)hrow)[lane + 64 * j] = (v2u){w0, w1}; ((unsigned*)h8row)[lane + 64 * j] = w8; } }
	v_pk_mul_f32 v[10:11], v[10:11], v[202:203] op_sel_hi:[1,0]
	v_pk_mul_f32 v[12:13], v[12:13], v[202:203] op_sel_hi:[1,0]
	v_pk_fma_f32 v[10:11], v[10:11], v[214:215], v[218:219]
	v_pk_fma_f32 v[12:13], v[12:13], v[216:217], v[220:221]
	v_med3_f32 v230, v10, s43, v200
	v_med3_f32 v231, v11, s43, v200
	v_med3_f32 v232, v12, s43, v200
	v_med3_f32 v233, v13, s43, v200
	v_cvt_pk_fp8_f32 v234, v230, v231
	v_cvt_pk_bf16_f32 v236, v10, v11
	v_cvt_pk_bf16_f32 v237, v12, v13
	v_cvt_pk_fp8_f32 v234, v232, v233 op_sel:[0,0,1]
	global_store_dwordx2 v246, v[236:237], s[44:45] offset:1024 sc1
	global_store_dword v247, v234, s[52:53] offset:512 sc1
	v_pk_mul_f32 v[42:43], v[42:43], v[204:205] op_sel_hi:[1,0]
	v_pk_mul_f32 v[44:45], v[44:45], v[204:205] op_sel_hi:[1,0]
	v_pk_fma_f32 v[42:43], v[42:43], v[214:215], v[218:219]
	v_pk_fma_f32 v[44:45], v[44:45], v[216:217], v[220:221]
	v_med3_f32 v238, v42, s43, v200
	v_med3_f32 v239, v43, s43, v200
	v_med3_f32 v240, v44, s43, v200
	v_med3_f32 v241, v45, s43, v200
	v_cvt_pk_fp8_f32 v242, v238, v239
	v_cvt_pk_bf16_f32 v244, v42, v43
	v_cvt_pk_bf16_f32 v245, v44, v45
	v_cvt_pk_fp8_f32 v242, v240, v241 op_sel:[0,0,1]
	global_store_dwordx2 v246, v[244:245], s[46:47] offset:1024 sc1
	global_store_dword v247, v242, s[54:55] offset:512 sc1
	v_pk_mul_f32 v[74:75], v[74:75], v[206:207] op_sel_hi:[1,0]
	v_pk_mul_f32 v[76:77], v[76:77], v[206:207] op_sel_hi:[1,0]
	v_pk_fma_f32 v[74:75], v[74:75], v[214:215], v[218:219]
	v_pk_fma_f32 v[76:77], v[76:77], v[216:217], v[220:221]
	v_med3_f32 v230, v74, s43, v200
	v_med3_f32 v231, v75, s43, v200
	v_med3_f32 v232, v76, s43, v200
	v_med3_f32 v233, v77, s43, v200
	v_cvt_pk_fp8_f32 v234, v230, v231
	v_cvt_pk_bf16_f32 v236, v74, v75
	v_cvt_pk_bf16_f32 v237, v76, v77
	v_cvt_pk_fp8_f32 v234, v232, v233 op_sel:[0,0,1]
	global_store_dwordx2 v246, v[236:237], s[48:49] offset:1024 sc1
	global_store_dword v247, v234, s[60:61] offset:512 sc1
	v_pk_mul_f32 v[106:107], v[106:107], v[208:209] op_sel_hi:[1,0]
	v_pk_mul_f32 v[108:109], v[108:109], v[208:209] op_sel_hi:[1,0]
	v_pk_fma_f32 v[106:107], v[106:107], v[214:215], v[218:219]
	v_pk_fma_f32 v[108:109], v[108:109], v[216:217], v[220:221]
	v_med3_f32 v238, v106, s43, v200
	v_med3_f32 v239, v107, s43, v200
	v_med3_f32 v240, v108, s43, v200
	v_med3_f32 v241, v109, s43, v200
	v_cvt_pk_fp8_f32 v242, v238, v239
	v_cvt_pk_bf16_f32 v244, v106, v107
	v_cvt_pk_bf16_f32 v245, v108, v109
	v_cvt_pk_fp8_f32 v242, v240, v241 op_sel:[0,0,1]
	global_store_dwordx2 v246, v[244:245], s[50:51] offset:1024 sc1
	global_store_dword v247, v242, s[62:63] offset:512 sc1
	ds_read_b128 v[214:217], v193 offset:4096
	ds_read_b128 v[218:221], v193 offset:12288
	s_waitcnt lgkmcnt(2)
	v_pk_mul_f32 v[14:15], v[14:15], v[202:203] op_sel_hi:[1,0]
	v_pk_mul_f32 v[16:17], v[16:17], v[202:203] op_sel_hi:[1,0]
	v_pk_fma_f32 v[14:15], v[14:15], v[222:223], v[226:227]
	v_pk_fma_f32 v[16:17], v[16:17], v[224:225], v[228:229]
	v_med3_f32 v230, v14, s43, v200
	v_med3_f32 v231, v15, s43, v200
	v_med3_f32 v232, v16, s43, v200
	v_med3_f32 v233, v17, s43, v200
	v_cvt_pk_fp8_f32 v234, v230, v231
	v_cvt_pk_bf16_f32 v236, v14, v15
	v_cvt_pk_bf16_f32 v237, v16, v17
	v_cvt_pk_fp8_f32 v234, v232, v233 op_sel:[0,0,1]
	global_store_dwordx2 v246, v[236:237], s[44:45] offset:1536 sc1
	global_store_dword v247, v234, s[52:53] offset:768 sc1
	v_pk_mul_f32 v[46:47], v[46:47], v[204:205] op_sel_hi:[1,0]
	v_pk_mul_f32 v[48:49], v[48:49], v[204:205] op_sel_hi:[1,0]
	v_pk_fma_f32 v[46:47], v[46:47], v[222:223], v[226:227]
	v_pk_fma_f32 v[48:49], v[48:49], v[224:225], v[228:229]
	v_med3_f32 v238, v46, s43, v200
	v_med3_f32 v239, v47, s43, v200
	v_med3_f32 v240, v48, s43, v200
	v_med3_f32 v241, v49, s43, v200
	v_cvt_pk_fp8_f32 v242, v238, v239
	v_cvt_pk_bf16_f32 v244, v46, v47
	v_cvt_pk_bf16_f32 v245, v48, v49
	v_cvt_pk_fp8_f32 v242, v240, v241 op_sel:[0,0,1]
	global_store_dwordx2 v246, v[244:245], s[46:47] offset:1536 sc1
	global_store_dword v247, v242, s[54:55] offset:768 sc1
	v_pk_mul_f32 v[78:79], v[78:79], v[206:207] op_sel_hi:[1,0]
	v_pk_mul_f32 v[80:81], v[80:81], v[206:207] op_sel_hi:[1,0]
	v_pk_fma_f32 v[78:79], v[78:79], v[222:223], v[226:227]
	v_pk_fma_f32 v[80:81], v[80:81], v[224:225], v[228:229]
	v_med3_f32 v230, v78, s43, v200
	v_med3_f32 v231, v79, s43, v200
	v_med3_f32 v232, v80, s43, v200
	v_med3_f32 v233, v81, s43, v200
	v_cvt_pk_fp8_f32 v234, v230, v231
	v_cvt_pk_bf16_f32 v236, v78, v79
	v_cvt_pk_bf16_f32 v237, v80, v81
	v_cvt_pk_fp8_f32 v234, v232, v233 op_sel:[0,0,1]
	global_store_dwordx2 v246, v[236:237], s[48:49] offset:1536 sc1
	global_store_dword v247, v234, s[60:61] offset:768 sc1
	v_pk_mul_f32 v[110:111], v[110:111], v[208:209] op_sel_hi:[1,0]
	v_pk_mul_f32 v[112:113], v[112:113], v[208:209] op_sel_hi:[1,0]
	v_pk_fma_f32 v[110:111], v[110:111], v[222:223], v[226:227]
	v_pk_fma_f32 v[112:113], v[112:113], v[224:225], v[228:229]
	v_med3_f32 v238, v110, s43, v200
	v_med3_f32 v239, v111, s43, v200
	v_med3_f32 v240, v112, s43, v200
	v_med3_f32 v241, v113, s43, v200
	v_cvt_pk_fp8_f32 v242, v238, v239
	v_cvt_pk_bf16_f32 v244, v110, v111
	v_cvt_pk_bf16_f32 v245, v112, v113
	v_cvt_pk_fp8_f32 v242, v240, v241 op_sel:[0,0,1]
	global_store_dwordx2 v246, v[244:245], s[50:51] offset:1536 sc1
	global_store_dword v247, v242, s[62:63] offset:768 sc1
	ds_read_b128 v[222:225], v193 offset:5120
	ds_read_b128 v[226:229], v193 offset:13312
	s_waitcnt lgkmcnt(2)
; #define GAS __attribute__((address_space(1)))
; __device__ __forceinline__ unsigned pk2(float lo, float hi) { return pg8::cvt_pk_bf16(lo, hi); }
; __device__ __forceinline__ unsigned pk4f8(float a, float b, float c, float d) { int p = __builtin_amdgcn_cvt_pk_fp8_f32(sat8(a), sat8(b), 0, false); p = __builtin_amdgcn_cvt_pk_fp8_f32(sat8(c), sat8(d), p, true); return (unsigned)p; }
; template <bool WT = true> __device__ __forceinline__ void h_store_tab(const HRow& X, const LAS f32x4* GS, const LAS f32x4* SH, bf16* hrow, unsigned char* h8row, int lane, float* rms_slot) {
;     ...
; #pragma unroll
;     for (int j = 0; j < 8; ++j) { const f32x4 h = X.v[j] * rr * GS[lane + 64 * j] + SH[lane + 64 * j]; const unsigned w0 = pk2(h[0], h[1]), w1 = pk2(h[2], h[3]);
;         const unsigned w8 = pk4f8(h[0], h[1], h[2], h[3]);
;         if (WT) { __hip_atomic_store((unsigned long long*)(hrow) + lane + 64 * j, ((unsigned long long)w1 << 32) | w0, RLX_AGENT); __hip_atomic_store((unsigned*)h8row + lane + 64 * j, w8, RLX_AGENT); }
;         else { ((GAS v2u*)hrow)[lane + 64 * j] = (v2u){w0, w1}; ((unsigned*)h8row)[lane + 64 * j] = w8; } }
	v_pk_mul_f32 v[18:19], v[18:19], v[202:203] op_sel_hi:[1,0]
	v_pk_mul_f32 v[20:21], v[20:21], v[202:203] op_sel_hi:[1,0]
	v_pk_fma_f32 v[18:19], v[18:19], v[214:215], v[218:219]
	v_pk_fma_f32 v[20:21], v[20:21], v[216:217], v[220:221]
	v_med3_f32 v230, v18, s43, v200
	v_med3_f32 v231, v19, s43, v200
	v_med3_f32 v232, v20, s43, v200
	v_med3_f32 v233, v21, s43, v200
	v_cvt_pk_fp8_f32 v234, v230, v231
	v_cvt_pk_bf16_f32 v236, v18, v19
	v_cvt_pk_bf16_f32 v237, v20, v21
	v_cvt_pk_fp8_f32 v234, v232, v233 op_sel:[0,0,1]
	global_store_dwordx2 v246, v[236:237], s[44:45] offset:2048 sc1
	global_store_dword v247, v234, s[52:53] offset:1024 sc1
	v_pk_mul_f32 v[50:51], v[50:51], v[204:205] op_sel_hi:[1,0]
	v_pk_mul_f32 v[52:53], v[52:53], v[204:205] op_sel_hi:[1,0]
	v_pk_fma_f32 v[50:51], v[50:51], v[214:215], v[218:219]
	v_pk_fma_f32 v[52:53], v[52:53], v[216:217], v[220:221]
	v_med3_f32 v238, v50, s43, v200
	v_med3_f32 v239, v51, s43, v200
	v_med3_f32 v240, v52, s43, v200
	v_med3_f32 v241, v53, s43, v200
	v_cvt_pk_fp8_f32 v242, v238, v239
	v_cvt_pk_bf16_f32 v244, v50, v51
	v_cvt_pk_bf16_f32 v245, v52, v53
	v_cvt_pk_fp8_f32 v242, v240, v241 op_sel:[0,0,1]
	global_store_dwordx2 v246, v[244:245], s[46:47] offset:2048 sc1
	global_store_dword v247, v242, s[54:55] offset:1024 sc1
	v_pk_mul_f32 v[82:83], v[82:83], v[206:207] op_sel_hi:[1,0]
	v_pk_mul_f32 v[84:85], v[84:85], v[206:207] op_sel_hi:[1,0]
	v_pk_fma_f32 v[82:83], v[82:83], v[214:215], v[218:219]
	v_pk_fma_f32 v[84:85], v[84:85], v[216:217], v[220:221]
	v_med3_f32 v230, v82, s43, v200
	v_med3_f32 v231, v83, s43, v200
	v_med3_f32 v232, v84, s43, v200
	v_med3_f32 v233, v85, s43, v200
	v_cvt_pk_fp8_f32 v234, v230, v231
	v_cvt_pk_bf16_f32 v236, v82, v83
	v_cvt_pk_bf16_f32 v237, v84, v85
	v_cvt_pk_fp8_f32 v234, v232, v233 op_sel:[0,0,1]
	global_store_dwordx2 v246, v[236:237], s[48:49] offset:2048 sc1
	global_store_dword v247, v234, s[60:61] offset:1024 sc1
	v_pk_mul_f32 v[114:115], v[114:115], v[208:209] op_sel_hi:[1,0]
	v_pk_mul_f32 v[116:117], v[116:117], v[208:209] op_sel_hi:[1,0]
	v_pk_fma_f32 v[114:115], v[114:115], v[214:215], v[218:219]
	v_pk_fma_f32 v[116:117], v[116:117], v[216:217], v[220:221]
	v_med3_f32 v238, v114, s43, v200
	v_med3_f32 v239, v115, s43, v200
	v_med3_f32 v240, v116, s43, v200
	v_med3_f32 v241, v117, s43, v200
	v_cvt_pk_fp8_f32 v242, v238, v239
	v_cvt_pk_bf16_f32 v244, v114, v115
	v_cvt_pk_bf16_f32 v245, v116, v117
	v_cvt_pk_fp8_f32 v242, v240, v241 op_sel:[0,0,1]
	global_store_dwordx2 v246, v[244:245], s[50:51] offset:2048 sc1
	global_store_dword v247, v242, s[62:63] offset:1024 sc1
	ds_read_b128 v[214:217], v193 offset:6144
	ds_read_b128 v[218:221], v193 offset:14336
	s_waitcnt lgkmcnt(2)
	v_pk_mul_f32 v[22:23], v[22:23], v[202:203] op_sel_hi:[1,0]
	v_pk_mul_f32 v[24:25], v[24:25], v[202:203] op_sel_hi:[1,0]
	v_pk_fma_f32 v[22:23], v[22:23], v[222:223], v[226:227]
	v_pk_fma_f32 v[24:25], v[24:25], v[224:225], v[228:229]
	v_med3_f32 v230, v22, s43, v200
	v_med3_f32 v231, v23, s43, v200
	v_med3_f32 v232, v24, s43, v200
	v_med3_f32 v233, v25, s43, v200
	v_cvt_pk_fp8_f32 v234, v230, v231
	v_cvt_pk_bf16_f32 v236, v22, v23
	v_cvt_pk_bf16_f32 v237, v24, v25
	v_cvt_pk_fp8_f32 v234, v232, v233 op_sel:[0,0,1]
	global_store_dwordx2 v246, v[236:237], s[44:45] offset:2560 sc1
	global_store_dword v247, v234, s[52:53] offset:1280 sc1
	v_pk_mul_f32 v[54:55], v[54:55], v[204:205] op_sel_hi:[1,0]
	v_pk_mul_f32 v[56:57], v[56:57], v[204:205] op_sel_hi:[1,0]
	v_pk_fma_f32 v[54:55], v[54:55], v[222:223], v[226:227]
	v_pk_fma_f32 v[56:57], v[56:57], v[224:225], v[228:229]
	v_med3_f32 v238, v54, s43, v200
	v_med3_f32 v239, v55, s43, v200
	v_med3_f32 v240, v56, s43, v200
	v_med3_f32 v241, v57, s43, v200
	v_cvt_pk_fp8_f32 v242, v238, v239
	v_cvt_pk_bf16_f32 v244, v54, v55
	v_cvt_pk_bf16_f32 v245, v56, v57
	v_cvt_pk_fp8_f32 v242, v240, v241 op_sel:[0,0,1]
	global_store_dwordx2 v246, v[244:245], s[46:47] offset:2560 sc1
	global_store_dword v247, v242, s[54:55] offset:1280 sc1
	v_pk_mul_f32 v[86:87], v[86:87], v[206:207] op_sel_hi:[1,0]
	v_pk_mul_f32 v[88:89], v[88:89], v[206:207] op_sel_hi:[1,0]
	v_pk_fma_f32 v[86:87], v[86:87], v[222:223], v[226:227]
	v_pk_fma_f32 v[88:89], v[88:89], v[224:225], v[228:229]
	v_med3_f32 v230, v86, s43, v200
	v_med3_f32 v231, v87, s43, v200
	v_med3_f32 v232, v88, s43, v200
	v_med3_f32 v233, v89, s43, v200
	v_cvt_pk_fp8_f32 v234, v230, v231
	v_cvt_pk_bf16_f32 v236, v86, v87
	v_cvt_pk_bf16_f32 v237, v88, v89
	v_cvt_pk_fp8_f32 v234, v232, v233 op_sel:[0,0,1]
	global_store_dwordx2 v246, v[236:237], s[48:49] offset:2560 sc1
	global_store_dword v247, v234, s[60:61] offset:1280 sc1
	v_pk_mul_f32 v[118:119], v[118:119], v[208:209] op_sel_hi:[1,0]
	v_pk_mul_f32 v[120:121], v[120:121], v[208:209] op_sel_hi:[1,0]
	v_pk_fma_f32 v[118:119], v[118:119], v[222:223], v[226:227]
	v_pk_fma_f32 v[120:121], v[120:121], v[224:225], v[228:229]
	v_med3_f32 v238, v118, s43, v200
	v_med3_f32 v239, v119, s43, v200
	v_med3_f32 v240, v120, s43, v200
	v_med3_f32 v241, v121, s43, v200
	v_cvt_pk_fp8_f32 v242, v238, v239
	v_cvt_pk_bf16_f32 v244, v118, v119
	v_cvt_pk_bf16_f32 v245, v120, v121
	v_cvt_pk_fp8_f32 v242, v240, v241 op_sel:[0,0,1]
	global_store_dwordx2 v246, v[244:245], s[50:51] offset:2560 sc1
	global_store_dword v247, v242, s[62:63] offset:1280 sc1
	ds_read_b128 v[222:225], v193 offset:7168
	ds_read_b128 v[226:229], v193 offset:15360
	s_waitcnt lgkmcnt(2)
; #define GAS __attribute__((address_space(1)))
; __device__ __forceinline__ unsigned pk2(float lo, float hi) { return pg8::cvt_pk_bf16(lo, hi); }
; __device__ __forceinline__ unsigned pk4f8(float a, float b, float c, float d) { int p = __builtin_amdgcn_cvt_pk_fp8_f32(sat8(a), sat8(b), 0, false); p = __builtin_amdgcn_cvt_pk_fp8_f32(sat8(c), sat8(d), p, true); return (unsigned)p; }
; template <bool WT = true> __device__ __forceinline__ void h_store_tab(const HRow& X, const LAS f32x4* GS, const LAS f32x4* SH, bf16* hrow, unsigned char* h8row, int lane, float* rms_slot) {
;     ...
; #pragma unroll
;     for (int j = 0; j < 8; ++j) { const f32x4 h = X.v[j] * rr * GS[lane + 64 * j] + SH[lane + 64 * j]; const unsigned w0 = pk2(h[0], h[1]), w1 = pk2(h[2], h[3]);
;         const unsigned w8 = pk4f8(h[0], h[1], h[2], h[3]);
;         if (WT) { __hip_atomic_store((unsigned long long*)(hrow) + lane + 64 * j, ((unsigned long long)w1 << 32) | w0, RLX_AGENT); __hip_atomic_store((unsigned*)h8row + lane + 64 * j, w8, RLX_AGENT); }
;         else { ((GAS v2u*)hrow)[lane + 64 * j] = (v2u){w0, w1}; ((unsigned*)h8row)[lane + 64 * j] = w8; } }
	v_pk_mul_f32 v[26:27], v[26:27], v[202:203] op_sel_hi:[1,0]
	v_pk_mul_f32 v[28:29], v[28:29], v[202:203] op_sel_hi:[1,0]
	v_pk_fma_f32 v[26:27], v[26:27], v[214:215], v[218:219]
	v_pk_fma_f32 v[28:29], v[28:29], v[216:217], v[220:221]
	v_med3_f32 v230, v26, s43, v200
	v_med3_f32 v231, v27, s43, v200
	v_med3_f32 v232, v28, s43, v200
	v_med3_f32 v233, v29, s43, v200
	v_cvt_pk_fp8_f32 v234, v230, v231
	v_cvt_pk_bf16_f32 v236, v26, v27
	v_cvt_pk_bf16_f32 v237, v28, v29
	v_cvt_pk_fp8_f32 v234, v232, v233 op_sel:[0,0,1]
	global_store_dwordx2 v246, v[236:237], s[44:45] offset:3072 sc1
	global_store_dword v247, v234, s[52:53] offset:1536 sc1
	v_pk_mul_f32 v[58:59], v[58:59], v[204:205] op_sel_hi:[1,0]
	v_pk_mul_f32 v[60:61], v[60:61], v[204:205] op_sel_hi:[1,0]
	v_pk_fma_f32 v[58:59], v[58:59], v[214:215], v[218:219]
	v_pk_fma_f32 v[60:61], v[60:61], v[216:217], v[220:221]
	v_med3_f32 v238, v58, s43, v200
	v_med3_f32 v239, v59, s43, v200
	v_med3_f32 v240, v60, s43, v200
	v_med3_f32 v241, v61, s43, v200
	v_cvt_pk_fp8_f32 v242, v238, v239
	v_cvt_pk_bf16_f32 v244, v58, v59
	v_cvt_pk_bf16_f32 v245, v60, v61
	v_cvt_pk_fp8_f32 v242, v240, v241 op_sel:[0,0,1]
	global_store_dwordx2 v246, v[244:245], s[46:47] offset:3072 sc1
	global_store_dword v247, v242, s[54:55] offset:1536 sc1
	v_pk_mul_f32 v[90:91], v[90:91], v[206:207] op_sel_hi:[1,0]
	v_pk_mul_f32 v[92:93], v[92:93], v[206:207] op_sel_hi:[1,0]
	v_pk_fma_f32 v[90:91], v[90:91], v[214:215], v[218:219]
	v_pk_fma_f32 v[92:93], v[92:93], v[216:217], v[220:221]
	v_med3_f32 v230, v90, s43, v200
	v_med3_f32 v231, v91, s43, v200
	v_med3_f32 v232, v92, s43, v200
	v_med3_f32 v233, v93, s43, v200
	v_cvt_pk_fp8_f32 v234, v230, v231
	v_cvt_pk_bf16_f32 v236, v90, v91
	v_cvt_pk_bf16_f32 v237, v92, v93
	v_cvt_pk_fp8_f32 v234, v232, v233 op_sel:[0,0,1]
	global_store_dwordx2 v246, v[236:237], s[48:49] offset:3072 sc1
	global_store_dword v247, v234, s[60:61] offset:1536 sc1
	v_pk_mul_f32 v[122:123], v[122:123], v[208:209] op_sel_hi:[1,0]
	v_pk_mul_f32 v[124:125], v[124:125], v[208:209] op_sel_hi:[1,0]
	v_pk_fma_f32 v[122:123], v[122:123], v[214:215], v[218:219]
	v_pk_fma_f32 v[124:125], v[124:125], v[216:217], v[220:221]
	v_med3_f32 v238, v122, s43, v200
	v_med3_f32 v239, v123, s43, v200
	v_med3_f32 v240, v124, s43, v200
	v_med3_f32 v241, v125, s43, v200
	v_cvt_pk_fp8_f32 v242, v238, v239
	v_cvt_pk_bf16_f32 v244, v122, v123
	v_cvt_pk_bf16_f32 v245, v124, v125
	v_cvt_pk_fp8_f32 v242, v240, v241 op_sel:[0,0,1]
	global_store_dwordx2 v246, v[244:245], s[50:51] offset:3072 sc1
	global_store_dword v247, v242, s[62:63] offset:1536 sc1
	s_waitcnt lgkmcnt(0)
	v_pk_mul_f32 v[30:31], v[30:31], v[202:203] op_sel_hi:[1,0]
	v_pk_mul_f32 v[32:33], v[32:33], v[202:203] op_sel_hi:[1,0]
	v_pk_fma_f32 v[30:31], v[30:31], v[222:223], v[226:227]
	v_pk_fma_f32 v[32:33], v[32:33], v[224:225], v[228:229]
	v_med3_f32 v230, v30, s43, v200
	v_med3_f32 v231, v31, s43, v200
	v_med3_f32 v232, v32, s43, v200
	v_med3_f32 v233, v33, s43, v200
	v_cvt_pk_fp8_f32 v234, v230, v231
	v_cvt_pk_bf16_f32 v236, v30, v31
	v_cvt_pk_bf16_f32 v237, v32, v33
	v_cvt_pk_fp8_f32 v234, v232, v233 op_sel:[0,0,1]
	global_store_dwordx2 v246, v[236:237], s[44:45] offset:3584 sc1
	global_store_dword v247, v234, s[52:53] offset:1792 sc1
	v_pk_mul_f32 v[62:63], v[62:63], v[204:205] op_sel_hi:[1,0]
	v_pk_mul_f32 v[64:65], v[64:65], v[204:205] op_sel_hi:[1,0]
	v_pk_fma_f32 v[62:63], v[62:63], v[222:223], v[226:227]
	v_pk_fma_f32 v[64:65], v[64:65], v[224:225], v[228:229]
	v_med3_f32 v238, v62, s43, v200
	v_med3_f32 v239, v63, s43, v200
	v_med3_f32 v240, v64, s43, v200
	v_med3_f32 v241, v65, s43, v200
	v_cvt_pk_fp8_f32 v242, v238, v239
	v_cvt_pk_bf16_f32 v244, v62, v63
	v_cvt_pk_bf16_f32 v245, v64, v65
	v_cvt_pk_fp8_f32 v242, v240, v241 op_sel:[0,0,1]
	global_store_dwordx2 v246, v[244:245], s[46:47] offset:3584 sc1
	global_store_dword v247, v242, s[54:55] offset:1792 sc1
	v_pk_mul_f32 v[94:95], v[94:95], v[206:207] op_sel_hi:[1,0]
	v_pk_mul_f32 v[96:97], v[96:97], v[206:207] op_sel_hi:[1,0]
	v_pk_fma_f32 v[94:95], v[94:95], v[222:223], v[226:227]
	v_pk_fma_f32 v[96:97], v[96:97], v[224:225], v[228:229]
	v_med3_f32 v230, v94, s43, v200
	v_med3_f32 v231, v95, s43, v200
	v_med3_f32 v232, v96, s43, v200
	v_med3_f32 v233, v97, s43, v200
	v_cvt_pk_fp8_f32 v234, v230, v231
	v_cvt_pk_bf16_f32 v236, v94, v95
	v_cvt_pk_bf16_f32 v237, v96, v97
	v_cvt_pk_fp8_f32 v234, v232, v233 op_sel:[0,0,1]
	global_store_dwordx2 v246, v[236:237], s[48:49] offset:3584 sc1
	global_store_dword v247, v234, s[60:61] offset:1792 sc1
	v_pk_mul_f32 v[126:127], v[126:127], v[208:209] op_sel_hi:[1,0]
	v_pk_mul_f32 v[128:129], v[128:129], v[208:209] op_sel_hi:[1,0]
	v_pk_fma_f32 v[126:127], v[126:127], v[222:223], v[226:227]
	v_pk_fma_f32 v[128:129], v[128:129], v[224:225], v[228:229]
	v_med3_f32 v238, v126, s43, v200
	v_med3_f32 v239, v127, s43, v200
	v_med3_f32 v240, v128, s43, v200
	v_med3_f32 v241, v129, s43, v200
	v_cvt_pk_fp8_f32 v242, v238, v239
	v_cvt_pk_bf16_f32 v244, v126, v127
	v_cvt_pk_bf16_f32 v245, v128, v129
	v_cvt_pk_fp8_f32 v242, v240, v241 op_sel:[0,0,1]
	global_store_dwordx2 v246, v[244:245], s[50:51] offset:3584 sc1
	global_store_dword v247, v242, s[62:63] offset:1792 sc1
	s_cmpk_eq_i32 s26, 0xc00
	s_cbranch_scc1 .Laux_last_prompt
; __device__ __forceinline__ const float* h_xrow(const Args& a, int r) { return (r < NBATCH * SEQ) ? a.in[I_XP] + (size_t)r * DM : a.in[I_XS] + (size_t)(r - NBATCH * SEQ) * DM; }
; __device__ __forceinline__ void p3_aux(const Args& a, const Ctx& C, int x) {
;     ...
;                 h_load_nt(x0, h_xrow(a, 256 * p0 + aw), lane); h_load_nt(x1, h_xrow(a, 256 * (p0 + 1) + aw), lane);
;                 h_load_nt(x2, h_xrow(a, 256 * (p0 + 2) + aw), lane); h_load_nt(x3, h_xrow(a, 256 * (p0 + 3) + aw), lane);
;                 h_pin(x0); h_pin(x1); h_pin(x2); h_pin(x3);
;     ...
;         asm volatile("s_waitcnt vmcnt(0)" ::: "memory"); __syncthreads();
	s_addk_i32 s2, 0x400
	s_lshl_b32 s31, s2, 13
	s_add_u32 s34, s56, s31
	s_addc_u32 s35, s57, 0
	s_add_u32 s36, s34, 0x1000
	s_addc_u32 s37, s35, 0
	global_load_dwordx4 v[2:5], v130, s[34:35] nt
	global_load_dwordx4 v[6:9], v130, s[34:35] offset:1024 nt
	global_load_dwordx4 v[10:13], v130, s[34:35] offset:2048 nt
	global_load_dwordx4 v[14:17], v130, s[34:35] offset:3072 nt
	global_load_dwordx4 v[18:21], v130, s[36:37] nt
	global_load_dwordx4 v[22:25], v130, s[36:37] offset:1024 nt
	global_load_dwordx4 v[26:29], v130, s[36:37] offset:2048 nt
	global_load_dwordx4 v[30:33], v130, s[36:37] offset:3072 nt
	s_add_i32 s30, s2, 256
	s_lshl_b32 s31, s30, 13
	s_add_u32 s34, s56, s31
	s_addc_u32 s35, s57, 0
	s_add_u32 s36, s34, 0x1000
	s_addc_u32 s37, s35, 0
	global_load_dwordx4 v[34:37], v130, s[34:35] nt
	global_load_dwordx4 v[38:41], v130, s[34:35] offset:1024 nt
	global_load_dwordx4 v[42:45], v130, s[34:35] offset:2048 nt
	global_load_dwordx4 v[46:49], v130, s[34:35] offset:3072 nt
	global_load_dwordx4 v[50:53], v130, s[36:37] nt
	global_load_dwordx4 v[54:57], v130, s[36:37] offset:1024 nt
	global_load_dwordx4 v[58:61], v130, s[36:37] offset:2048 nt
	global_load_dwordx4 v[62:65], v130, s[36:37] offset:3072 nt
	s_add_i32 s30, s2, 512
	s_lshl_b32 s31, s30, 13
	s_add_u32 s34, s56, s31
	s_addc_u32 s35, s57, 0
	s_add_u32 s36, s34, 0x1000
	s_addc_u32 s37, s35, 0
	global_load_dwordx4 v[66:69], v130, s[34:35] nt
	global_load_dwordx4 v[70:73], v130, s[34:35] offset:1024 nt
	global_load_dwordx4 v[74:77], v130, s[34:35] offset:2048 nt
	global_load_dwordx4 v[78:81], v130, s[34:35] offset:3072 nt
	global_load_dwordx4 v[82:85], v130, s[36:37] nt
	global_load_dwordx4 v[86:89], v130, s[36:37] offset:1024 nt
	global_load_dwordx4 v[90:93], v130, s[36:37] offset:2048 nt
	global_load_dwordx4 v[94:97], v130, s[36:37] offset:3072 nt
	s_add_i32 s30, s2, 768
	s_lshl_b32 s31, s30, 13
	s_add_u32 s34, s56, s31
	s_addc_u32 s35, s57, 0
	s_add_u32 s36, s34, 0x1000
	s_addc_u32 s37, s35, 0
	global_load_dwordx4 v[98:101], v130, s[34:35] nt
	global_load_dwordx4 v[102:105], v130, s[34:35] offset:1024 nt
	global_load_dwordx4 v[106:109], v130, s[34:35] offset:2048 nt
	global_load_dwordx4 v[110:113], v130, s[34:35] offset:3072 nt
	global_load_dwordx4 v[114:117], v130, s[36:37] nt
	global_load_dwordx4 v[118:121], v130, s[36:37] offset:1024 nt
	global_load_dwordx4 v[122:125], v130, s[36:37] offset:2048 nt
	global_load_dwordx4 v[126:129], v130, s[36:37] offset:3072 nt
	s_waitcnt vmcnt(32)
	s_branch .Laux_after_drain
.Laux_last_prompt:
	s_waitcnt vmcnt(0)
	s_branch .Laux_after_drain

; __device__ __forceinline__ void p3_aux(const Args& a, const Ctx& C, int x) {
;     ...
;         asm volatile("s_waitcnt vmcnt(0)" ::: "memory"); __syncthreads();
;         if (C.tid == 0) {
;             for (int j = 0; j < 4; ++j) if (p0 + j < 33) __hip_atomic_fetch_add(ready + 64 * (p0 + j), 1u, RLX_AGENT); }
.Laux_after_drain:
	s_barrier
	s_mov_b64 s[30:31], exec
	v_readlane_b32 s34, v249, 17
	v_readlane_b32 s35, v249, 18
	s_and_b64 s[34:35], s[30:31], s[34:35]
	s_mov_b64 exec, s[34:35]
	s_cbranch_execz .LBB0_312
	s_mov_b64 s[36:37], exec
	s_getpc_b64 s[34:35]
	s_add_u32 s34, s34, g_ctl@rel32@lo+4
	s_addc_u32 s35, s35, g_ctl@rel32@hi+12
	v_mbcnt_lo_u32_b32 v201, s36, 0
	s_add_u32 s34, s34, s26
	v_mbcnt_hi_u32_b32 v201, s37, v201
	s_addc_u32 s35, s35, s27
	v_cmp_eq_u32_e32 vcc, 0, v201
	s_and_saveexec_b64 s[38:39], vcc
	s_cbranch_execz .LBB0_341
	s_bcnt1_i32_b64 s2, s[36:37]
	v_mov_b32_e32 v201, s2
	global_atomic_add v198, v201, s[34:35]
	s_or_b64 exec, exec, s[38:39]
	s_add_i32 s2, s42, -2
	s_cmp_gt_u32 s2, 32
	s_cbranch_scc0 .LBB0_342

; __device__ __forceinline__ void p3_aux(const Args& a, const Ctx& C, int x) {
;     ...
;         if (C.tid == 0) {
;             for (int j = 0; j < 4; ++j) if (p0 + j < 33) __hip_atomic_fetch_add(ready + 64 * (p0 + j), 1u, RLX_AGENT); }
.LBB0_338:
	s_mov_b64 s[38:39], exec
	v_mbcnt_lo_u32_b32 v201, s38, 0
	v_mbcnt_hi_u32_b32 v201, s39, v201
	v_cmp_eq_u32_e32 vcc, 0, v201
	s_and_saveexec_b64 s[36:37], vcc
	s_cbranch_execz .LBB0_340
	s_bcnt1_i32_b64 s2, s[38:39]
	v_mov_b32_e32 v201, s2
	global_atomic_add v198, v201, s[34:35] offset:512

; __device__ __forceinline__ void p3_aux(const Args& a, const Ctx& C, int x) {
;     ...
;         if (C.tid == 0) {
;             for (int j = 0; j < 4; ++j) if (p0 + j < 33) __hip_atomic_fetch_add(ready + 64 * (p0 + j), 1u, RLX_AGENT); }
.LBB0_342:
	s_mov_b64 s[38:39], exec
	v_mbcnt_lo_u32_b32 v201, s38, 0
	v_mbcnt_hi_u32_b32 v201, s39, v201
	v_cmp_eq_u32_e32 vcc, 0, v201
	s_and_saveexec_b64 s[36:37], vcc
	s_cbranch_execz .LBB0_344
	s_bcnt1_i32_b64 s2, s[38:39]
	v_mov_b32_e32 v201, s2
	global_atomic_add v198, v201, s[34:35] offset:256

; __device__ __forceinline__ void p3_aux(const Args& a, const Ctx& C, int x) {
;     ...
;         if (C.tid == 0) {
;             for (int j = 0; j < 4; ++j) if (p0 + j < 33) __hip_atomic_fetch_add(ready + 64 * (p0 + j), 1u, RLX_AGENT); }
.LBB0_346:
	s_mov_b64 s[36:37], exec
	v_mbcnt_lo_u32_b32 v201, s36, 0
	v_mbcnt_hi_u32_b32 v201, s37, v201
	v_cmp_eq_u32_e32 vcc, 0, v201
	s_and_b64 s[38:39], exec, vcc
	s_mov_b64 exec, s[38:39]
	s_cbranch_execz .LBB0_312
	s_bcnt1_i32_b64 s2, s[36:37]
	v_mov_b32_e32 v201, s2
	global_atomic_add v198, v201, s[34:35] offset:768
	s_branch .LBB0_312

; __device__ __forceinline__ unsigned cvt_pk_bf16(float lo, float hi) { const f32x2_t v = {lo, hi}; return __builtin_bit_cast(unsigned, __builtin_convertvector(v, bf16x2_t)); }
; __device__ __forceinline__ float silu_f(float x) { return x * __builtin_amdgcn_rcpf(1.0f + __expf(-x)); }
;     __device__ __forceinline__ void operator()(const f32x4 (&acc)[2][2][4][2], const Unit& u, int wr, int wc, int fr, int fq) const {
;         const int row0 = u.pm * BM + wr * 64 + fr, lc = wc * 32 + 8 * fq;
;         const int pnl = (f8tiles && u.pn >= 12) ? u.pn + 4 : u.pn;
;         const int type = (pnl < 8) ? 0 : (pnl < 12) ? 1 : (pnl < 16) ? 3 : 4;
; #pragma unroll
;         for (int ai = 0; ai < 2; ++ai)
; #pragma unroll
;             for (int m = 0; m < 4; ++m) { const int row = row0 + ai * HALF + m * 16;
;                 if (type == 0) { f32x4 p0, p1;
; #pragma unroll
;                     for (int j = 0; j < 4; ++j) { p0[j] = (acc[ai][0][m][0][j] * osc) * silu_f(acc[ai][1][m][0][j] * osc); p1[j] = (acc[ai][0][m][1][j] * osc) * silu_f(acc[ai][1][m][1][j] * osc); }
;                     u32x4 w; w.x = cvt_pk_bf16(p0[0], p0[1]); w.y = cvt_pk_bf16(p0[2], p0[3]); w.z = cvt_pk_bf16(p1[0], p1[1]); w.w = cvt_pk_bf16(p1[2], p1[3]);
;                     *(u32x4*)(P + (size_t)row * 5120 + pnl * HALF + lc) = w; }
.LBB0_400:
	s_cmp_lt_i32 s44, 8
	s_cselect_b64 s[8:9], -1, 0
	s_cmp_lt_u32 s44, 16
	v_lshl_add_u32 v136, s2, 8, v131
	s_cselect_b32 s2, 3, 4
	s_cmp_lt_u32 s44, 12
	s_cselect_b64 s[76:77], -1, 0
	s_and_b64 s[4:5], s[76:77], exec
	s_cselect_b32 s2, 1, s2
	s_cmp_gt_i32 s44, 7
	s_cselect_b64 s[4:5], -1, 0
	s_and_b64 vcc, s[4:5], exec
	s_cselect_b32 s2, s2, 0
	s_lshl_b32 s86, s44, 7
	s_ashr_i32 s87, s86, 31
	s_cmp_eq_u32 s2, 4
	s_cselect_b64 s[4:5], -1, 0
	s_and_b32 s6, s44, 0x7ffffffc
	s_cmp_lg_u32 s6, 8
	s_cselect_b64 s[84:85], -1, 0
	s_cmp_eq_u32 s2, 3
	s_cselect_b64 s[78:79], -1, 0
	s_and_b64 s[6:7], s[78:79], exec
	s_cselect_b32 s2, -12, -16
	s_mov_b64 s[6:7], -1
	v_lshlrev_b32_e32 v172, 1, v130
	s_cbranch_vccnz .LBB0_402
	v_pk_mul_f32 v[138:139], v[134:135], v[118:119]
	v_pk_mul_f32 v[144:145], v[134:135], v[126:127]
	v_mul_f32_e32 v137, 0xbfb8aa3b, v138
	v_exp_f32_e32 v137, v137
	v_pk_mul_f32 v[146:147], v[134:135], v[122:123]
	v_pk_mul_f32 v[148:149], v[134:135], v[128:129]
	v_pk_mul_f32 v[150:151], v[134:135], v[124:125]
	v_add_f32_e32 v137, 1.0, v137
	v_rcp_f32_e32 v140, v137
	v_mul_f32_e32 v137, 0xbfb8aa3b, v139
	v_exp_f32_e32 v137, v137
	s_nop 0
	v_add_f32_e32 v137, 1.0, v137
	v_rcp_f32_e32 v141, v137
	s_nop 0
	v_pk_mul_f32 v[138:139], v[138:139], v[140:141]
	v_pk_mul_f32 v[140:141], v[134:135], v[114:115]
	v_pk_mul_f32 v[138:139], v[138:139], v[144:145]
	v_mul_f32_e32 v137, 0xbfb8aa3b, v140
	v_exp_f32_e32 v137, v137
	v_cvt_pk_bf16_f32 v138, v138, v139
	v_add_f32_e32 v137, 1.0, v137
	v_rcp_f32_e32 v144, v137
	v_mul_f32_e32 v137, 0xbfb8aa3b, v141
	v_exp_f32_e32 v137, v137
	s_nop 0
	v_add_f32_e32 v137, 1.0, v137
	v_rcp_f32_e32 v145, v137
	s_nop 0
	v_pk_mul_f32 v[140:141], v[140:141], v[144:145]
	v_pk_mul_f32 v[144:145], v[134:135], v[120:121]
	v_pk_mul_f32 v[140:141], v[140:141], v[146:147]
	v_mul_f32_e32 v137, 0xbfb8aa3b, v144
	v_exp_f32_e32 v137, v137
	v_cvt_pk_bf16_f32 v140, v140, v141
	v_add_f32_e32 v137, 1.0, v137
	v_rcp_f32_e32 v146, v137
	v_mul_f32_e32 v137, 0xbfb8aa3b, v145
	v_exp_f32_e32 v137, v137
	s_nop 0
	v_add_f32_e32 v137, 1.0, v137
	v_rcp_f32_e32 v147, v137
	s_nop 0
	v_pk_mul_f32 v[144:145], v[144:145], v[146:147]
	v_pk_mul_f32 v[146:147], v[134:135], v[116:117]
	v_pk_mul_f32 v[144:145], v[144:145], v[148:149]
	v_mul_f32_e32 v137, 0xbfb8aa3b, v146
	v_exp_f32_e32 v137, v137
	v_cvt_pk_bf16_f32 v139, v144, v145
	v_mov_b64_e32 v[144:145], s[14:15]
	v_mad_i64_i32 v[144:145], s[6:7], v136, s40, v[144:145]
	v_add_f32_e32 v137, 1.0, v137
	v_rcp_f32_e32 v148, v137
	v_mul_f32_e32 v137, 0xbfb8aa3b, v147
	v_exp_f32_e32 v137, v137
	v_lshl_add_u64 v[144:145], s[86:87], 1, v[144:145]
	v_lshl_add_u64 v[144:145], v[144:145], 0, v[172:173]
	s_mov_b64 s[6:7], 0
	v_add_f32_e32 v137, 1.0, v137
	v_rcp_f32_e32 v149, v137
	s_nop 0
	v_pk_mul_f32 v[146:147], v[146:147], v[148:149]
	s_nop 0
	v_pk_mul_f32 v[146:147], v[146:147], v[150:151]
	s_nop 0
	v_cvt_pk_bf16_f32 v141, v146, v147
	global_store_dwordx4 v[144:145], v[138:141], off sc1

; __device__ __forceinline__ unsigned cvt_pk_bf16(float lo, float hi) { const f32x2_t v = {lo, hi}; return __builtin_bit_cast(unsigned, __builtin_convertvector(v, bf16x2_t)); }
;     __device__ __forceinline__ void operator()(const f32x4 (&acc)[2][2][4][2], const Unit& u, int wr, int wc, int fr, int fq) const {
;     ...
;                         u32x4 w; w.x = cvt_pk_bf16(v0[0], v0[1]); w.y = cvt_pk_bf16(v0[2], v0[3]); w.z = cvt_pk_bf16(v1[0], v1[1]); w.w = cvt_pk_bf16(v1[2], v1[3]);
;                         if (type == 1) *(u32x4*)(P + (size_t)row * 5120 + 1024 + (pnl - 8) * BM + bj * HALF + lc) = w;
;                         else { const int cg = (pnl - (type == 3 ? 12 : 16)) * BM + bj * HALF + lc;
;                             *(u32x4*)((type == 3 ? XB : ZB) + ((size_t)(cg >> 4) * 8448 + row) * 16 + (cg & 8)) = w; } }
.LBB0_410:
	v_ashrrev_i32_e32 v137, 31, v136
	v_cvt_pk_bf16_f32 v122, v138, v139
	v_cvt_pk_bf16_f32 v123, v128, v129
	v_cvt_pk_bf16_f32 v124, v124, v125
	v_cvt_pk_bf16_f32 v125, v140, v141
	s_mov_b64 s[88:89], -1
	s_and_b64 vcc, exec, s[84:85]
	s_cbranch_vccz .LBB0_412
	v_ashrrev_i32_e32 v128, 4, v144
	s_and_b64 s[44:45], s[78:79], exec
	v_mad_i64_i32 v[128:129], s[88:89], v128, s41, v[136:137]
	s_cselect_b32 s45, s29, s53
	s_cselect_b32 s44, s28, s52
	v_lshlrev_b64 v[128:129], 5, v[128:129]
	v_lshl_add_u64 v[128:129], s[44:45], 0, v[128:129]
	v_lshlrev_b32_e32 v138, 1, v174
	v_mov_b32_e32 v139, v173
	v_lshl_add_u64 v[128:129], v[128:129], 0, v[138:139]
	global_store_dwordx4 v[128:129], v[122:125], off sc1
	s_mov_b64 s[88:89], 0
.LBB0_412:
	v_mad_i64_i32 v[128:129], s[44:45], v136, s40, 0
	s_andn2_b64 vcc, exec, s[88:89]
	v_lshl_add_u64 v[128:129], s[14:15], 0, v[128:129]
	s_cbranch_vccnz .LBB0_414
	s_lshl_b32 s34, s67, 1
	v_lshl_add_u64 v[138:139], v[128:129], 0, s[34:35]
	v_lshl_add_u64 v[138:139], v[138:139], 0, v[172:173]
	global_store_dwordx4 v[138:139], v[122:125], off offset:-2048 sc1

; __device__ __forceinline__ unsigned cvt_pk_bf16(float lo, float hi) { const f32x2_t v = {lo, hi}; return __builtin_bit_cast(unsigned, __builtin_convertvector(v, bf16x2_t)); }
;     __device__ __forceinline__ void operator()(const f32x4 (&acc)[2][2][4][2], const Unit& u, int wr, int wc, int fr, int fq) const {
;     ...
;                         u32x4 w; w.x = cvt_pk_bf16(v0[0], v0[1]); w.y = cvt_pk_bf16(v0[2], v0[3]); w.z = cvt_pk_bf16(v1[0], v1[1]); w.w = cvt_pk_bf16(v1[2], v1[3]);
;                         if (type == 1) *(u32x4*)(P + (size_t)row * 5120 + 1024 + (pnl - 8) * BM + bj * HALF + lc) = w;
;                         else { const int cg = (pnl - (type == 3 ? 12 : 16)) * BM + bj * HALF + lc;
;                             *(u32x4*)((type == 3 ? XB : ZB) + ((size_t)(cg >> 4) * 8448 + row) * 16 + (cg & 8)) = w; } }
.LBB0_418:
	v_cvt_pk_bf16_f32 v114, v118, v119
	v_cvt_pk_bf16_f32 v115, v120, v121
	v_cvt_pk_bf16_f32 v116, v116, v117
	v_cvt_pk_bf16_f32 v117, v122, v123
	s_and_b64 vcc, exec, s[6:7]
	s_mov_b64 s[6:7], -1
	s_cbranch_vccnz .LBB0_423
	v_ashrrev_i32_e32 v118, 4, v144
	v_or_b32_e32 v118, 8, v118
	s_and_b64 s[6:7], s[78:79], exec
	v_mad_i64_i32 v[118:119], s[44:45], v118, s41, v[136:137]
	s_cselect_b32 s7, s29, s53
	s_cselect_b32 s6, s28, s52
	v_lshlrev_b64 v[118:119], 5, v[118:119]
	v_lshl_add_u64 v[118:119], s[6:7], 0, v[118:119]
	v_lshlrev_b32_e32 v120, 1, v174
	v_mov_b32_e32 v121, v173
	v_lshl_add_u64 v[118:119], v[118:119], 0, v[120:121]
	global_store_dwordx4 v[118:119], v[114:117], off sc1
	s_cbranch_execz .LBB0_424

; __device__ __forceinline__ unsigned cvt_pk_bf16(float lo, float hi) { const f32x2_t v = {lo, hi}; return __builtin_bit_cast(unsigned, __builtin_convertvector(v, bf16x2_t)); }
;     __device__ __forceinline__ void operator()(const f32x4 (&acc)[2][2][4][2], const Unit& u, int wr, int wc, int fr, int fq) const {
;     ...
;                         u32x4 w; w.x = cvt_pk_bf16(v0[0], v0[1]); w.y = cvt_pk_bf16(v0[2], v0[3]); w.z = cvt_pk_bf16(v1[0], v1[1]); w.w = cvt_pk_bf16(v1[2], v1[3]);
;                         if (type == 1) *(u32x4*)(P + (size_t)row * 5120 + 1024 + (pnl - 8) * BM + bj * HALF + lc) = w;
;                         else { const int cg = (pnl - (type == 3 ? 12 : 16)) * BM + bj * HALF + lc;
;                             *(u32x4*)((type == 3 ? XB : ZB) + ((size_t)(cg >> 4) * 8448 + row) * 16 + (cg & 8)) = w; } }
.LBB0_424:
	s_lshl_b32 s34, s67, 1
	v_lshl_add_u64 v[118:119], v[128:129], 0, s[34:35]
	v_lshl_add_u64 v[118:119], v[118:119], 0, v[172:173]
	global_store_dwordx4 v[118:119], v[114:117], off offset:-1792 sc1
	s_andn2_b64 vcc, exec, s[76:77]
	s_cbranch_vccnz .LBB0_428

; __device__ __forceinline__ unsigned cvt_pk_bf16(float lo, float hi) { const f32x2_t v = {lo, hi}; return __builtin_bit_cast(unsigned, __builtin_convertvector(v, bf16x2_t)); }
; __device__ __forceinline__ float silu_f(float x) { return x * __builtin_amdgcn_rcpf(1.0f + __expf(-x)); }
;     __device__ __forceinline__ void operator()(const f32x4 (&acc)[2][2][4][2], const Unit& u, int wr, int wc, int fr, int fq) const {
;     ...
;             for (int m = 0; m < 4; ++m) { const int row = row0 + ai * HALF + m * 16;
;                 if (type == 0) { f32x4 p0, p1;
; #pragma unroll
;                     for (int j = 0; j < 4; ++j) { p0[j] = (acc[ai][0][m][0][j] * osc) * silu_f(acc[ai][1][m][0][j] * osc); p1[j] = (acc[ai][0][m][1][j] * osc) * silu_f(acc[ai][1][m][1][j] * osc); }
;                     u32x4 w; w.x = cvt_pk_bf16(p0[0], p0[1]); w.y = cvt_pk_bf16(p0[2], p0[3]); w.z = cvt_pk_bf16(p1[0], p1[1]); w.w = cvt_pk_bf16(p1[2], p1[3]);
;                     *(u32x4*)(P + (size_t)row * 5120 + pnl * HALF + lc) = w; }
.LBB0_428:
	s_waitcnt lgkmcnt(0)
	v_cndmask_b32_e64 v115, 0, 1, s[8:9]
	v_or_b32_e32 v114, 16, v136
	v_cmp_ne_u32_e64 s[6:7], 1, v115
	s_andn2_b64 vcc, exec, s[8:9]
	s_mov_b64 s[8:9], -1
	s_cbranch_vccnz .LBB0_430
	v_pk_mul_f32 v[116:117], v[134:135], v[102:103]
	v_pk_mul_f32 v[120:121], v[134:135], v[110:111]
	v_mul_f32_e32 v115, 0xbfb8aa3b, v116
	v_exp_f32_e32 v115, v115
	v_pk_mul_f32 v[122:123], v[134:135], v[106:107]
	v_pk_mul_f32 v[124:125], v[134:135], v[112:113]
	v_pk_mul_f32 v[126:127], v[134:135], v[108:109]
	v_add_f32_e32 v115, 1.0, v115
	v_rcp_f32_e32 v118, v115
	v_mul_f32_e32 v115, 0xbfb8aa3b, v117
	v_exp_f32_e32 v115, v115
	s_nop 0
	v_add_f32_e32 v115, 1.0, v115
	v_rcp_f32_e32 v119, v115
	s_nop 0
	v_pk_mul_f32 v[116:117], v[116:117], v[118:119]
	v_pk_mul_f32 v[118:119], v[134:135], v[98:99]
	v_pk_mul_f32 v[116:117], v[116:117], v[120:121]
	v_mul_f32_e32 v115, 0xbfb8aa3b, v118
	v_exp_f32_e32 v115, v115
	v_cvt_pk_bf16_f32 v116, v116, v117
	v_add_f32_e32 v115, 1.0, v115
	v_rcp_f32_e32 v120, v115
	v_mul_f32_e32 v115, 0xbfb8aa3b, v119
	v_exp_f32_e32 v115, v115
	s_nop 0
	v_add_f32_e32 v115, 1.0, v115
	v_rcp_f32_e32 v121, v115
	s_nop 0
	v_pk_mul_f32 v[118:119], v[118:119], v[120:121]
	v_pk_mul_f32 v[120:121], v[134:135], v[104:105]
	v_pk_mul_f32 v[118:119], v[118:119], v[122:123]
	v_mul_f32_e32 v115, 0xbfb8aa3b, v120
	v_exp_f32_e32 v115, v115
	v_cvt_pk_bf16_f32 v118, v118, v119
	v_add_f32_e32 v115, 1.0, v115
	v_rcp_f32_e32 v122, v115
	v_mul_f32_e32 v115, 0xbfb8aa3b, v121
	v_exp_f32_e32 v115, v115
	s_nop 0
	v_add_f32_e32 v115, 1.0, v115
	v_rcp_f32_e32 v123, v115
	s_nop 0
	v_pk_mul_f32 v[120:121], v[120:121], v[122:123]
	v_pk_mul_f32 v[122:123], v[134:135], v[100:101]
	v_pk_mul_f32 v[120:121], v[120:121], v[124:125]
	v_mul_f32_e32 v115, 0xbfb8aa3b, v122
	v_exp_f32_e32 v115, v115
	v_cvt_pk_bf16_f32 v117, v120, v121
	v_mov_b64_e32 v[120:121], s[14:15]
	v_mad_i64_i32 v[120:121], s[8:9], v114, s40, v[120:121]
	v_add_f32_e32 v115, 1.0, v115
	v_rcp_f32_e32 v124, v115
	v_mul_f32_e32 v115, 0xbfb8aa3b, v123
	v_exp_f32_e32 v115, v115
	v_lshl_add_u64 v[120:121], s[86:87], 1, v[120:121]
	v_lshl_add_u64 v[120:121], v[120:121], 0, v[172:173]
	s_mov_b64 s[8:9], 0
	v_add_f32_e32 v115, 1.0, v115
	v_rcp_f32_e32 v125, v115
	s_nop 0
	v_pk_mul_f32 v[122:123], v[122:123], v[124:125]
	s_nop 0
	v_pk_mul_f32 v[122:123], v[122:123], v[126:127]
	s_nop 0
	v_cvt_pk_bf16_f32 v119, v122, v123
	global_store_dwordx4 v[120:121], v[116:119], off sc1

; __device__ __forceinline__ unsigned cvt_pk_bf16(float lo, float hi) { const f32x2_t v = {lo, hi}; return __builtin_bit_cast(unsigned, __builtin_convertvector(v, bf16x2_t)); }
;     __device__ __forceinline__ void operator()(const f32x4 (&acc)[2][2][4][2], const Unit& u, int wr, int wc, int fr, int fq) const {
;     ...
;                         u32x4 w; w.x = cvt_pk_bf16(v0[0], v0[1]); w.y = cvt_pk_bf16(v0[2], v0[3]); w.z = cvt_pk_bf16(v1[0], v1[1]); w.w = cvt_pk_bf16(v1[2], v1[3]);
;                         if (type == 1) *(u32x4*)(P + (size_t)row * 5120 + 1024 + (pnl - 8) * BM + bj * HALF + lc) = w;
;                         else { const int cg = (pnl - (type == 3 ? 12 : 16)) * BM + bj * HALF + lc;
;                             *(u32x4*)((type == 3 ? XB : ZB) + ((size_t)(cg >> 4) * 8448 + row) * 16 + (cg & 8)) = w; } }
.LBB0_438:
	v_ashrrev_i32_e32 v115, 31, v114
	v_cvt_pk_bf16_f32 v106, v116, v117
	v_cvt_pk_bf16_f32 v107, v112, v113
	v_cvt_pk_bf16_f32 v108, v108, v109
	v_cvt_pk_bf16_f32 v109, v118, v119
	s_and_b64 vcc, exec, s[8:9]
	s_mov_b64 s[88:89], -1
	s_cbranch_vccnz .LBB0_440
	v_ashrrev_i32_e32 v112, 4, v144
	s_and_b64 s[44:45], s[78:79], exec
	v_mad_i64_i32 v[112:113], s[88:89], v112, s41, v[114:115]
	s_cselect_b32 s45, s29, s53
	s_cselect_b32 s44, s28, s52
	v_lshlrev_b64 v[112:113], 5, v[112:113]
	v_lshl_add_u64 v[112:113], s[44:45], 0, v[112:113]
	v_lshlrev_b32_e32 v116, 1, v174
	v_mov_b32_e32 v117, v173
	v_lshl_add_u64 v[112:113], v[112:113], 0, v[116:117]
	s_mov_b64 s[88:89], 0
	global_store_dwordx4 v[112:113], v[106:109], off sc1
.LBB0_440:
	v_mad_i64_i32 v[112:113], s[44:45], v114, s40, 0
	s_andn2_b64 vcc, exec, s[88:89]
	v_lshl_add_u64 v[112:113], s[14:15], 0, v[112:113]
	s_cbranch_vccnz .LBB0_442
	s_lshl_b32 s34, s67, 1
	v_lshl_add_u64 v[116:117], v[112:113], 0, s[34:35]
	v_lshl_add_u64 v[116:117], v[116:117], 0, v[172:173]
	global_store_dwordx4 v[116:117], v[106:109], off offset:-2048 sc1

; __device__ __forceinline__ unsigned cvt_pk_bf16(float lo, float hi) { const f32x2_t v = {lo, hi}; return __builtin_bit_cast(unsigned, __builtin_convertvector(v, bf16x2_t)); }
;     __device__ __forceinline__ void operator()(const f32x4 (&acc)[2][2][4][2], const Unit& u, int wr, int wc, int fr, int fq) const {
;     ...
;                         u32x4 w; w.x = cvt_pk_bf16(v0[0], v0[1]); w.y = cvt_pk_bf16(v0[2], v0[3]); w.z = cvt_pk_bf16(v1[0], v1[1]); w.w = cvt_pk_bf16(v1[2], v1[3]);
;                         if (type == 1) *(u32x4*)(P + (size_t)row * 5120 + 1024 + (pnl - 8) * BM + bj * HALF + lc) = w;
;                         else { const int cg = (pnl - (type == 3 ? 12 : 16)) * BM + bj * HALF + lc;
;                             *(u32x4*)((type == 3 ? XB : ZB) + ((size_t)(cg >> 4) * 8448 + row) * 16 + (cg & 8)) = w; } }
.LBB0_446:
	v_cvt_pk_bf16_f32 v98, v102, v103
	v_cvt_pk_bf16_f32 v99, v104, v105
	v_cvt_pk_bf16_f32 v100, v100, v101
	v_cvt_pk_bf16_f32 v101, v106, v107
	s_and_b64 vcc, exec, s[8:9]
	s_mov_b64 s[8:9], -1
	s_cbranch_vccnz .LBB0_454
	v_ashrrev_i32_e32 v102, 4, v144
	v_or_b32_e32 v102, 8, v102
	s_and_b64 s[8:9], s[78:79], exec
	v_mad_i64_i32 v[102:103], s[44:45], v102, s41, v[114:115]
	s_cselect_b32 s9, s29, s53
	s_cselect_b32 s8, s28, s52
	v_lshlrev_b64 v[102:103], 5, v[102:103]
	v_lshl_add_u64 v[102:103], s[8:9], 0, v[102:103]
	v_lshlrev_b32_e32 v104, 1, v174
	v_mov_b32_e32 v105, v173
	v_lshl_add_u64 v[102:103], v[102:103], 0, v[104:105]
	global_store_dwordx4 v[102:103], v[98:101], off sc1
	s_cbranch_execz .LBB0_455

; __device__ __forceinline__ unsigned cvt_pk_bf16(float lo, float hi) { const f32x2_t v = {lo, hi}; return __builtin_bit_cast(unsigned, __builtin_convertvector(v, bf16x2_t)); }
;     __device__ __forceinline__ void operator()(const f32x4 (&acc)[2][2][4][2], const Unit& u, int wr, int wc, int fr, int fq) const {
;     ...
;                         u32x4 w; w.x = cvt_pk_bf16(v0[0], v0[1]); w.y = cvt_pk_bf16(v0[2], v0[3]); w.z = cvt_pk_bf16(v1[0], v1[1]); w.w = cvt_pk_bf16(v1[2], v1[3]);
;                         if (type == 1) *(u32x4*)(P + (size_t)row * 5120 + 1024 + (pnl - 8) * BM + bj * HALF + lc) = w;
;                         else { const int cg = (pnl - (type == 3 ? 12 : 16)) * BM + bj * HALF + lc;
;                             *(u32x4*)((type == 3 ? XB : ZB) + ((size_t)(cg >> 4) * 8448 + row) * 16 + (cg & 8)) = w; } }
.LBB0_455:
	s_lshl_b32 s34, s67, 1
	v_lshl_add_u64 v[102:103], v[112:113], 0, s[34:35]
	v_lshl_add_u64 v[102:103], v[102:103], 0, v[172:173]
	global_store_dwordx4 v[102:103], v[98:101], off offset:-1792 sc1
	s_andn2_b64 vcc, exec, s[76:77]
	s_cbranch_vccz .LBB0_449

; __device__ __forceinline__ unsigned cvt_pk_bf16(float lo, float hi) { const f32x2_t v = {lo, hi}; return __builtin_bit_cast(unsigned, __builtin_convertvector(v, bf16x2_t)); }
; __device__ __forceinline__ float silu_f(float x) { return x * __builtin_amdgcn_rcpf(1.0f + __expf(-x)); }
;     __device__ __forceinline__ void operator()(const f32x4 (&acc)[2][2][4][2], const Unit& u, int wr, int wc, int fr, int fq) const {
;     ...
;             for (int m = 0; m < 4; ++m) { const int row = row0 + ai * HALF + m * 16;
;                 if (type == 0) { f32x4 p0, p1;
; #pragma unroll
;                     for (int j = 0; j < 4; ++j) { p0[j] = (acc[ai][0][m][0][j] * osc) * silu_f(acc[ai][1][m][0][j] * osc); p1[j] = (acc[ai][0][m][1][j] * osc) * silu_f(acc[ai][1][m][1][j] * osc); }
;                     u32x4 w; w.x = cvt_pk_bf16(p0[0], p0[1]); w.y = cvt_pk_bf16(p0[2], p0[3]); w.z = cvt_pk_bf16(p1[0], p1[1]); w.w = cvt_pk_bf16(p1[2], p1[3]);
;                     *(u32x4*)(P + (size_t)row * 5120 + pnl * HALF + lc) = w; }
.LBB0_457:
	s_waitcnt lgkmcnt(0)
	v_pk_mul_f32 v[100:101], v[134:135], v[86:87]
	v_pk_mul_f32 v[104:105], v[134:135], v[94:95]
	v_mul_f32_e32 v99, 0xbfb8aa3b, v100
	v_exp_f32_e32 v99, v99
	v_pk_mul_f32 v[106:107], v[134:135], v[90:91]
	v_pk_mul_f32 v[108:109], v[134:135], v[96:97]
	v_pk_mul_f32 v[110:111], v[134:135], v[92:93]
	v_add_f32_e32 v99, 1.0, v99
	v_rcp_f32_e32 v102, v99
	v_mul_f32_e32 v99, 0xbfb8aa3b, v101
	v_exp_f32_e32 v99, v99
	s_nop 0
	v_add_f32_e32 v99, 1.0, v99
	v_rcp_f32_e32 v103, v99
	s_nop 0
	v_pk_mul_f32 v[100:101], v[100:101], v[102:103]
	v_pk_mul_f32 v[102:103], v[134:135], v[82:83]
	v_pk_mul_f32 v[100:101], v[100:101], v[104:105]
	v_mul_f32_e32 v99, 0xbfb8aa3b, v102
	v_exp_f32_e32 v99, v99
	v_cvt_pk_bf16_f32 v100, v100, v101
	v_add_f32_e32 v99, 1.0, v99
	v_rcp_f32_e32 v104, v99
	v_mul_f32_e32 v99, 0xbfb8aa3b, v103
	v_exp_f32_e32 v99, v99
	s_nop 0
	v_add_f32_e32 v99, 1.0, v99
	v_rcp_f32_e32 v105, v99
	s_nop 0
	v_pk_mul_f32 v[102:103], v[102:103], v[104:105]
	v_pk_mul_f32 v[104:105], v[134:135], v[88:89]
	v_pk_mul_f32 v[102:103], v[102:103], v[106:107]
	v_mul_f32_e32 v99, 0xbfb8aa3b, v104
	v_exp_f32_e32 v99, v99
	v_cvt_pk_bf16_f32 v102, v102, v103
	v_add_f32_e32 v99, 1.0, v99
	v_rcp_f32_e32 v106, v99
	v_mul_f32_e32 v99, 0xbfb8aa3b, v105
	v_exp_f32_e32 v99, v99
	s_nop 0
	v_add_f32_e32 v99, 1.0, v99
	v_rcp_f32_e32 v107, v99
	s_nop 0
	v_pk_mul_f32 v[104:105], v[104:105], v[106:107]
	v_pk_mul_f32 v[106:107], v[134:135], v[84:85]
	v_pk_mul_f32 v[104:105], v[104:105], v[108:109]
	v_mul_f32_e32 v99, 0xbfb8aa3b, v106
	v_exp_f32_e32 v99, v99
	v_cvt_pk_bf16_f32 v101, v104, v105
	v_mov_b64_e32 v[104:105], s[14:15]
	v_mad_i64_i32 v[104:105], s[8:9], v98, s40, v[104:105]
	v_add_f32_e32 v99, 1.0, v99
	v_rcp_f32_e32 v108, v99
	v_mul_f32_e32 v99, 0xbfb8aa3b, v107
	v_exp_f32_e32 v99, v99
	v_lshl_add_u64 v[104:105], s[86:87], 1, v[104:105]
	v_lshl_add_u64 v[104:105], v[104:105], 0, v[172:173]
	s_mov_b64 s[8:9], 0
	v_add_f32_e32 v99, 1.0, v99
	v_rcp_f32_e32 v109, v99
	s_nop 0
	v_pk_mul_f32 v[106:107], v[106:107], v[108:109]
	s_nop 0
	v_pk_mul_f32 v[106:107], v[106:107], v[110:111]
	s_nop 0
	v_cvt_pk_bf16_f32 v103, v106, v107
	global_store_dwordx4 v[104:105], v[100:103], off sc1

; __device__ __forceinline__ unsigned cvt_pk_bf16(float lo, float hi) { const f32x2_t v = {lo, hi}; return __builtin_bit_cast(unsigned, __builtin_convertvector(v, bf16x2_t)); }
;     __device__ __forceinline__ void operator()(const f32x4 (&acc)[2][2][4][2], const Unit& u, int wr, int wc, int fr, int fq) const {
;     ...
;                         u32x4 w; w.x = cvt_pk_bf16(v0[0], v0[1]); w.y = cvt_pk_bf16(v0[2], v0[3]); w.z = cvt_pk_bf16(v1[0], v1[1]); w.w = cvt_pk_bf16(v1[2], v1[3]);
;                         if (type == 1) *(u32x4*)(P + (size_t)row * 5120 + 1024 + (pnl - 8) * BM + bj * HALF + lc) = w;
;                         else { const int cg = (pnl - (type == 3 ? 12 : 16)) * BM + bj * HALF + lc;
;                             *(u32x4*)((type == 3 ? XB : ZB) + ((size_t)(cg >> 4) * 8448 + row) * 16 + (cg & 8)) = w; } }
.LBB0_466:
	v_ashrrev_i32_e32 v99, 31, v98
	v_cvt_pk_bf16_f32 v90, v100, v101
	v_cvt_pk_bf16_f32 v91, v96, v97
	v_cvt_pk_bf16_f32 v92, v92, v93
	v_cvt_pk_bf16_f32 v93, v102, v103
	s_and_b64 vcc, exec, s[8:9]
	s_mov_b64 s[88:89], -1
	s_cbranch_vccnz .LBB0_468
	v_ashrrev_i32_e32 v96, 4, v144
	s_and_b64 s[44:45], s[78:79], exec
	v_mad_i64_i32 v[96:97], s[88:89], v96, s41, v[98:99]
	s_cselect_b32 s45, s29, s53
	s_cselect_b32 s44, s28, s52
	v_lshlrev_b64 v[96:97], 5, v[96:97]
	v_lshl_add_u64 v[96:97], s[44:45], 0, v[96:97]
	v_lshlrev_b32_e32 v100, 1, v174
	v_mov_b32_e32 v101, v173
	v_lshl_add_u64 v[96:97], v[96:97], 0, v[100:101]
	s_mov_b64 s[88:89], 0
	global_store_dwordx4 v[96:97], v[90:93], off sc1
.LBB0_468:
	v_mad_i64_i32 v[96:97], s[44:45], v98, s40, 0
	s_andn2_b64 vcc, exec, s[88:89]
	v_lshl_add_u64 v[96:97], s[14:15], 0, v[96:97]
	s_cbranch_vccnz .LBB0_470
	s_lshl_b32 s34, s67, 1
	v_lshl_add_u64 v[100:101], v[96:97], 0, s[34:35]
	v_lshl_add_u64 v[100:101], v[100:101], 0, v[172:173]
	global_store_dwordx4 v[100:101], v[90:93], off offset:-2048 sc1

; __device__ __forceinline__ unsigned cvt_pk_bf16(float lo, float hi) { const f32x2_t v = {lo, hi}; return __builtin_bit_cast(unsigned, __builtin_convertvector(v, bf16x2_t)); }
;     __device__ __forceinline__ void operator()(const f32x4 (&acc)[2][2][4][2], const Unit& u, int wr, int wc, int fr, int fq) const {
;     ...
;                         u32x4 w; w.x = cvt_pk_bf16(v0[0], v0[1]); w.y = cvt_pk_bf16(v0[2], v0[3]); w.z = cvt_pk_bf16(v1[0], v1[1]); w.w = cvt_pk_bf16(v1[2], v1[3]);
;                         if (type == 1) *(u32x4*)(P + (size_t)row * 5120 + 1024 + (pnl - 8) * BM + bj * HALF + lc) = w;
;                         else { const int cg = (pnl - (type == 3 ? 12 : 16)) * BM + bj * HALF + lc;
;                             *(u32x4*)((type == 3 ? XB : ZB) + ((size_t)(cg >> 4) * 8448 + row) * 16 + (cg & 8)) = w; } }
.LBB0_474:
	v_cvt_pk_bf16_f32 v82, v86, v87
	v_cvt_pk_bf16_f32 v83, v88, v89
	v_cvt_pk_bf16_f32 v84, v84, v85
	v_cvt_pk_bf16_f32 v85, v90, v91
	s_and_b64 vcc, exec, s[8:9]
	s_mov_b64 s[8:9], -1
	s_cbranch_vccnz .LBB0_482
	v_ashrrev_i32_e32 v86, 4, v144
	v_or_b32_e32 v86, 8, v86
	s_and_b64 s[8:9], s[78:79], exec
	v_mad_i64_i32 v[86:87], s[44:45], v86, s41, v[98:99]
	s_cselect_b32 s9, s29, s53
	s_cselect_b32 s8, s28, s52
	v_lshlrev_b64 v[86:87], 5, v[86:87]
	v_lshl_add_u64 v[86:87], s[8:9], 0, v[86:87]
	v_lshlrev_b32_e32 v88, 1, v174
	v_mov_b32_e32 v89, v173
	v_lshl_add_u64 v[86:87], v[86:87], 0, v[88:89]
	global_store_dwordx4 v[86:87], v[82:85], off sc1
	s_cbranch_execz .LBB0_483

; __device__ __forceinline__ unsigned cvt_pk_bf16(float lo, float hi) { const f32x2_t v = {lo, hi}; return __builtin_bit_cast(unsigned, __builtin_convertvector(v, bf16x2_t)); }
;     __device__ __forceinline__ void operator()(const f32x4 (&acc)[2][2][4][2], const Unit& u, int wr, int wc, int fr, int fq) const {
;     ...
;                         u32x4 w; w.x = cvt_pk_bf16(v0[0], v0[1]); w.y = cvt_pk_bf16(v0[2], v0[3]); w.z = cvt_pk_bf16(v1[0], v1[1]); w.w = cvt_pk_bf16(v1[2], v1[3]);
;                         if (type == 1) *(u32x4*)(P + (size_t)row * 5120 + 1024 + (pnl - 8) * BM + bj * HALF + lc) = w;
;                         else { const int cg = (pnl - (type == 3 ? 12 : 16)) * BM + bj * HALF + lc;
;                             *(u32x4*)((type == 3 ? XB : ZB) + ((size_t)(cg >> 4) * 8448 + row) * 16 + (cg & 8)) = w; } }
.LBB0_483:
	s_lshl_b32 s34, s67, 1
	v_lshl_add_u64 v[86:87], v[96:97], 0, s[34:35]
	v_lshl_add_u64 v[86:87], v[86:87], 0, v[172:173]
	global_store_dwordx4 v[86:87], v[82:85], off offset:-1792 sc1
	s_andn2_b64 vcc, exec, s[76:77]
	s_cbranch_vccz .LBB0_477

; __device__ __forceinline__ unsigned cvt_pk_bf16(float lo, float hi) { const f32x2_t v = {lo, hi}; return __builtin_bit_cast(unsigned, __builtin_convertvector(v, bf16x2_t)); }
; __device__ __forceinline__ float silu_f(float x) { return x * __builtin_amdgcn_rcpf(1.0f + __expf(-x)); }
;     __device__ __forceinline__ void operator()(const f32x4 (&acc)[2][2][4][2], const Unit& u, int wr, int wc, int fr, int fq) const {
;     ...
;             for (int m = 0; m < 4; ++m) { const int row = row0 + ai * HALF + m * 16;
;                 if (type == 0) { f32x4 p0, p1;
; #pragma unroll
;                     for (int j = 0; j < 4; ++j) { p0[j] = (acc[ai][0][m][0][j] * osc) * silu_f(acc[ai][1][m][0][j] * osc); p1[j] = (acc[ai][0][m][1][j] * osc) * silu_f(acc[ai][1][m][1][j] * osc); }
;                     u32x4 w; w.x = cvt_pk_bf16(p0[0], p0[1]); w.y = cvt_pk_bf16(p0[2], p0[3]); w.z = cvt_pk_bf16(p1[0], p1[1]); w.w = cvt_pk_bf16(p1[2], p1[3]);
;                     *(u32x4*)(P + (size_t)row * 5120 + pnl * HALF + lc) = w; }
.LBB0_485:
	s_waitcnt lgkmcnt(0)
	v_pk_mul_f32 v[84:85], v[134:135], v[70:71]
	v_pk_mul_f32 v[88:89], v[134:135], v[78:79]
	v_mul_f32_e32 v83, 0xbfb8aa3b, v84
	v_exp_f32_e32 v83, v83
	v_pk_mul_f32 v[90:91], v[134:135], v[74:75]
	v_pk_mul_f32 v[92:93], v[134:135], v[80:81]
	v_pk_mul_f32 v[94:95], v[134:135], v[76:77]
	v_add_f32_e32 v83, 1.0, v83
	v_rcp_f32_e32 v86, v83
	v_mul_f32_e32 v83, 0xbfb8aa3b, v85
	v_exp_f32_e32 v83, v83
	s_nop 0
	v_add_f32_e32 v83, 1.0, v83
	v_rcp_f32_e32 v87, v83
	s_nop 0
	v_pk_mul_f32 v[84:85], v[84:85], v[86:87]
	v_pk_mul_f32 v[86:87], v[134:135], v[66:67]
	v_pk_mul_f32 v[84:85], v[84:85], v[88:89]
	v_mul_f32_e32 v83, 0xbfb8aa3b, v86
	v_exp_f32_e32 v83, v83
	v_cvt_pk_bf16_f32 v84, v84, v85
	v_add_f32_e32 v83, 1.0, v83
	v_rcp_f32_e32 v88, v83
	v_mul_f32_e32 v83, 0xbfb8aa3b, v87
	v_exp_f32_e32 v83, v83
	s_nop 0
	v_add_f32_e32 v83, 1.0, v83
	v_rcp_f32_e32 v89, v83
	s_nop 0
	v_pk_mul_f32 v[86:87], v[86:87], v[88:89]
	v_pk_mul_f32 v[88:89], v[134:135], v[72:73]
	v_pk_mul_f32 v[86:87], v[86:87], v[90:91]
	v_mul_f32_e32 v83, 0xbfb8aa3b, v88
	v_exp_f32_e32 v83, v83
	v_cvt_pk_bf16_f32 v86, v86, v87
	v_add_f32_e32 v83, 1.0, v83
	v_rcp_f32_e32 v90, v83
	v_mul_f32_e32 v83, 0xbfb8aa3b, v89
	v_exp_f32_e32 v83, v83
	s_nop 0
	v_add_f32_e32 v83, 1.0, v83
	v_rcp_f32_e32 v91, v83
	s_nop 0
	v_pk_mul_f32 v[88:89], v[88:89], v[90:91]
	v_pk_mul_f32 v[90:91], v[134:135], v[68:69]
	v_pk_mul_f32 v[88:89], v[88:89], v[92:93]
	v_mul_f32_e32 v83, 0xbfb8aa3b, v90
	v_exp_f32_e32 v83, v83
	v_cvt_pk_bf16_f32 v85, v88, v89
	v_mov_b64_e32 v[88:89], s[14:15]
	v_mad_i64_i32 v[88:89], s[8:9], v82, s40, v[88:89]
	v_add_f32_e32 v83, 1.0, v83
	v_rcp_f32_e32 v92, v83
	v_mul_f32_e32 v83, 0xbfb8aa3b, v91
	v_exp_f32_e32 v83, v83
	v_lshl_add_u64 v[88:89], s[86:87], 1, v[88:89]
	v_lshl_add_u64 v[88:89], v[88:89], 0, v[172:173]
	s_mov_b64 s[8:9], 0
	v_add_f32_e32 v83, 1.0, v83
	v_rcp_f32_e32 v93, v83
	s_nop 0
	v_pk_mul_f32 v[90:91], v[90:91], v[92:93]
	s_nop 0
	v_pk_mul_f32 v[90:91], v[90:91], v[94:95]
	s_nop 0
	v_cvt_pk_bf16_f32 v87, v90, v91
	global_store_dwordx4 v[88:89], v[84:87], off sc1

; __device__ __forceinline__ unsigned cvt_pk_bf16(float lo, float hi) { const f32x2_t v = {lo, hi}; return __builtin_bit_cast(unsigned, __builtin_convertvector(v, bf16x2_t)); }
;     __device__ __forceinline__ void operator()(const f32x4 (&acc)[2][2][4][2], const Unit& u, int wr, int wc, int fr, int fq) const {
;     ...
;                         u32x4 w; w.x = cvt_pk_bf16(v0[0], v0[1]); w.y = cvt_pk_bf16(v0[2], v0[3]); w.z = cvt_pk_bf16(v1[0], v1[1]); w.w = cvt_pk_bf16(v1[2], v1[3]);
;                         if (type == 1) *(u32x4*)(P + (size_t)row * 5120 + 1024 + (pnl - 8) * BM + bj * HALF + lc) = w;
;                         else { const int cg = (pnl - (type == 3 ? 12 : 16)) * BM + bj * HALF + lc;
;                             *(u32x4*)((type == 3 ? XB : ZB) + ((size_t)(cg >> 4) * 8448 + row) * 16 + (cg & 8)) = w; } }
.LBB0_494:
	v_ashrrev_i32_e32 v83, 31, v82
	v_cvt_pk_bf16_f32 v74, v84, v85
	v_cvt_pk_bf16_f32 v75, v80, v81
	v_cvt_pk_bf16_f32 v76, v76, v77
	v_cvt_pk_bf16_f32 v77, v86, v87
	s_and_b64 vcc, exec, s[8:9]
	s_mov_b64 s[88:89], -1
	s_cbranch_vccnz .LBB0_496
	v_ashrrev_i32_e32 v80, 4, v144
	s_and_b64 s[44:45], s[78:79], exec
	v_mad_i64_i32 v[80:81], s[88:89], v80, s41, v[82:83]
	s_cselect_b32 s45, s29, s53
	s_cselect_b32 s44, s28, s52
	v_lshlrev_b64 v[80:81], 5, v[80:81]
	v_lshl_add_u64 v[80:81], s[44:45], 0, v[80:81]
	v_lshlrev_b32_e32 v84, 1, v174
	v_mov_b32_e32 v85, v173
	v_lshl_add_u64 v[80:81], v[80:81], 0, v[84:85]
	s_mov_b64 s[88:89], 0
	global_store_dwordx4 v[80:81], v[74:77], off sc1
.LBB0_496:
	v_mad_i64_i32 v[80:81], s[44:45], v82, s40, 0
	s_andn2_b64 vcc, exec, s[88:89]
	v_lshl_add_u64 v[80:81], s[14:15], 0, v[80:81]
	s_cbranch_vccnz .LBB0_498
	s_lshl_b32 s34, s67, 1
	v_lshl_add_u64 v[84:85], v[80:81], 0, s[34:35]
	v_lshl_add_u64 v[84:85], v[84:85], 0, v[172:173]
	global_store_dwordx4 v[84:85], v[74:77], off offset:-2048 sc1

; __device__ __forceinline__ unsigned cvt_pk_bf16(float lo, float hi) { const f32x2_t v = {lo, hi}; return __builtin_bit_cast(unsigned, __builtin_convertvector(v, bf16x2_t)); }
;     __device__ __forceinline__ void operator()(const f32x4 (&acc)[2][2][4][2], const Unit& u, int wr, int wc, int fr, int fq) const {
;     ...
;                         u32x4 w; w.x = cvt_pk_bf16(v0[0], v0[1]); w.y = cvt_pk_bf16(v0[2], v0[3]); w.z = cvt_pk_bf16(v1[0], v1[1]); w.w = cvt_pk_bf16(v1[2], v1[3]);
;                         if (type == 1) *(u32x4*)(P + (size_t)row * 5120 + 1024 + (pnl - 8) * BM + bj * HALF + lc) = w;
;                         else { const int cg = (pnl - (type == 3 ? 12 : 16)) * BM + bj * HALF + lc;
;                             *(u32x4*)((type == 3 ? XB : ZB) + ((size_t)(cg >> 4) * 8448 + row) * 16 + (cg & 8)) = w; } }
.LBB0_502:
	v_cvt_pk_bf16_f32 v66, v70, v71
	v_cvt_pk_bf16_f32 v67, v72, v73
	v_cvt_pk_bf16_f32 v68, v68, v69
	v_cvt_pk_bf16_f32 v69, v74, v75
	s_and_b64 vcc, exec, s[8:9]
	s_mov_b64 s[8:9], -1
	s_cbranch_vccnz .LBB0_510
	v_ashrrev_i32_e32 v70, 4, v144
	v_or_b32_e32 v70, 8, v70
	s_and_b64 s[8:9], s[78:79], exec
	v_mad_i64_i32 v[70:71], s[44:45], v70, s41, v[82:83]
	s_cselect_b32 s9, s29, s53
	s_cselect_b32 s8, s28, s52
	v_lshlrev_b64 v[70:71], 5, v[70:71]
	v_lshl_add_u64 v[70:71], s[8:9], 0, v[70:71]
	v_lshlrev_b32_e32 v72, 1, v174
	v_mov_b32_e32 v73, v173
	v_lshl_add_u64 v[70:71], v[70:71], 0, v[72:73]
	global_store_dwordx4 v[70:71], v[66:69], off sc1
	s_cbranch_execz .LBB0_511

; __device__ __forceinline__ unsigned cvt_pk_bf16(float lo, float hi) { const f32x2_t v = {lo, hi}; return __builtin_bit_cast(unsigned, __builtin_convertvector(v, bf16x2_t)); }
;     __device__ __forceinline__ void operator()(const f32x4 (&acc)[2][2][4][2], const Unit& u, int wr, int wc, int fr, int fq) const {
;     ...
;                         u32x4 w; w.x = cvt_pk_bf16(v0[0], v0[1]); w.y = cvt_pk_bf16(v0[2], v0[3]); w.z = cvt_pk_bf16(v1[0], v1[1]); w.w = cvt_pk_bf16(v1[2], v1[3]);
;                         if (type == 1) *(u32x4*)(P + (size_t)row * 5120 + 1024 + (pnl - 8) * BM + bj * HALF + lc) = w;
;                         else { const int cg = (pnl - (type == 3 ? 12 : 16)) * BM + bj * HALF + lc;
;                             *(u32x4*)((type == 3 ? XB : ZB) + ((size_t)(cg >> 4) * 8448 + row) * 16 + (cg & 8)) = w; } }
.LBB0_511:
	s_lshl_b32 s34, s67, 1
	v_lshl_add_u64 v[70:71], v[80:81], 0, s[34:35]
	v_lshl_add_u64 v[70:71], v[70:71], 0, v[172:173]
	global_store_dwordx4 v[70:71], v[66:69], off offset:-1792 sc1
	s_andn2_b64 vcc, exec, s[76:77]
	s_cbranch_vccz .LBB0_505

; __device__ __forceinline__ unsigned cvt_pk_bf16(float lo, float hi) { const f32x2_t v = {lo, hi}; return __builtin_bit_cast(unsigned, __builtin_convertvector(v, bf16x2_t)); }
; __device__ __forceinline__ float silu_f(float x) { return x * __builtin_amdgcn_rcpf(1.0f + __expf(-x)); }
;     __device__ __forceinline__ void operator()(const f32x4 (&acc)[2][2][4][2], const Unit& u, int wr, int wc, int fr, int fq) const {
;     ...
;             for (int m = 0; m < 4; ++m) { const int row = row0 + ai * HALF + m * 16;
;                 if (type == 0) { f32x4 p0, p1;
; #pragma unroll
;                     for (int j = 0; j < 4; ++j) { p0[j] = (acc[ai][0][m][0][j] * osc) * silu_f(acc[ai][1][m][0][j] * osc); p1[j] = (acc[ai][0][m][1][j] * osc) * silu_f(acc[ai][1][m][1][j] * osc); }
;                     u32x4 w; w.x = cvt_pk_bf16(p0[0], p0[1]); w.y = cvt_pk_bf16(p0[2], p0[3]); w.z = cvt_pk_bf16(p1[0], p1[1]); w.w = cvt_pk_bf16(p1[2], p1[3]);
;                     *(u32x4*)(P + (size_t)row * 5120 + pnl * HALF + lc) = w; }
.LBB0_513:
	s_waitcnt lgkmcnt(0)
	v_pk_mul_f32 v[68:69], v[134:135], v[54:55]
	v_pk_mul_f32 v[72:73], v[134:135], v[62:63]
	v_mul_f32_e32 v67, 0xbfb8aa3b, v68
	v_exp_f32_e32 v67, v67
	v_pk_mul_f32 v[74:75], v[134:135], v[58:59]
	v_pk_mul_f32 v[76:77], v[134:135], v[64:65]
	v_pk_mul_f32 v[78:79], v[134:135], v[60:61]
	v_add_f32_e32 v67, 1.0, v67
	v_rcp_f32_e32 v70, v67
	v_mul_f32_e32 v67, 0xbfb8aa3b, v69
	v_exp_f32_e32 v67, v67
	s_nop 0
	v_add_f32_e32 v67, 1.0, v67
	v_rcp_f32_e32 v71, v67
	s_nop 0
	v_pk_mul_f32 v[68:69], v[68:69], v[70:71]
	v_pk_mul_f32 v[70:71], v[134:135], v[50:51]
	v_pk_mul_f32 v[68:69], v[68:69], v[72:73]
	v_mul_f32_e32 v67, 0xbfb8aa3b, v70
	v_exp_f32_e32 v67, v67
	v_cvt_pk_bf16_f32 v68, v68, v69
	v_add_f32_e32 v67, 1.0, v67
	v_rcp_f32_e32 v72, v67
	v_mul_f32_e32 v67, 0xbfb8aa3b, v71
	v_exp_f32_e32 v67, v67
	s_nop 0
	v_add_f32_e32 v67, 1.0, v67
	v_rcp_f32_e32 v73, v67
	s_nop 0
	v_pk_mul_f32 v[70:71], v[70:71], v[72:73]
	v_pk_mul_f32 v[72:73], v[134:135], v[56:57]
	v_pk_mul_f32 v[70:71], v[70:71], v[74:75]
	v_mul_f32_e32 v67, 0xbfb8aa3b, v72
	v_exp_f32_e32 v67, v67
	v_cvt_pk_bf16_f32 v70, v70, v71
	v_add_f32_e32 v67, 1.0, v67
	v_rcp_f32_e32 v74, v67
	v_mul_f32_e32 v67, 0xbfb8aa3b, v73
	v_exp_f32_e32 v67, v67
	s_nop 0
	v_add_f32_e32 v67, 1.0, v67
	v_rcp_f32_e32 v75, v67
	s_nop 0
	v_pk_mul_f32 v[72:73], v[72:73], v[74:75]
	v_pk_mul_f32 v[74:75], v[134:135], v[52:53]
	v_pk_mul_f32 v[72:73], v[72:73], v[76:77]
	v_mul_f32_e32 v67, 0xbfb8aa3b, v74
	v_exp_f32_e32 v67, v67
	v_cvt_pk_bf16_f32 v69, v72, v73
	v_mov_b64_e32 v[72:73], s[14:15]
	v_mad_i64_i32 v[72:73], s[8:9], v66, s40, v[72:73]
	v_add_f32_e32 v67, 1.0, v67
	v_rcp_f32_e32 v76, v67
	v_mul_f32_e32 v67, 0xbfb8aa3b, v75
	v_exp_f32_e32 v67, v67
	v_lshl_add_u64 v[72:73], s[86:87], 1, v[72:73]
	v_lshl_add_u64 v[72:73], v[72:73], 0, v[172:173]
	s_mov_b64 s[8:9], 0
	v_add_f32_e32 v67, 1.0, v67
	v_rcp_f32_e32 v77, v67
	s_nop 0
	v_pk_mul_f32 v[74:75], v[74:75], v[76:77]
	s_nop 0
	v_pk_mul_f32 v[74:75], v[74:75], v[78:79]
	s_nop 0
	v_cvt_pk_bf16_f32 v71, v74, v75
	global_store_dwordx4 v[72:73], v[68:71], off sc1

; __device__ __forceinline__ unsigned cvt_pk_bf16(float lo, float hi) { const f32x2_t v = {lo, hi}; return __builtin_bit_cast(unsigned, __builtin_convertvector(v, bf16x2_t)); }
;     __device__ __forceinline__ void operator()(const f32x4 (&acc)[2][2][4][2], const Unit& u, int wr, int wc, int fr, int fq) const {
;     ...
;                         u32x4 w; w.x = cvt_pk_bf16(v0[0], v0[1]); w.y = cvt_pk_bf16(v0[2], v0[3]); w.z = cvt_pk_bf16(v1[0], v1[1]); w.w = cvt_pk_bf16(v1[2], v1[3]);
;                         if (type == 1) *(u32x4*)(P + (size_t)row * 5120 + 1024 + (pnl - 8) * BM + bj * HALF + lc) = w;
;                         else { const int cg = (pnl - (type == 3 ? 12 : 16)) * BM + bj * HALF + lc;
;                             *(u32x4*)((type == 3 ? XB : ZB) + ((size_t)(cg >> 4) * 8448 + row) * 16 + (cg & 8)) = w; } }
.LBB0_522:
	v_ashrrev_i32_e32 v67, 31, v66
	v_cvt_pk_bf16_f32 v58, v68, v69
	v_cvt_pk_bf16_f32 v59, v64, v65
	v_cvt_pk_bf16_f32 v60, v60, v61
	v_cvt_pk_bf16_f32 v61, v70, v71
	s_and_b64 vcc, exec, s[8:9]
	s_mov_b64 s[88:89], -1
	s_cbranch_vccnz .LBB0_524
	v_ashrrev_i32_e32 v64, 4, v144
	s_and_b64 s[44:45], s[78:79], exec
	v_mad_i64_i32 v[64:65], s[88:89], v64, s41, v[66:67]
	s_cselect_b32 s45, s29, s53
	s_cselect_b32 s44, s28, s52
	v_lshlrev_b64 v[64:65], 5, v[64:65]
	v_lshl_add_u64 v[64:65], s[44:45], 0, v[64:65]
	v_lshlrev_b32_e32 v68, 1, v174
	v_mov_b32_e32 v69, v173
	v_lshl_add_u64 v[64:65], v[64:65], 0, v[68:69]
	s_mov_b64 s[88:89], 0
	global_store_dwordx4 v[64:65], v[58:61], off sc1
.LBB0_524:
	v_mad_i64_i32 v[64:65], s[44:45], v66, s40, 0
	s_andn2_b64 vcc, exec, s[88:89]
	v_lshl_add_u64 v[64:65], s[14:15], 0, v[64:65]
	s_cbranch_vccnz .LBB0_526
	s_lshl_b32 s34, s67, 1
	v_lshl_add_u64 v[68:69], v[64:65], 0, s[34:35]
	v_lshl_add_u64 v[68:69], v[68:69], 0, v[172:173]
	global_store_dwordx4 v[68:69], v[58:61], off offset:-2048 sc1

; __device__ __forceinline__ unsigned cvt_pk_bf16(float lo, float hi) { const f32x2_t v = {lo, hi}; return __builtin_bit_cast(unsigned, __builtin_convertvector(v, bf16x2_t)); }
;     __device__ __forceinline__ void operator()(const f32x4 (&acc)[2][2][4][2], const Unit& u, int wr, int wc, int fr, int fq) const {
;     ...
;                         u32x4 w; w.x = cvt_pk_bf16(v0[0], v0[1]); w.y = cvt_pk_bf16(v0[2], v0[3]); w.z = cvt_pk_bf16(v1[0], v1[1]); w.w = cvt_pk_bf16(v1[2], v1[3]);
;                         if (type == 1) *(u32x4*)(P + (size_t)row * 5120 + 1024 + (pnl - 8) * BM + bj * HALF + lc) = w;
;                         else { const int cg = (pnl - (type == 3 ? 12 : 16)) * BM + bj * HALF + lc;
;                             *(u32x4*)((type == 3 ? XB : ZB) + ((size_t)(cg >> 4) * 8448 + row) * 16 + (cg & 8)) = w; } }
.LBB0_530:
	v_cvt_pk_bf16_f32 v50, v54, v55
	v_cvt_pk_bf16_f32 v51, v56, v57
	v_cvt_pk_bf16_f32 v52, v52, v53
	v_cvt_pk_bf16_f32 v53, v58, v59
	s_and_b64 vcc, exec, s[8:9]
	s_mov_b64 s[8:9], -1
	s_cbranch_vccnz .LBB0_538
	v_ashrrev_i32_e32 v54, 4, v144
	v_or_b32_e32 v54, 8, v54
	s_and_b64 s[8:9], s[78:79], exec
	v_mad_i64_i32 v[54:55], s[44:45], v54, s41, v[66:67]
	s_cselect_b32 s9, s29, s53
	s_cselect_b32 s8, s28, s52
	v_lshlrev_b64 v[54:55], 5, v[54:55]
	v_lshl_add_u64 v[54:55], s[8:9], 0, v[54:55]
	v_lshlrev_b32_e32 v56, 1, v174
	v_mov_b32_e32 v57, v173
	v_lshl_add_u64 v[54:55], v[54:55], 0, v[56:57]
	global_store_dwordx4 v[54:55], v[50:53], off sc1
	s_cbranch_execz .LBB0_539

; __device__ __forceinline__ unsigned cvt_pk_bf16(float lo, float hi) { const f32x2_t v = {lo, hi}; return __builtin_bit_cast(unsigned, __builtin_convertvector(v, bf16x2_t)); }
;     __device__ __forceinline__ void operator()(const f32x4 (&acc)[2][2][4][2], const Unit& u, int wr, int wc, int fr, int fq) const {
;     ...
;                         u32x4 w; w.x = cvt_pk_bf16(v0[0], v0[1]); w.y = cvt_pk_bf16(v0[2], v0[3]); w.z = cvt_pk_bf16(v1[0], v1[1]); w.w = cvt_pk_bf16(v1[2], v1[3]);
;                         if (type == 1) *(u32x4*)(P + (size_t)row * 5120 + 1024 + (pnl - 8) * BM + bj * HALF + lc) = w;
;                         else { const int cg = (pnl - (type == 3 ? 12 : 16)) * BM + bj * HALF + lc;
;                             *(u32x4*)((type == 3 ? XB : ZB) + ((size_t)(cg >> 4) * 8448 + row) * 16 + (cg & 8)) = w; } }
.LBB0_539:
	s_lshl_b32 s34, s67, 1
	v_lshl_add_u64 v[54:55], v[64:65], 0, s[34:35]
	v_lshl_add_u64 v[54:55], v[54:55], 0, v[172:173]
	global_store_dwordx4 v[54:55], v[50:53], off offset:-1792 sc1
	s_andn2_b64 vcc, exec, s[76:77]
	s_cbranch_vccz .LBB0_533

; __device__ __forceinline__ unsigned cvt_pk_bf16(float lo, float hi) { const f32x2_t v = {lo, hi}; return __builtin_bit_cast(unsigned, __builtin_convertvector(v, bf16x2_t)); }
; __device__ __forceinline__ float silu_f(float x) { return x * __builtin_amdgcn_rcpf(1.0f + __expf(-x)); }
;     __device__ __forceinline__ void operator()(const f32x4 (&acc)[2][2][4][2], const Unit& u, int wr, int wc, int fr, int fq) const {
;     ...
;             for (int m = 0; m < 4; ++m) { const int row = row0 + ai * HALF + m * 16;
;                 if (type == 0) { f32x4 p0, p1;
; #pragma unroll
;                     for (int j = 0; j < 4; ++j) { p0[j] = (acc[ai][0][m][0][j] * osc) * silu_f(acc[ai][1][m][0][j] * osc); p1[j] = (acc[ai][0][m][1][j] * osc) * silu_f(acc[ai][1][m][1][j] * osc); }
;                     u32x4 w; w.x = cvt_pk_bf16(p0[0], p0[1]); w.y = cvt_pk_bf16(p0[2], p0[3]); w.z = cvt_pk_bf16(p1[0], p1[1]); w.w = cvt_pk_bf16(p1[2], p1[3]);
;                     *(u32x4*)(P + (size_t)row * 5120 + pnl * HALF + lc) = w; }
.LBB0_541:
	s_waitcnt lgkmcnt(0)
	v_pk_mul_f32 v[52:53], v[134:135], v[38:39]
	v_pk_mul_f32 v[56:57], v[134:135], v[46:47]
	v_mul_f32_e32 v51, 0xbfb8aa3b, v52
	v_exp_f32_e32 v51, v51
	v_pk_mul_f32 v[58:59], v[134:135], v[42:43]
	v_pk_mul_f32 v[60:61], v[134:135], v[48:49]
	v_pk_mul_f32 v[62:63], v[134:135], v[44:45]
	v_add_f32_e32 v51, 1.0, v51
	v_rcp_f32_e32 v54, v51
	v_mul_f32_e32 v51, 0xbfb8aa3b, v53
	v_exp_f32_e32 v51, v51
	s_nop 0
	v_add_f32_e32 v51, 1.0, v51
	v_rcp_f32_e32 v55, v51
	s_nop 0
	v_pk_mul_f32 v[52:53], v[52:53], v[54:55]
	v_pk_mul_f32 v[54:55], v[134:135], v[34:35]
	v_pk_mul_f32 v[52:53], v[52:53], v[56:57]
	v_mul_f32_e32 v51, 0xbfb8aa3b, v54
	v_exp_f32_e32 v51, v51
	v_cvt_pk_bf16_f32 v52, v52, v53
	v_add_f32_e32 v51, 1.0, v51
	v_rcp_f32_e32 v56, v51
	v_mul_f32_e32 v51, 0xbfb8aa3b, v55
	v_exp_f32_e32 v51, v51
	s_nop 0
	v_add_f32_e32 v51, 1.0, v51
	v_rcp_f32_e32 v57, v51
	s_nop 0
	v_pk_mul_f32 v[54:55], v[54:55], v[56:57]
	v_pk_mul_f32 v[56:57], v[134:135], v[40:41]
	v_pk_mul_f32 v[54:55], v[54:55], v[58:59]
	v_mul_f32_e32 v51, 0xbfb8aa3b, v56
	v_exp_f32_e32 v51, v51
	v_cvt_pk_bf16_f32 v54, v54, v55
	v_add_f32_e32 v51, 1.0, v51
	v_rcp_f32_e32 v58, v51
	v_mul_f32_e32 v51, 0xbfb8aa3b, v57
	v_exp_f32_e32 v51, v51
	s_nop 0
	v_add_f32_e32 v51, 1.0, v51
	v_rcp_f32_e32 v59, v51
	s_nop 0
	v_pk_mul_f32 v[56:57], v[56:57], v[58:59]
	v_pk_mul_f32 v[58:59], v[134:135], v[36:37]
	v_pk_mul_f32 v[56:57], v[56:57], v[60:61]
	v_mul_f32_e32 v51, 0xbfb8aa3b, v58
	v_exp_f32_e32 v51, v51
	v_cvt_pk_bf16_f32 v53, v56, v57
	v_mov_b64_e32 v[56:57], s[14:15]
	v_mad_i64_i32 v[56:57], s[8:9], v50, s40, v[56:57]
	v_add_f32_e32 v51, 1.0, v51
	v_rcp_f32_e32 v60, v51
	v_mul_f32_e32 v51, 0xbfb8aa3b, v59
	v_exp_f32_e32 v51, v51
	v_lshl_add_u64 v[56:57], s[86:87], 1, v[56:57]
	v_lshl_add_u64 v[56:57], v[56:57], 0, v[172:173]
	s_mov_b64 s[8:9], 0
	v_add_f32_e32 v51, 1.0, v51
	v_rcp_f32_e32 v61, v51
	s_nop 0
	v_pk_mul_f32 v[58:59], v[58:59], v[60:61]
	s_nop 0
	v_pk_mul_f32 v[58:59], v[58:59], v[62:63]
	s_nop 0
	v_cvt_pk_bf16_f32 v55, v58, v59
	global_store_dwordx4 v[56:57], v[52:55], off sc1

; __device__ __forceinline__ unsigned cvt_pk_bf16(float lo, float hi) { const f32x2_t v = {lo, hi}; return __builtin_bit_cast(unsigned, __builtin_convertvector(v, bf16x2_t)); }
;     __device__ __forceinline__ void operator()(const f32x4 (&acc)[2][2][4][2], const Unit& u, int wr, int wc, int fr, int fq) const {
;     ...
;                         u32x4 w; w.x = cvt_pk_bf16(v0[0], v0[1]); w.y = cvt_pk_bf16(v0[2], v0[3]); w.z = cvt_pk_bf16(v1[0], v1[1]); w.w = cvt_pk_bf16(v1[2], v1[3]);
;                         if (type == 1) *(u32x4*)(P + (size_t)row * 5120 + 1024 + (pnl - 8) * BM + bj * HALF + lc) = w;
;                         else { const int cg = (pnl - (type == 3 ? 12 : 16)) * BM + bj * HALF + lc;
;                             *(u32x4*)((type == 3 ? XB : ZB) + ((size_t)(cg >> 4) * 8448 + row) * 16 + (cg & 8)) = w; } }
.LBB0_550:
	v_ashrrev_i32_e32 v51, 31, v50
	v_cvt_pk_bf16_f32 v42, v52, v53
	v_cvt_pk_bf16_f32 v43, v48, v49
	v_cvt_pk_bf16_f32 v44, v44, v45
	v_cvt_pk_bf16_f32 v45, v54, v55
	s_and_b64 vcc, exec, s[8:9]
	s_mov_b64 s[88:89], -1
	s_cbranch_vccnz .LBB0_552
	v_ashrrev_i32_e32 v48, 4, v144
	s_and_b64 s[44:45], s[78:79], exec
	v_mad_i64_i32 v[48:49], s[88:89], v48, s41, v[50:51]
	s_cselect_b32 s45, s29, s53
	s_cselect_b32 s44, s28, s52
	v_lshlrev_b64 v[48:49], 5, v[48:49]
	v_lshl_add_u64 v[48:49], s[44:45], 0, v[48:49]
	v_lshlrev_b32_e32 v52, 1, v174
	v_mov_b32_e32 v53, v173
	v_lshl_add_u64 v[48:49], v[48:49], 0, v[52:53]
	s_mov_b64 s[88:89], 0
	global_store_dwordx4 v[48:49], v[42:45], off sc1
.LBB0_552:
	v_mad_i64_i32 v[48:49], s[44:45], v50, s40, 0
	s_andn2_b64 vcc, exec, s[88:89]
	v_lshl_add_u64 v[48:49], s[14:15], 0, v[48:49]
	s_cbranch_vccnz .LBB0_554
	s_lshl_b32 s34, s67, 1
	v_lshl_add_u64 v[52:53], v[48:49], 0, s[34:35]
	v_lshl_add_u64 v[52:53], v[52:53], 0, v[172:173]
	global_store_dwordx4 v[52:53], v[42:45], off offset:-2048 sc1

; __device__ __forceinline__ unsigned cvt_pk_bf16(float lo, float hi) { const f32x2_t v = {lo, hi}; return __builtin_bit_cast(unsigned, __builtin_convertvector(v, bf16x2_t)); }
;     __device__ __forceinline__ void operator()(const f32x4 (&acc)[2][2][4][2], const Unit& u, int wr, int wc, int fr, int fq) const {
;     ...
;                         u32x4 w; w.x = cvt_pk_bf16(v0[0], v0[1]); w.y = cvt_pk_bf16(v0[2], v0[3]); w.z = cvt_pk_bf16(v1[0], v1[1]); w.w = cvt_pk_bf16(v1[2], v1[3]);
;                         if (type == 1) *(u32x4*)(P + (size_t)row * 5120 + 1024 + (pnl - 8) * BM + bj * HALF + lc) = w;
;                         else { const int cg = (pnl - (type == 3 ? 12 : 16)) * BM + bj * HALF + lc;
;                             *(u32x4*)((type == 3 ? XB : ZB) + ((size_t)(cg >> 4) * 8448 + row) * 16 + (cg & 8)) = w; } }
.LBB0_558:
	v_cvt_pk_bf16_f32 v34, v38, v39
	v_cvt_pk_bf16_f32 v35, v40, v41
	v_cvt_pk_bf16_f32 v36, v36, v37
	v_cvt_pk_bf16_f32 v37, v42, v43
	s_and_b64 vcc, exec, s[8:9]
	s_mov_b64 s[8:9], -1
	s_cbranch_vccnz .LBB0_566
	v_ashrrev_i32_e32 v38, 4, v144
	v_or_b32_e32 v38, 8, v38
	s_and_b64 s[8:9], s[78:79], exec
	v_mad_i64_i32 v[38:39], s[44:45], v38, s41, v[50:51]
	s_cselect_b32 s9, s29, s53
	s_cselect_b32 s8, s28, s52
	v_lshlrev_b64 v[38:39], 5, v[38:39]
	v_lshl_add_u64 v[38:39], s[8:9], 0, v[38:39]
	v_lshlrev_b32_e32 v40, 1, v174
	v_mov_b32_e32 v41, v173
	v_lshl_add_u64 v[38:39], v[38:39], 0, v[40:41]
	global_store_dwordx4 v[38:39], v[34:37], off sc1
	s_cbranch_execz .LBB0_567

; __device__ __forceinline__ unsigned cvt_pk_bf16(float lo, float hi) { const f32x2_t v = {lo, hi}; return __builtin_bit_cast(unsigned, __builtin_convertvector(v, bf16x2_t)); }
;     __device__ __forceinline__ void operator()(const f32x4 (&acc)[2][2][4][2], const Unit& u, int wr, int wc, int fr, int fq) const {
;     ...
;                         u32x4 w; w.x = cvt_pk_bf16(v0[0], v0[1]); w.y = cvt_pk_bf16(v0[2], v0[3]); w.z = cvt_pk_bf16(v1[0], v1[1]); w.w = cvt_pk_bf16(v1[2], v1[3]);
;                         if (type == 1) *(u32x4*)(P + (size_t)row * 5120 + 1024 + (pnl - 8) * BM + bj * HALF + lc) = w;
;                         else { const int cg = (pnl - (type == 3 ? 12 : 16)) * BM + bj * HALF + lc;
;                             *(u32x4*)((type == 3 ? XB : ZB) + ((size_t)(cg >> 4) * 8448 + row) * 16 + (cg & 8)) = w; } }
.LBB0_567:
	s_lshl_b32 s34, s67, 1
	v_lshl_add_u64 v[38:39], v[48:49], 0, s[34:35]
	v_lshl_add_u64 v[38:39], v[38:39], 0, v[172:173]
	global_store_dwordx4 v[38:39], v[34:37], off offset:-1792 sc1
	s_andn2_b64 vcc, exec, s[76:77]
	s_cbranch_vccz .LBB0_561

; __device__ __forceinline__ unsigned cvt_pk_bf16(float lo, float hi) { const f32x2_t v = {lo, hi}; return __builtin_bit_cast(unsigned, __builtin_convertvector(v, bf16x2_t)); }
; __device__ __forceinline__ float silu_f(float x) { return x * __builtin_amdgcn_rcpf(1.0f + __expf(-x)); }
;     __device__ __forceinline__ void operator()(const f32x4 (&acc)[2][2][4][2], const Unit& u, int wr, int wc, int fr, int fq) const {
;     ...
;             for (int m = 0; m < 4; ++m) { const int row = row0 + ai * HALF + m * 16;
;                 if (type == 0) { f32x4 p0, p1;
; #pragma unroll
;                     for (int j = 0; j < 4; ++j) { p0[j] = (acc[ai][0][m][0][j] * osc) * silu_f(acc[ai][1][m][0][j] * osc); p1[j] = (acc[ai][0][m][1][j] * osc) * silu_f(acc[ai][1][m][1][j] * osc); }
;                     u32x4 w; w.x = cvt_pk_bf16(p0[0], p0[1]); w.y = cvt_pk_bf16(p0[2], p0[3]); w.z = cvt_pk_bf16(p1[0], p1[1]); w.w = cvt_pk_bf16(p1[2], p1[3]);
;                     *(u32x4*)(P + (size_t)row * 5120 + pnl * HALF + lc) = w; }
.LBB0_569:
	s_waitcnt lgkmcnt(0)
	v_pk_mul_f32 v[36:37], v[134:135], v[22:23]
	v_pk_mul_f32 v[40:41], v[134:135], v[30:31]
	v_mul_f32_e32 v35, 0xbfb8aa3b, v36
	v_exp_f32_e32 v35, v35
	v_pk_mul_f32 v[42:43], v[134:135], v[26:27]
	v_pk_mul_f32 v[44:45], v[134:135], v[32:33]
	v_pk_mul_f32 v[46:47], v[134:135], v[28:29]
	v_add_f32_e32 v35, 1.0, v35
	v_rcp_f32_e32 v38, v35
	v_mul_f32_e32 v35, 0xbfb8aa3b, v37
	v_exp_f32_e32 v35, v35
	s_nop 0
	v_add_f32_e32 v35, 1.0, v35
	v_rcp_f32_e32 v39, v35
	s_nop 0
	v_pk_mul_f32 v[36:37], v[36:37], v[38:39]
	v_pk_mul_f32 v[38:39], v[134:135], v[18:19]
	v_pk_mul_f32 v[36:37], v[36:37], v[40:41]
	v_mul_f32_e32 v35, 0xbfb8aa3b, v38
	v_exp_f32_e32 v35, v35
	v_cvt_pk_bf16_f32 v36, v36, v37
	v_add_f32_e32 v35, 1.0, v35
	v_rcp_f32_e32 v40, v35
	v_mul_f32_e32 v35, 0xbfb8aa3b, v39
	v_exp_f32_e32 v35, v35
	s_nop 0
	v_add_f32_e32 v35, 1.0, v35
	v_rcp_f32_e32 v41, v35
	s_nop 0
	v_pk_mul_f32 v[38:39], v[38:39], v[40:41]
	v_pk_mul_f32 v[40:41], v[134:135], v[24:25]
	v_pk_mul_f32 v[38:39], v[38:39], v[42:43]
	v_mul_f32_e32 v35, 0xbfb8aa3b, v40
	v_exp_f32_e32 v35, v35
	v_cvt_pk_bf16_f32 v38, v38, v39
	v_add_f32_e32 v35, 1.0, v35
	v_rcp_f32_e32 v42, v35
	v_mul_f32_e32 v35, 0xbfb8aa3b, v41
	v_exp_f32_e32 v35, v35
	s_nop 0
	v_add_f32_e32 v35, 1.0, v35
	v_rcp_f32_e32 v43, v35
	s_nop 0
	v_pk_mul_f32 v[40:41], v[40:41], v[42:43]
	v_pk_mul_f32 v[42:43], v[134:135], v[20:21]
	v_pk_mul_f32 v[40:41], v[40:41], v[44:45]
	v_mul_f32_e32 v35, 0xbfb8aa3b, v42
	v_exp_f32_e32 v35, v35
	v_cvt_pk_bf16_f32 v37, v40, v41
	v_mov_b64_e32 v[40:41], s[14:15]
	v_mad_i64_i32 v[40:41], s[8:9], v34, s40, v[40:41]
	v_add_f32_e32 v35, 1.0, v35
	v_rcp_f32_e32 v44, v35
	v_mul_f32_e32 v35, 0xbfb8aa3b, v43
	v_exp_f32_e32 v35, v35
	v_lshl_add_u64 v[40:41], s[86:87], 1, v[40:41]
	v_lshl_add_u64 v[40:41], v[40:41], 0, v[172:173]
	s_mov_b64 s[8:9], 0
	v_add_f32_e32 v35, 1.0, v35
	v_rcp_f32_e32 v45, v35
	s_nop 0
	v_pk_mul_f32 v[42:43], v[42:43], v[44:45]
	s_nop 0
	v_pk_mul_f32 v[42:43], v[42:43], v[46:47]
	s_nop 0
	v_cvt_pk_bf16_f32 v39, v42, v43
	global_store_dwordx4 v[40:41], v[36:39], off sc1

; __device__ __forceinline__ unsigned cvt_pk_bf16(float lo, float hi) { const f32x2_t v = {lo, hi}; return __builtin_bit_cast(unsigned, __builtin_convertvector(v, bf16x2_t)); }
;     __device__ __forceinline__ void operator()(const f32x4 (&acc)[2][2][4][2], const Unit& u, int wr, int wc, int fr, int fq) const {
;     ...
;                         u32x4 w; w.x = cvt_pk_bf16(v0[0], v0[1]); w.y = cvt_pk_bf16(v0[2], v0[3]); w.z = cvt_pk_bf16(v1[0], v1[1]); w.w = cvt_pk_bf16(v1[2], v1[3]);
;                         if (type == 1) *(u32x4*)(P + (size_t)row * 5120 + 1024 + (pnl - 8) * BM + bj * HALF + lc) = w;
;                         else { const int cg = (pnl - (type == 3 ? 12 : 16)) * BM + bj * HALF + lc;
;                             *(u32x4*)((type == 3 ? XB : ZB) + ((size_t)(cg >> 4) * 8448 + row) * 16 + (cg & 8)) = w; } }
.LBB0_578:
	v_ashrrev_i32_e32 v35, 31, v34
	v_cvt_pk_bf16_f32 v26, v36, v37
	v_cvt_pk_bf16_f32 v27, v32, v33
	v_cvt_pk_bf16_f32 v28, v28, v29
	v_cvt_pk_bf16_f32 v29, v38, v39
	s_and_b64 vcc, exec, s[8:9]
	s_mov_b64 s[88:89], -1
	s_cbranch_vccnz .LBB0_580
	v_ashrrev_i32_e32 v32, 4, v144
	s_and_b64 s[44:45], s[78:79], exec
	v_mad_i64_i32 v[32:33], s[88:89], v32, s41, v[34:35]
	s_cselect_b32 s45, s29, s53
	s_cselect_b32 s44, s28, s52
	v_lshlrev_b64 v[32:33], 5, v[32:33]
	v_lshl_add_u64 v[32:33], s[44:45], 0, v[32:33]
	v_lshlrev_b32_e32 v36, 1, v174
	v_mov_b32_e32 v37, v173
	v_lshl_add_u64 v[32:33], v[32:33], 0, v[36:37]
	s_mov_b64 s[88:89], 0
	global_store_dwordx4 v[32:33], v[26:29], off sc1
.LBB0_580:
	v_mad_i64_i32 v[32:33], s[44:45], v34, s40, 0
	s_andn2_b64 vcc, exec, s[88:89]
	v_lshl_add_u64 v[32:33], s[14:15], 0, v[32:33]
	s_cbranch_vccnz .LBB0_582
	s_lshl_b32 s34, s67, 1
	v_lshl_add_u64 v[36:37], v[32:33], 0, s[34:35]
	v_lshl_add_u64 v[36:37], v[36:37], 0, v[172:173]
	global_store_dwordx4 v[36:37], v[26:29], off offset:-2048 sc1

; __device__ __forceinline__ unsigned cvt_pk_bf16(float lo, float hi) { const f32x2_t v = {lo, hi}; return __builtin_bit_cast(unsigned, __builtin_convertvector(v, bf16x2_t)); }
;     __device__ __forceinline__ void operator()(const f32x4 (&acc)[2][2][4][2], const Unit& u, int wr, int wc, int fr, int fq) const {
;     ...
;                         u32x4 w; w.x = cvt_pk_bf16(v0[0], v0[1]); w.y = cvt_pk_bf16(v0[2], v0[3]); w.z = cvt_pk_bf16(v1[0], v1[1]); w.w = cvt_pk_bf16(v1[2], v1[3]);
;                         if (type == 1) *(u32x4*)(P + (size_t)row * 5120 + 1024 + (pnl - 8) * BM + bj * HALF + lc) = w;
;                         else { const int cg = (pnl - (type == 3 ? 12 : 16)) * BM + bj * HALF + lc;
;                             *(u32x4*)((type == 3 ? XB : ZB) + ((size_t)(cg >> 4) * 8448 + row) * 16 + (cg & 8)) = w; } }
.LBB0_586:
	v_cvt_pk_bf16_f32 v18, v22, v23
	v_cvt_pk_bf16_f32 v19, v24, v25
	v_cvt_pk_bf16_f32 v20, v20, v21
	v_cvt_pk_bf16_f32 v21, v26, v27
	s_and_b64 vcc, exec, s[8:9]
	s_mov_b64 s[8:9], -1
	s_cbranch_vccnz .LBB0_594
	v_ashrrev_i32_e32 v22, 4, v144
	v_or_b32_e32 v22, 8, v22
	s_and_b64 s[8:9], s[78:79], exec
	v_mad_i64_i32 v[22:23], s[44:45], v22, s41, v[34:35]
	s_cselect_b32 s9, s29, s53
	s_cselect_b32 s8, s28, s52
	v_lshlrev_b64 v[22:23], 5, v[22:23]
	v_lshl_add_u64 v[22:23], s[8:9], 0, v[22:23]
	v_lshlrev_b32_e32 v24, 1, v174
	v_mov_b32_e32 v25, v173
	v_lshl_add_u64 v[22:23], v[22:23], 0, v[24:25]
	global_store_dwordx4 v[22:23], v[18:21], off sc1
	s_cbranch_execz .LBB0_595

; __device__ __forceinline__ unsigned cvt_pk_bf16(float lo, float hi) { const f32x2_t v = {lo, hi}; return __builtin_bit_cast(unsigned, __builtin_convertvector(v, bf16x2_t)); }
;     __device__ __forceinline__ void operator()(const f32x4 (&acc)[2][2][4][2], const Unit& u, int wr, int wc, int fr, int fq) const {
;     ...
;                         u32x4 w; w.x = cvt_pk_bf16(v0[0], v0[1]); w.y = cvt_pk_bf16(v0[2], v0[3]); w.z = cvt_pk_bf16(v1[0], v1[1]); w.w = cvt_pk_bf16(v1[2], v1[3]);
;                         if (type == 1) *(u32x4*)(P + (size_t)row * 5120 + 1024 + (pnl - 8) * BM + bj * HALF + lc) = w;
;                         else { const int cg = (pnl - (type == 3 ? 12 : 16)) * BM + bj * HALF + lc;
;                             *(u32x4*)((type == 3 ? XB : ZB) + ((size_t)(cg >> 4) * 8448 + row) * 16 + (cg & 8)) = w; } }
.LBB0_595:
	s_lshl_b32 s34, s67, 1
	v_lshl_add_u64 v[22:23], v[32:33], 0, s[34:35]
	v_lshl_add_u64 v[22:23], v[22:23], 0, v[172:173]
	global_store_dwordx4 v[22:23], v[18:21], off offset:-1792 sc1
	s_andn2_b64 vcc, exec, s[76:77]
	s_cbranch_vccz .LBB0_589

; __device__ __forceinline__ unsigned cvt_pk_bf16(float lo, float hi) { const f32x2_t v = {lo, hi}; return __builtin_bit_cast(unsigned, __builtin_convertvector(v, bf16x2_t)); }
; __device__ __forceinline__ float silu_f(float x) { return x * __builtin_amdgcn_rcpf(1.0f + __expf(-x)); }
;     __device__ __forceinline__ void operator()(const f32x4 (&acc)[2][2][4][2], const Unit& u, int wr, int wc, int fr, int fq) const {
;     ...
;             for (int m = 0; m < 4; ++m) { const int row = row0 + ai * HALF + m * 16;
;                 if (type == 0) { f32x4 p0, p1;
; #pragma unroll
;                     for (int j = 0; j < 4; ++j) { p0[j] = (acc[ai][0][m][0][j] * osc) * silu_f(acc[ai][1][m][0][j] * osc); p1[j] = (acc[ai][0][m][1][j] * osc) * silu_f(acc[ai][1][m][1][j] * osc); }
;                     u32x4 w; w.x = cvt_pk_bf16(p0[0], p0[1]); w.y = cvt_pk_bf16(p0[2], p0[3]); w.z = cvt_pk_bf16(p1[0], p1[1]); w.w = cvt_pk_bf16(p1[2], p1[3]);
;                     *(u32x4*)(P + (size_t)row * 5120 + pnl * HALF + lc) = w; }
.LBB0_597:
	s_waitcnt lgkmcnt(0)
	v_pk_mul_f32 v[20:21], v[134:135], v[6:7]
	v_pk_mul_f32 v[24:25], v[134:135], v[14:15]
	v_mul_f32_e32 v19, 0xbfb8aa3b, v20
	v_exp_f32_e32 v19, v19
	v_pk_mul_f32 v[26:27], v[134:135], v[10:11]
	v_pk_mul_f32 v[28:29], v[134:135], v[16:17]
	v_pk_mul_f32 v[30:31], v[134:135], v[12:13]
	v_add_f32_e32 v19, 1.0, v19
	v_rcp_f32_e32 v22, v19
	v_mul_f32_e32 v19, 0xbfb8aa3b, v21
	v_exp_f32_e32 v19, v19
	s_nop 0
	v_add_f32_e32 v19, 1.0, v19
	v_rcp_f32_e32 v23, v19
	s_nop 0
	v_pk_mul_f32 v[20:21], v[20:21], v[22:23]
	v_pk_mul_f32 v[22:23], v[134:135], v[2:3]
	v_pk_mul_f32 v[20:21], v[20:21], v[24:25]
	v_mul_f32_e32 v19, 0xbfb8aa3b, v22
	v_exp_f32_e32 v19, v19
	v_cvt_pk_bf16_f32 v20, v20, v21
	v_add_f32_e32 v19, 1.0, v19
	v_rcp_f32_e32 v24, v19
	v_mul_f32_e32 v19, 0xbfb8aa3b, v23
	v_exp_f32_e32 v19, v19
	s_nop 0
	v_add_f32_e32 v19, 1.0, v19
	v_rcp_f32_e32 v25, v19
	s_nop 0
	v_pk_mul_f32 v[22:23], v[22:23], v[24:25]
	v_pk_mul_f32 v[24:25], v[134:135], v[8:9]
	v_pk_mul_f32 v[22:23], v[22:23], v[26:27]
	v_mul_f32_e32 v19, 0xbfb8aa3b, v24
	v_exp_f32_e32 v19, v19
	v_cvt_pk_bf16_f32 v22, v22, v23
	v_add_f32_e32 v19, 1.0, v19
	v_rcp_f32_e32 v26, v19
	v_mul_f32_e32 v19, 0xbfb8aa3b, v25
	v_exp_f32_e32 v19, v19
	s_nop 0
	v_add_f32_e32 v19, 1.0, v19
	v_rcp_f32_e32 v27, v19
	s_nop 0
	v_pk_mul_f32 v[24:25], v[24:25], v[26:27]
	v_pk_mul_f32 v[26:27], v[134:135], v[4:5]
	v_pk_mul_f32 v[24:25], v[24:25], v[28:29]
	v_mul_f32_e32 v19, 0xbfb8aa3b, v26
	v_exp_f32_e32 v19, v19
	v_cvt_pk_bf16_f32 v21, v24, v25
	v_mov_b64_e32 v[24:25], s[14:15]
	v_mad_i64_i32 v[24:25], s[6:7], v18, s40, v[24:25]
	v_add_f32_e32 v19, 1.0, v19
	v_rcp_f32_e32 v28, v19
	v_mul_f32_e32 v19, 0xbfb8aa3b, v27
	v_exp_f32_e32 v19, v19
	v_lshl_add_u64 v[24:25], s[86:87], 1, v[24:25]
	v_lshl_add_u64 v[24:25], v[24:25], 0, v[172:173]
	s_mov_b64 s[6:7], 0
	v_add_f32_e32 v19, 1.0, v19
	v_rcp_f32_e32 v29, v19
	s_nop 0
	v_pk_mul_f32 v[26:27], v[26:27], v[28:29]
	s_nop 0
	v_pk_mul_f32 v[26:27], v[26:27], v[30:31]
	s_nop 0
	v_cvt_pk_bf16_f32 v23, v26, v27
	global_store_dwordx4 v[24:25], v[20:23], off sc1

; __device__ __forceinline__ unsigned cvt_pk_bf16(float lo, float hi) { const f32x2_t v = {lo, hi}; return __builtin_bit_cast(unsigned, __builtin_convertvector(v, bf16x2_t)); }
;     __device__ __forceinline__ void operator()(const f32x4 (&acc)[2][2][4][2], const Unit& u, int wr, int wc, int fr, int fq) const {
;     ...
;                         u32x4 w; w.x = cvt_pk_bf16(v0[0], v0[1]); w.y = cvt_pk_bf16(v0[2], v0[3]); w.z = cvt_pk_bf16(v1[0], v1[1]); w.w = cvt_pk_bf16(v1[2], v1[3]);
;                         if (type == 1) *(u32x4*)(P + (size_t)row * 5120 + 1024 + (pnl - 8) * BM + bj * HALF + lc) = w;
;                         else { const int cg = (pnl - (type == 3 ? 12 : 16)) * BM + bj * HALF + lc;
;                             *(u32x4*)((type == 3 ? XB : ZB) + ((size_t)(cg >> 4) * 8448 + row) * 16 + (cg & 8)) = w; } }
.LBB0_606:
	v_ashrrev_i32_e32 v19, 31, v18
	v_cvt_pk_bf16_f32 v10, v20, v21
	v_cvt_pk_bf16_f32 v11, v16, v17
	v_cvt_pk_bf16_f32 v12, v12, v13
	v_cvt_pk_bf16_f32 v13, v22, v23
	s_mov_b64 s[8:9], -1
	s_and_b64 vcc, exec, s[6:7]
	v_ashrrev_i32_e32 v20, 4, v144
	s_cbranch_vccnz .LBB0_608
	s_and_b64 s[8:9], s[78:79], exec
	v_mad_i64_i32 v[16:17], s[44:45], v20, s41, v[18:19]
	s_cselect_b32 s9, s29, s53
	s_cselect_b32 s8, s28, s52
	v_lshlrev_b64 v[16:17], 5, v[16:17]
	v_lshl_add_u64 v[16:17], s[8:9], 0, v[16:17]
	v_lshlrev_b32_e32 v22, 1, v174
	v_mov_b32_e32 v23, v173
	v_lshl_add_u64 v[16:17], v[16:17], 0, v[22:23]
	s_mov_b64 s[8:9], 0
	global_store_dwordx4 v[16:17], v[10:13], off sc1
.LBB0_608:
	v_mad_i64_i32 v[16:17], s[44:45], v18, s40, 0
	s_andn2_b64 vcc, exec, s[8:9]
	v_lshl_add_u64 v[16:17], s[14:15], 0, v[16:17]
	s_cbranch_vccnz .LBB0_610
	s_lshl_b32 s34, s67, 1
	v_lshl_add_u64 v[22:23], v[16:17], 0, s[34:35]
	v_lshl_add_u64 v[22:23], v[22:23], 0, v[172:173]
	global_store_dwordx4 v[22:23], v[10:13], off offset:-2048 sc1

; __device__ __forceinline__ unsigned cvt_pk_bf16(float lo, float hi) { const f32x2_t v = {lo, hi}; return __builtin_bit_cast(unsigned, __builtin_convertvector(v, bf16x2_t)); }
;     __device__ __forceinline__ void operator()(const f32x4 (&acc)[2][2][4][2], const Unit& u, int wr, int wc, int fr, int fq) const {
;     ...
;                         u32x4 w; w.x = cvt_pk_bf16(v0[0], v0[1]); w.y = cvt_pk_bf16(v0[2], v0[3]); w.z = cvt_pk_bf16(v1[0], v1[1]); w.w = cvt_pk_bf16(v1[2], v1[3]);
;                         if (type == 1) *(u32x4*)(P + (size_t)row * 5120 + 1024 + (pnl - 8) * BM + bj * HALF + lc) = w;
;                         else { const int cg = (pnl - (type == 3 ? 12 : 16)) * BM + bj * HALF + lc;
;                             *(u32x4*)((type == 3 ? XB : ZB) + ((size_t)(cg >> 4) * 8448 + row) * 16 + (cg & 8)) = w; } }
.LBB0_614:
	v_cvt_pk_bf16_f32 v2, v6, v7
	v_cvt_pk_bf16_f32 v3, v8, v9
	v_cvt_pk_bf16_f32 v4, v4, v5
	v_cvt_pk_bf16_f32 v5, v10, v11
	s_and_b64 vcc, exec, s[6:7]
	s_mov_b64 s[4:5], -1
	s_cbranch_vccnz .LBB0_622
	v_or_b32_e32 v6, 8, v20
	s_and_b64 s[4:5], s[78:79], exec
	v_mad_i64_i32 v[6:7], s[6:7], v6, s41, v[18:19]
	s_cselect_b32 s5, s29, s53
	s_cselect_b32 s4, s28, s52
	v_lshlrev_b64 v[6:7], 5, v[6:7]
	v_lshl_add_u64 v[6:7], s[4:5], 0, v[6:7]
	v_lshlrev_b32_e32 v8, 1, v174
	v_mov_b32_e32 v9, v173
	v_lshl_add_u64 v[6:7], v[6:7], 0, v[8:9]
	global_store_dwordx4 v[6:7], v[2:5], off sc1
	s_cbranch_execz .LBB0_623

; __device__ __forceinline__ unsigned cvt_pk_bf16(float lo, float hi) { const f32x2_t v = {lo, hi}; return __builtin_bit_cast(unsigned, __builtin_convertvector(v, bf16x2_t)); }
;     __device__ __forceinline__ void operator()(const f32x4 (&acc)[2][2][4][2], const Unit& u, int wr, int wc, int fr, int fq) const {
;     ...
;                         u32x4 w; w.x = cvt_pk_bf16(v0[0], v0[1]); w.y = cvt_pk_bf16(v0[2], v0[3]); w.z = cvt_pk_bf16(v1[0], v1[1]); w.w = cvt_pk_bf16(v1[2], v1[3]);
;                         if (type == 1) *(u32x4*)(P + (size_t)row * 5120 + 1024 + (pnl - 8) * BM + bj * HALF + lc) = w;
;                         else { const int cg = (pnl - (type == 3 ? 12 : 16)) * BM + bj * HALF + lc;
;                             *(u32x4*)((type == 3 ? XB : ZB) + ((size_t)(cg >> 4) * 8448 + row) * 16 + (cg & 8)) = w; } }
.LBB0_623:
	s_lshl_b32 s34, s67, 1
	v_lshl_add_u64 v[6:7], v[16:17], 0, s[34:35]
	v_lshl_add_u64 v[6:7], v[6:7], 0, v[172:173]
	global_store_dwordx4 v[6:7], v[2:5], off offset:-1792 sc1
	s_andn2_b64 vcc, exec, s[76:77]
	s_cbranch_vccz .LBB0_617

; __device__ __forceinline__ unsigned cvt_pk_bf16(float lo, float hi) { const f32x2_t v = {lo, hi}; return __builtin_bit_cast(unsigned, __builtin_convertvector(v, bf16x2_t)); }
; __device__ __forceinline__ float silu_f(float x) { return x * __builtin_amdgcn_rcpf(1.0f + __expf(-x)); }
;     __device__ __forceinline__ void operator()(const f32x4 (&acc)[2][2][4][2], const Unit& u, int wr, int wc, int fr, int fq) const {
;         const int row0 = u.pm * BM + wr * 64 + fr, lc = wc * 32 + 8 * fq;
;         const int pnl = (f8tiles && u.pn >= 12) ? u.pn + 4 : u.pn;
;         const int type = (pnl < 8) ? 0 : (pnl < 12) ? 1 : (pnl < 16) ? 3 : 4;
; #pragma unroll
;         for (int ai = 0; ai < 2; ++ai)
; #pragma unroll
;             for (int m = 0; m < 4; ++m) { const int row = row0 + ai * HALF + m * 16;
;                 if (type == 0) { f32x4 p0, p1;
; #pragma unroll
;                     for (int j = 0; j < 4; ++j) { p0[j] = (acc[ai][0][m][0][j] * osc) * silu_f(acc[ai][1][m][0][j] * osc); p1[j] = (acc[ai][0][m][1][j] * osc) * silu_f(acc[ai][1][m][1][j] * osc); }
;                     u32x4 w; w.x = cvt_pk_bf16(p0[0], p0[1]); w.y = cvt_pk_bf16(p0[2], p0[3]); w.z = cvt_pk_bf16(p1[0], p1[1]); w.w = cvt_pk_bf16(p1[2], p1[3]);
;                     *(u32x4*)(P + (size_t)row * 5120 + pnl * HALF + lc) = w; }
.LBB0_665:
	v_lshl_add_u32 v6, s2, 8, v209
	s_add_i32 s2, s44, 4
	s_cmp_gt_i32 s44, 11
	s_cselect_b32 s2, s2, s44
	s_cmp_lt_i32 s2, 8
	s_cselect_b64 s[8:9], -1, 0
	s_cmp_lt_u32 s2, 16
	s_cselect_b32 s6, 3, 4
	s_cmp_lt_u32 s2, 12
	s_cselect_b64 s[76:77], -1, 0
	s_and_b64 s[4:5], s[76:77], exec
	s_cselect_b32 s6, 1, s6
	s_cmp_gt_i32 s2, 7
	s_cselect_b64 s[4:5], -1, 0
	s_and_b64 vcc, s[4:5], exec
	s_cselect_b32 s6, s6, 0
	s_lshl_b32 s86, s2, 7
	s_ashr_i32 s87, s86, 31
	s_cmp_eq_u32 s6, 4
	s_cselect_b64 s[4:5], -1, 0
	s_and_b32 s7, s2, 0x7ffffffc
	s_cmp_lg_u32 s7, 8
	s_cselect_b64 s[84:85], -1, 0
	s_cmp_eq_u32 s6, 3
	s_cselect_b64 s[78:79], -1, 0
	s_and_b64 s[6:7], s[78:79], exec
	s_cselect_b32 s33, -12, -16
	s_mov_b64 s[6:7], -1
	v_lshlrev_b32_e32 v172, 1, v186
	s_cbranch_vccnz .LBB0_667
	v_pk_mul_f32 v[2:3], v[190:191], v[150:151]
	v_pk_mul_f32 v[8:9], v[190:191], v[158:159]
	v_mul_f32_e32 v4, 0xbfb8aa3b, v2
	v_mul_f32_e32 v5, 0xbfb8aa3b, v3
	v_exp_f32_e32 v4, v4
	v_exp_f32_e32 v5, v5
	v_pk_mul_f32 v[10:11], v[190:191], v[154:155]
	v_pk_mul_f32 v[12:13], v[190:191], v[160:161]
	v_add_f32_e32 v4, 1.0, v4
	v_add_f32_e32 v5, 1.0, v5
	v_rcp_f32_e32 v4, v4
	v_rcp_f32_e32 v5, v5
	v_pk_mul_f32 v[14:15], v[190:191], v[156:157]
	v_pk_mul_f32 v[2:3], v[2:3], v[4:5]
	v_pk_mul_f32 v[4:5], v[190:191], v[146:147]
	v_pk_mul_f32 v[2:3], v[2:3], v[8:9]
	v_mul_f32_e32 v7, 0xbfb8aa3b, v4
	v_exp_f32_e32 v7, v7
	v_cvt_pk_bf16_f32 v2, v2, v3
	v_add_f32_e32 v7, 1.0, v7
	v_rcp_f32_e32 v8, v7
	v_mul_f32_e32 v7, 0xbfb8aa3b, v5
	v_exp_f32_e32 v7, v7
	s_nop 0
	v_add_f32_e32 v7, 1.0, v7
	v_rcp_f32_e32 v9, v7
	s_nop 0
	v_pk_mul_f32 v[4:5], v[4:5], v[8:9]
	v_pk_mul_f32 v[8:9], v[190:191], v[152:153]
	v_pk_mul_f32 v[4:5], v[4:5], v[10:11]
	v_mul_f32_e32 v7, 0xbfb8aa3b, v8
	v_exp_f32_e32 v7, v7
	v_cvt_pk_bf16_f32 v4, v4, v5
	v_add_f32_e32 v7, 1.0, v7
	v_rcp_f32_e32 v10, v7
	v_mul_f32_e32 v7, 0xbfb8aa3b, v9
	v_exp_f32_e32 v7, v7
	s_nop 0
	v_add_f32_e32 v7, 1.0, v7
	v_rcp_f32_e32 v11, v7
	s_nop 0
	v_pk_mul_f32 v[8:9], v[8:9], v[10:11]
	v_pk_mul_f32 v[10:11], v[190:191], v[148:149]
	v_pk_mul_f32 v[8:9], v[8:9], v[12:13]
	v_mul_f32_e32 v7, 0xbfb8aa3b, v10
	v_exp_f32_e32 v7, v7
	v_cvt_pk_bf16_f32 v3, v8, v9
	v_mov_b64_e32 v[8:9], s[14:15]
	v_mad_i64_i32 v[8:9], s[6:7], v6, s40, v[8:9]
	v_add_f32_e32 v7, 1.0, v7
	v_rcp_f32_e32 v12, v7
	v_mul_f32_e32 v7, 0xbfb8aa3b, v11
	v_exp_f32_e32 v7, v7
	v_lshl_add_u64 v[8:9], s[86:87], 1, v[8:9]
	v_lshl_add_u64 v[8:9], v[8:9], 0, v[172:173]
	s_mov_b64 s[6:7], 0
	v_add_f32_e32 v7, 1.0, v7
	v_rcp_f32_e32 v13, v7
	s_nop 0
	v_pk_mul_f32 v[10:11], v[10:11], v[12:13]
	s_nop 0
	v_pk_mul_f32 v[10:11], v[10:11], v[14:15]
	s_nop 0
	v_cvt_pk_bf16_f32 v5, v10, v11
	global_store_dwordx4 v[8:9], v[2:5], off sc1

; __device__ __forceinline__ unsigned cvt_pk_bf16(float lo, float hi) { const f32x2_t v = {lo, hi}; return __builtin_bit_cast(unsigned, __builtin_convertvector(v, bf16x2_t)); }
;     __device__ __forceinline__ void operator()(const f32x4 (&acc)[2][2][4][2], const Unit& u, int wr, int wc, int fr, int fq) const {
;     ...
;                         u32x4 w; w.x = cvt_pk_bf16(v0[0], v0[1]); w.y = cvt_pk_bf16(v0[2], v0[3]); w.z = cvt_pk_bf16(v1[0], v1[1]); w.w = cvt_pk_bf16(v1[2], v1[3]);
;                         if (type == 1) *(u32x4*)(P + (size_t)row * 5120 + 1024 + (pnl - 8) * BM + bj * HALF + lc) = w;
;                         else { const int cg = (pnl - (type == 3 ? 12 : 16)) * BM + bj * HALF + lc;
;                             *(u32x4*)((type == 3 ? XB : ZB) + ((size_t)(cg >> 4) * 8448 + row) * 16 + (cg & 8)) = w; } }
.LBB0_675:
	v_ashrrev_i32_e32 v7, 31, v6
	v_cvt_pk_bf16_f32 v2, v2, v3
	v_cvt_pk_bf16_f32 v3, v4, v5
	v_cvt_pk_bf16_f32 v4, v12, v13
	v_cvt_pk_bf16_f32 v5, v10, v11
	s_mov_b64 s[88:89], -1
	s_and_b64 vcc, exec, s[84:85]
	s_cbranch_vccz .LBB0_677
	v_ashrrev_i32_e32 v10, 4, v18
	s_and_b64 s[44:45], s[78:79], exec
	v_mad_i64_i32 v[10:11], s[88:89], v10, s41, v[6:7]
	s_cselect_b32 s45, s29, s53
	s_cselect_b32 s44, s28, s52
	v_lshlrev_b64 v[10:11], 5, v[10:11]
	v_lshl_add_u64 v[10:11], s[44:45], 0, v[10:11]
	v_lshlrev_b32_e32 v12, 1, v174
	v_mov_b32_e32 v13, v173
	v_lshl_add_u64 v[10:11], v[10:11], 0, v[12:13]
	global_store_dwordx4 v[10:11], v[2:5], off sc1
	s_mov_b64 s[88:89], 0
.LBB0_677:
	v_mad_i64_i32 v[10:11], s[44:45], v6, s40, 0
	s_andn2_b64 vcc, exec, s[88:89]
	v_lshl_add_u64 v[10:11], s[14:15], 0, v[10:11]
	s_cbranch_vccnz .LBB0_679
	s_lshl_b32 s34, s67, 1
	v_lshl_add_u64 v[12:13], v[10:11], 0, s[34:35]
	v_lshl_add_u64 v[12:13], v[12:13], 0, v[172:173]
	global_store_dwordx4 v[12:13], v[2:5], off offset:-2048 sc1

; __device__ __forceinline__ unsigned cvt_pk_bf16(float lo, float hi) { const f32x2_t v = {lo, hi}; return __builtin_bit_cast(unsigned, __builtin_convertvector(v, bf16x2_t)); }
;     __device__ __forceinline__ void operator()(const f32x4 (&acc)[2][2][4][2], const Unit& u, int wr, int wc, int fr, int fq) const {
;     ...
;                         u32x4 w; w.x = cvt_pk_bf16(v0[0], v0[1]); w.y = cvt_pk_bf16(v0[2], v0[3]); w.z = cvt_pk_bf16(v1[0], v1[1]); w.w = cvt_pk_bf16(v1[2], v1[3]);
;                         if (type == 1) *(u32x4*)(P + (size_t)row * 5120 + 1024 + (pnl - 8) * BM + bj * HALF + lc) = w;
;                         else { const int cg = (pnl - (type == 3 ? 12 : 16)) * BM + bj * HALF + lc;
;                             *(u32x4*)((type == 3 ? XB : ZB) + ((size_t)(cg >> 4) * 8448 + row) * 16 + (cg & 8)) = w; } }
.LBB0_683:
	v_cvt_pk_bf16_f32 v2, v2, v3
	v_cvt_pk_bf16_f32 v3, v4, v5
	v_cvt_pk_bf16_f32 v4, v14, v15
	v_cvt_pk_bf16_f32 v5, v12, v13
	s_and_b64 vcc, exec, s[6:7]
	s_mov_b64 s[6:7], -1
	s_cbranch_vccnz .LBB0_688
	v_ashrrev_i32_e32 v12, 4, v18
	v_or_b32_e32 v12, 8, v12
	s_and_b64 s[6:7], s[78:79], exec
	v_mad_i64_i32 v[12:13], s[44:45], v12, s41, v[6:7]
	s_cselect_b32 s7, s29, s53
	s_cselect_b32 s6, s28, s52
	v_lshlrev_b64 v[12:13], 5, v[12:13]
	v_lshl_add_u64 v[12:13], s[6:7], 0, v[12:13]
	v_lshlrev_b32_e32 v14, 1, v174
	v_mov_b32_e32 v15, v173
	v_lshl_add_u64 v[12:13], v[12:13], 0, v[14:15]
	global_store_dwordx4 v[12:13], v[2:5], off sc1
	s_cbranch_execz .LBB0_689

; __device__ __forceinline__ unsigned cvt_pk_bf16(float lo, float hi) { const f32x2_t v = {lo, hi}; return __builtin_bit_cast(unsigned, __builtin_convertvector(v, bf16x2_t)); }
;     __device__ __forceinline__ void operator()(const f32x4 (&acc)[2][2][4][2], const Unit& u, int wr, int wc, int fr, int fq) const {
;     ...
;                         u32x4 w; w.x = cvt_pk_bf16(v0[0], v0[1]); w.y = cvt_pk_bf16(v0[2], v0[3]); w.z = cvt_pk_bf16(v1[0], v1[1]); w.w = cvt_pk_bf16(v1[2], v1[3]);
;                         if (type == 1) *(u32x4*)(P + (size_t)row * 5120 + 1024 + (pnl - 8) * BM + bj * HALF + lc) = w;
;                         else { const int cg = (pnl - (type == 3 ? 12 : 16)) * BM + bj * HALF + lc;
;                             *(u32x4*)((type == 3 ? XB : ZB) + ((size_t)(cg >> 4) * 8448 + row) * 16 + (cg & 8)) = w; } }
.LBB0_689:
	s_lshl_b32 s34, s67, 1
	v_lshl_add_u64 v[10:11], v[10:11], 0, s[34:35]
	v_lshl_add_u64 v[10:11], v[10:11], 0, v[172:173]
	global_store_dwordx4 v[10:11], v[2:5], off offset:-1792 sc1
	s_andn2_b64 vcc, exec, s[76:77]
	s_cbranch_vccnz .LBB0_693

; __device__ __forceinline__ unsigned cvt_pk_bf16(float lo, float hi) { const f32x2_t v = {lo, hi}; return __builtin_bit_cast(unsigned, __builtin_convertvector(v, bf16x2_t)); }
; __device__ __forceinline__ float silu_f(float x) { return x * __builtin_amdgcn_rcpf(1.0f + __expf(-x)); }
;     __device__ __forceinline__ void operator()(const f32x4 (&acc)[2][2][4][2], const Unit& u, int wr, int wc, int fr, int fq) const {
;     ...
;             for (int m = 0; m < 4; ++m) { const int row = row0 + ai * HALF + m * 16;
;                 if (type == 0) { f32x4 p0, p1;
; #pragma unroll
;                     for (int j = 0; j < 4; ++j) { p0[j] = (acc[ai][0][m][0][j] * osc) * silu_f(acc[ai][1][m][0][j] * osc); p1[j] = (acc[ai][0][m][1][j] * osc) * silu_f(acc[ai][1][m][1][j] * osc); }
;                     u32x4 w; w.x = cvt_pk_bf16(p0[0], p0[1]); w.y = cvt_pk_bf16(p0[2], p0[3]); w.z = cvt_pk_bf16(p1[0], p1[1]); w.w = cvt_pk_bf16(p1[2], p1[3]);
;                     *(u32x4*)(P + (size_t)row * 5120 + pnl * HALF + lc) = w; }
.LBB0_693:
	v_cndmask_b32_e64 v2, 0, 1, s[8:9]
	v_or_b32_e32 v8, 16, v6
	v_cmp_ne_u32_e64 s[6:7], 1, v2
	s_andn2_b64 vcc, exec, s[8:9]
	s_mov_b64 s[8:9], -1
	s_cbranch_vccnz .LBB0_695
	s_waitcnt lgkmcnt(0)
	v_pk_mul_f32 v[2:3], v[190:191], v[134:135]
	v_pk_mul_f32 v[10:11], v[190:191], v[142:143]
	v_mul_f32_e32 v4, 0xbfb8aa3b, v2
	v_mul_f32_e32 v5, 0xbfb8aa3b, v3
	v_exp_f32_e32 v4, v4
	v_exp_f32_e32 v5, v5
	v_pk_mul_f32 v[12:13], v[190:191], v[138:139]
	v_pk_mul_f32 v[14:15], v[190:191], v[144:145]
	v_add_f32_e32 v4, 1.0, v4
	v_add_f32_e32 v5, 1.0, v5
	v_rcp_f32_e32 v4, v4
	v_rcp_f32_e32 v5, v5
	v_pk_mul_f32 v[16:17], v[190:191], v[140:141]
	v_pk_mul_f32 v[2:3], v[2:3], v[4:5]
	v_pk_mul_f32 v[4:5], v[190:191], v[130:131]
	v_pk_mul_f32 v[2:3], v[2:3], v[10:11]
	v_mul_f32_e32 v7, 0xbfb8aa3b, v4
	v_exp_f32_e32 v7, v7
	v_cvt_pk_bf16_f32 v2, v2, v3
	v_add_f32_e32 v7, 1.0, v7
	v_rcp_f32_e32 v10, v7
	v_mul_f32_e32 v7, 0xbfb8aa3b, v5
	v_exp_f32_e32 v7, v7
	s_nop 0
	v_add_f32_e32 v7, 1.0, v7
	v_rcp_f32_e32 v11, v7
	s_nop 0
	v_pk_mul_f32 v[4:5], v[4:5], v[10:11]
	v_pk_mul_f32 v[10:11], v[190:191], v[136:137]
	v_pk_mul_f32 v[4:5], v[4:5], v[12:13]
	v_mul_f32_e32 v7, 0xbfb8aa3b, v10
	v_exp_f32_e32 v7, v7
	v_cvt_pk_bf16_f32 v4, v4, v5
	v_add_f32_e32 v7, 1.0, v7
	v_rcp_f32_e32 v12, v7
	v_mul_f32_e32 v7, 0xbfb8aa3b, v11
	v_exp_f32_e32 v7, v7
	s_nop 0
	v_add_f32_e32 v7, 1.0, v7
	v_rcp_f32_e32 v13, v7
	s_nop 0
	v_pk_mul_f32 v[10:11], v[10:11], v[12:13]
	v_pk_mul_f32 v[12:13], v[190:191], v[132:133]
	v_pk_mul_f32 v[10:11], v[10:11], v[14:15]
	v_mul_f32_e32 v7, 0xbfb8aa3b, v12
	v_exp_f32_e32 v7, v7
	v_cvt_pk_bf16_f32 v3, v10, v11
	v_mov_b64_e32 v[10:11], s[14:15]
	v_mad_i64_i32 v[10:11], s[8:9], v8, s40, v[10:11]
	v_add_f32_e32 v7, 1.0, v7
	v_rcp_f32_e32 v14, v7
	v_mul_f32_e32 v7, 0xbfb8aa3b, v13
	v_exp_f32_e32 v7, v7
	v_lshl_add_u64 v[10:11], s[86:87], 1, v[10:11]
	v_lshl_add_u64 v[10:11], v[10:11], 0, v[172:173]
	s_mov_b64 s[8:9], 0
	v_add_f32_e32 v7, 1.0, v7
	v_rcp_f32_e32 v15, v7
	s_nop 0
	v_pk_mul_f32 v[12:13], v[12:13], v[14:15]
	s_nop 0
	v_pk_mul_f32 v[12:13], v[12:13], v[16:17]
	s_nop 0
	v_cvt_pk_bf16_f32 v5, v12, v13
	global_store_dwordx4 v[10:11], v[2:5], off sc1

; __device__ __forceinline__ unsigned cvt_pk_bf16(float lo, float hi) { const f32x2_t v = {lo, hi}; return __builtin_bit_cast(unsigned, __builtin_convertvector(v, bf16x2_t)); }
;     __device__ __forceinline__ void operator()(const f32x4 (&acc)[2][2][4][2], const Unit& u, int wr, int wc, int fr, int fq) const {
;     ...
;                         u32x4 w; w.x = cvt_pk_bf16(v0[0], v0[1]); w.y = cvt_pk_bf16(v0[2], v0[3]); w.z = cvt_pk_bf16(v1[0], v1[1]); w.w = cvt_pk_bf16(v1[2], v1[3]);
;                         if (type == 1) *(u32x4*)(P + (size_t)row * 5120 + 1024 + (pnl - 8) * BM + bj * HALF + lc) = w;
;                         else { const int cg = (pnl - (type == 3 ? 12 : 16)) * BM + bj * HALF + lc;
;                             *(u32x4*)((type == 3 ? XB : ZB) + ((size_t)(cg >> 4) * 8448 + row) * 16 + (cg & 8)) = w; } }
.LBB0_703:
	v_ashrrev_i32_e32 v9, 31, v8
	v_cvt_pk_bf16_f32 v2, v2, v3
	v_cvt_pk_bf16_f32 v3, v4, v5
	v_cvt_pk_bf16_f32 v4, v14, v15
	v_cvt_pk_bf16_f32 v5, v12, v13
	s_and_b64 vcc, exec, s[8:9]
	s_mov_b64 s[88:89], -1
	s_cbranch_vccnz .LBB0_705
	v_ashrrev_i32_e32 v7, 4, v18
	s_and_b64 s[44:45], s[78:79], exec
	v_mad_i64_i32 v[12:13], s[88:89], v7, s41, v[8:9]
	s_cselect_b32 s45, s29, s53
	s_cselect_b32 s44, s28, s52
	v_lshlrev_b64 v[12:13], 5, v[12:13]
	v_lshl_add_u64 v[12:13], s[44:45], 0, v[12:13]
	v_lshlrev_b32_e32 v14, 1, v174
	v_mov_b32_e32 v15, v173
	v_lshl_add_u64 v[12:13], v[12:13], 0, v[14:15]
	s_mov_b64 s[88:89], 0
	global_store_dwordx4 v[12:13], v[2:5], off sc1
.LBB0_705:
	v_mad_i64_i32 v[12:13], s[44:45], v8, s40, 0
	s_andn2_b64 vcc, exec, s[88:89]
	v_lshl_add_u64 v[12:13], s[14:15], 0, v[12:13]
	s_cbranch_vccnz .LBB0_707
	s_lshl_b32 s34, s67, 1
	v_lshl_add_u64 v[14:15], v[12:13], 0, s[34:35]
	v_lshl_add_u64 v[14:15], v[14:15], 0, v[172:173]
	global_store_dwordx4 v[14:15], v[2:5], off offset:-2048 sc1

; __device__ __forceinline__ unsigned cvt_pk_bf16(float lo, float hi) { const f32x2_t v = {lo, hi}; return __builtin_bit_cast(unsigned, __builtin_convertvector(v, bf16x2_t)); }
;     __device__ __forceinline__ void operator()(const f32x4 (&acc)[2][2][4][2], const Unit& u, int wr, int wc, int fr, int fq) const {
;     ...
;                         u32x4 w; w.x = cvt_pk_bf16(v0[0], v0[1]); w.y = cvt_pk_bf16(v0[2], v0[3]); w.z = cvt_pk_bf16(v1[0], v1[1]); w.w = cvt_pk_bf16(v1[2], v1[3]);
;                         if (type == 1) *(u32x4*)(P + (size_t)row * 5120 + 1024 + (pnl - 8) * BM + bj * HALF + lc) = w;
;                         else { const int cg = (pnl - (type == 3 ? 12 : 16)) * BM + bj * HALF + lc;
;                             *(u32x4*)((type == 3 ? XB : ZB) + ((size_t)(cg >> 4) * 8448 + row) * 16 + (cg & 8)) = w; } }
.LBB0_711:
	v_cvt_pk_bf16_f32 v2, v2, v3
	v_cvt_pk_bf16_f32 v3, v4, v5
	v_cvt_pk_bf16_f32 v4, v16, v17
	v_cvt_pk_bf16_f32 v5, v14, v15
	s_and_b64 vcc, exec, s[8:9]
	s_mov_b64 s[8:9], -1
	s_cbranch_vccnz .LBB0_719
	v_ashrrev_i32_e32 v7, 4, v18
	v_or_b32_e32 v7, 8, v7
	s_and_b64 s[8:9], s[78:79], exec
	v_mad_i64_i32 v[14:15], s[44:45], v7, s41, v[8:9]
	s_cselect_b32 s9, s29, s53
	s_cselect_b32 s8, s28, s52
	v_lshlrev_b64 v[14:15], 5, v[14:15]
	v_lshl_add_u64 v[14:15], s[8:9], 0, v[14:15]
	v_lshlrev_b32_e32 v16, 1, v174
	v_mov_b32_e32 v17, v173
	v_lshl_add_u64 v[14:15], v[14:15], 0, v[16:17]
	global_store_dwordx4 v[14:15], v[2:5], off sc1
	s_cbranch_execz .LBB0_720

; __device__ __forceinline__ unsigned cvt_pk_bf16(float lo, float hi) { const f32x2_t v = {lo, hi}; return __builtin_bit_cast(unsigned, __builtin_convertvector(v, bf16x2_t)); }
;     __device__ __forceinline__ void operator()(const f32x4 (&acc)[2][2][4][2], const Unit& u, int wr, int wc, int fr, int fq) const {
;     ...
;                         u32x4 w; w.x = cvt_pk_bf16(v0[0], v0[1]); w.y = cvt_pk_bf16(v0[2], v0[3]); w.z = cvt_pk_bf16(v1[0], v1[1]); w.w = cvt_pk_bf16(v1[2], v1[3]);
;                         if (type == 1) *(u32x4*)(P + (size_t)row * 5120 + 1024 + (pnl - 8) * BM + bj * HALF + lc) = w;
;                         else { const int cg = (pnl - (type == 3 ? 12 : 16)) * BM + bj * HALF + lc;
;                             *(u32x4*)((type == 3 ? XB : ZB) + ((size_t)(cg >> 4) * 8448 + row) * 16 + (cg & 8)) = w; } }
.LBB0_720:
	s_lshl_b32 s34, s67, 1
	v_lshl_add_u64 v[12:13], v[12:13], 0, s[34:35]
	v_lshl_add_u64 v[12:13], v[12:13], 0, v[172:173]
	global_store_dwordx4 v[12:13], v[2:5], off offset:-1792 sc1
	s_andn2_b64 vcc, exec, s[76:77]
	s_cbranch_vccz .LBB0_714

; __device__ __forceinline__ unsigned cvt_pk_bf16(float lo, float hi) { const f32x2_t v = {lo, hi}; return __builtin_bit_cast(unsigned, __builtin_convertvector(v, bf16x2_t)); }
; __device__ __forceinline__ float silu_f(float x) { return x * __builtin_amdgcn_rcpf(1.0f + __expf(-x)); }
;     __device__ __forceinline__ void operator()(const f32x4 (&acc)[2][2][4][2], const Unit& u, int wr, int wc, int fr, int fq) const {
;     ...
;             for (int m = 0; m < 4; ++m) { const int row = row0 + ai * HALF + m * 16;
;                 if (type == 0) { f32x4 p0, p1;
; #pragma unroll
;                     for (int j = 0; j < 4; ++j) { p0[j] = (acc[ai][0][m][0][j] * osc) * silu_f(acc[ai][1][m][0][j] * osc); p1[j] = (acc[ai][0][m][1][j] * osc) * silu_f(acc[ai][1][m][1][j] * osc); }
;                     u32x4 w; w.x = cvt_pk_bf16(p0[0], p0[1]); w.y = cvt_pk_bf16(p0[2], p0[3]); w.z = cvt_pk_bf16(p1[0], p1[1]); w.w = cvt_pk_bf16(p1[2], p1[3]);
;                     *(u32x4*)(P + (size_t)row * 5120 + pnl * HALF + lc) = w; }
.LBB0_722:
	s_waitcnt lgkmcnt(0)
	v_pk_mul_f32 v[2:3], v[190:191], v[118:119]
	v_pk_mul_f32 v[10:11], v[190:191], v[126:127]
	v_mul_f32_e32 v4, 0xbfb8aa3b, v2
	v_mul_f32_e32 v5, 0xbfb8aa3b, v3
	v_exp_f32_e32 v4, v4
	v_exp_f32_e32 v5, v5
	v_pk_mul_f32 v[12:13], v[190:191], v[122:123]
	v_pk_mul_f32 v[14:15], v[190:191], v[128:129]
	v_add_f32_e32 v4, 1.0, v4
	v_add_f32_e32 v5, 1.0, v5
	v_rcp_f32_e32 v4, v4
	v_rcp_f32_e32 v5, v5
	v_pk_mul_f32 v[16:17], v[190:191], v[124:125]
	v_pk_mul_f32 v[2:3], v[2:3], v[4:5]
	v_pk_mul_f32 v[4:5], v[190:191], v[114:115]
	v_pk_mul_f32 v[2:3], v[2:3], v[10:11]
	v_mul_f32_e32 v7, 0xbfb8aa3b, v4
	v_exp_f32_e32 v7, v7
	v_cvt_pk_bf16_f32 v2, v2, v3
	v_add_f32_e32 v7, 1.0, v7
	v_rcp_f32_e32 v10, v7
	v_mul_f32_e32 v7, 0xbfb8aa3b, v5
	v_exp_f32_e32 v7, v7
	s_nop 0
	v_add_f32_e32 v7, 1.0, v7
	v_rcp_f32_e32 v11, v7
	s_nop 0
	v_pk_mul_f32 v[4:5], v[4:5], v[10:11]
	v_pk_mul_f32 v[10:11], v[190:191], v[120:121]
	v_pk_mul_f32 v[4:5], v[4:5], v[12:13]
	v_mul_f32_e32 v7, 0xbfb8aa3b, v10
	v_exp_f32_e32 v7, v7
	v_cvt_pk_bf16_f32 v4, v4, v5
	v_add_f32_e32 v7, 1.0, v7
	v_rcp_f32_e32 v12, v7
	v_mul_f32_e32 v7, 0xbfb8aa3b, v11
	v_exp_f32_e32 v7, v7
	s_nop 0
	v_add_f32_e32 v7, 1.0, v7
	v_rcp_f32_e32 v13, v7
	s_nop 0
	v_pk_mul_f32 v[10:11], v[10:11], v[12:13]
	v_pk_mul_f32 v[12:13], v[190:191], v[116:117]
	v_pk_mul_f32 v[10:11], v[10:11], v[14:15]
	v_mul_f32_e32 v7, 0xbfb8aa3b, v12
	v_exp_f32_e32 v7, v7
	v_cvt_pk_bf16_f32 v3, v10, v11
	v_mov_b64_e32 v[10:11], s[14:15]
	v_mad_i64_i32 v[10:11], s[8:9], v8, s40, v[10:11]
	v_add_f32_e32 v7, 1.0, v7
	v_rcp_f32_e32 v14, v7
	v_mul_f32_e32 v7, 0xbfb8aa3b, v13
	v_exp_f32_e32 v7, v7
	v_lshl_add_u64 v[10:11], s[86:87], 1, v[10:11]
	v_lshl_add_u64 v[10:11], v[10:11], 0, v[172:173]
	s_mov_b64 s[8:9], 0
	v_add_f32_e32 v7, 1.0, v7
	v_rcp_f32_e32 v15, v7
	s_nop 0
	v_pk_mul_f32 v[12:13], v[12:13], v[14:15]
	s_nop 0
	v_pk_mul_f32 v[12:13], v[12:13], v[16:17]
	s_nop 0
	v_cvt_pk_bf16_f32 v5, v12, v13
	global_store_dwordx4 v[10:11], v[2:5], off sc1

; __device__ __forceinline__ unsigned cvt_pk_bf16(float lo, float hi) { const f32x2_t v = {lo, hi}; return __builtin_bit_cast(unsigned, __builtin_convertvector(v, bf16x2_t)); }
; __device__ __forceinline__ float silu_f(float x) { return x * __builtin_amdgcn_rcpf(1.0f + __expf(-x)); }
;     __device__ __forceinline__ void operator()(const f32x4 (&acc)[2][2][4][2], const Unit& u, int wr, int wc, int fr, int fq) const {
;     ...
;             for (int m = 0; m < 4; ++m) { const int row = row0 + ai * HALF + m * 16;
;                 if (type == 0) { f32x4 p0, p1;
; #pragma unroll
;                     for (int j = 0; j < 4; ++j) { p0[j] = (acc[ai][0][m][0][j] * osc) * silu_f(acc[ai][1][m][0][j] * osc); p1[j] = (acc[ai][0][m][1][j] * osc) * silu_f(acc[ai][1][m][1][j] * osc); }
;                     u32x4 w; w.x = cvt_pk_bf16(p0[0], p0[1]); w.y = cvt_pk_bf16(p0[2], p0[3]); w.z = cvt_pk_bf16(p1[0], p1[1]); w.w = cvt_pk_bf16(p1[2], p1[3]);
;                     *(u32x4*)(P + (size_t)row * 5120 + pnl * HALF + lc) = w; }
.LBB0_750:
	s_waitcnt lgkmcnt(0)
	v_pk_mul_f32 v[2:3], v[190:191], v[102:103]
	v_pk_mul_f32 v[10:11], v[190:191], v[110:111]
	v_mul_f32_e32 v4, 0xbfb8aa3b, v2
	v_mul_f32_e32 v5, 0xbfb8aa3b, v3
	v_exp_f32_e32 v4, v4
	v_exp_f32_e32 v5, v5
	v_pk_mul_f32 v[12:13], v[190:191], v[106:107]
	v_pk_mul_f32 v[14:15], v[190:191], v[112:113]
	v_add_f32_e32 v4, 1.0, v4
	v_add_f32_e32 v5, 1.0, v5
	v_rcp_f32_e32 v4, v4
	v_rcp_f32_e32 v5, v5
	v_pk_mul_f32 v[16:17], v[190:191], v[108:109]
	v_pk_mul_f32 v[2:3], v[2:3], v[4:5]
	v_pk_mul_f32 v[4:5], v[190:191], v[98:99]
	v_pk_mul_f32 v[2:3], v[2:3], v[10:11]
	v_mul_f32_e32 v7, 0xbfb8aa3b, v4
	v_exp_f32_e32 v7, v7
	v_cvt_pk_bf16_f32 v2, v2, v3
	v_add_f32_e32 v7, 1.0, v7
	v_rcp_f32_e32 v10, v7
	v_mul_f32_e32 v7, 0xbfb8aa3b, v5
	v_exp_f32_e32 v7, v7
	s_nop 0
	v_add_f32_e32 v7, 1.0, v7
	v_rcp_f32_e32 v11, v7
	s_nop 0
	v_pk_mul_f32 v[4:5], v[4:5], v[10:11]
	v_pk_mul_f32 v[10:11], v[190:191], v[104:105]
	v_pk_mul_f32 v[4:5], v[4:5], v[12:13]
	v_mul_f32_e32 v7, 0xbfb8aa3b, v10
	v_exp_f32_e32 v7, v7
	v_cvt_pk_bf16_f32 v4, v4, v5
	v_add_f32_e32 v7, 1.0, v7
	v_rcp_f32_e32 v12, v7
	v_mul_f32_e32 v7, 0xbfb8aa3b, v11
	v_exp_f32_e32 v7, v7
	s_nop 0
	v_add_f32_e32 v7, 1.0, v7
	v_rcp_f32_e32 v13, v7
	s_nop 0
	v_pk_mul_f32 v[10:11], v[10:11], v[12:13]
	v_pk_mul_f32 v[12:13], v[190:191], v[100:101]
	v_pk_mul_f32 v[10:11], v[10:11], v[14:15]
	v_mul_f32_e32 v7, 0xbfb8aa3b, v12
	v_exp_f32_e32 v7, v7
	v_cvt_pk_bf16_f32 v3, v10, v11
	v_mov_b64_e32 v[10:11], s[14:15]
	v_mad_i64_i32 v[10:11], s[8:9], v8, s40, v[10:11]
	v_add_f32_e32 v7, 1.0, v7
	v_rcp_f32_e32 v14, v7
	v_mul_f32_e32 v7, 0xbfb8aa3b, v13
	v_exp_f32_e32 v7, v7
	v_lshl_add_u64 v[10:11], s[86:87], 1, v[10:11]
	v_lshl_add_u64 v[10:11], v[10:11], 0, v[172:173]
	s_mov_b64 s[8:9], 0
	v_add_f32_e32 v7, 1.0, v7
	v_rcp_f32_e32 v15, v7
	s_nop 0
	v_pk_mul_f32 v[12:13], v[12:13], v[14:15]
	s_nop 0
	v_pk_mul_f32 v[12:13], v[12:13], v[16:17]
	s_nop 0
	v_cvt_pk_bf16_f32 v5, v12, v13
	global_store_dwordx4 v[10:11], v[2:5], off sc1

; __device__ __forceinline__ unsigned cvt_pk_bf16(float lo, float hi) { const f32x2_t v = {lo, hi}; return __builtin_bit_cast(unsigned, __builtin_convertvector(v, bf16x2_t)); }
; __device__ __forceinline__ float silu_f(float x) { return x * __builtin_amdgcn_rcpf(1.0f + __expf(-x)); }
;     __device__ __forceinline__ void operator()(const f32x4 (&acc)[2][2][4][2], const Unit& u, int wr, int wc, int fr, int fq) const {
;     ...
;             for (int m = 0; m < 4; ++m) { const int row = row0 + ai * HALF + m * 16;
;                 if (type == 0) { f32x4 p0, p1;
; #pragma unroll
;                     for (int j = 0; j < 4; ++j) { p0[j] = (acc[ai][0][m][0][j] * osc) * silu_f(acc[ai][1][m][0][j] * osc); p1[j] = (acc[ai][0][m][1][j] * osc) * silu_f(acc[ai][1][m][1][j] * osc); }
;                     u32x4 w; w.x = cvt_pk_bf16(p0[0], p0[1]); w.y = cvt_pk_bf16(p0[2], p0[3]); w.z = cvt_pk_bf16(p1[0], p1[1]); w.w = cvt_pk_bf16(p1[2], p1[3]);
;                     *(u32x4*)(P + (size_t)row * 5120 + pnl * HALF + lc) = w; }
.LBB0_778:
	s_waitcnt lgkmcnt(0)
	v_pk_mul_f32 v[2:3], v[190:191], v[86:87]
	v_pk_mul_f32 v[10:11], v[190:191], v[94:95]
	v_mul_f32_e32 v4, 0xbfb8aa3b, v2
	v_mul_f32_e32 v5, 0xbfb8aa3b, v3
	v_exp_f32_e32 v4, v4
	v_exp_f32_e32 v5, v5
	v_pk_mul_f32 v[12:13], v[190:191], v[90:91]
	v_pk_mul_f32 v[14:15], v[190:191], v[96:97]
	v_add_f32_e32 v4, 1.0, v4
	v_add_f32_e32 v5, 1.0, v5
	v_rcp_f32_e32 v4, v4
	v_rcp_f32_e32 v5, v5
	v_pk_mul_f32 v[16:17], v[190:191], v[92:93]
	v_pk_mul_f32 v[2:3], v[2:3], v[4:5]
	v_pk_mul_f32 v[4:5], v[190:191], v[82:83]
	v_pk_mul_f32 v[2:3], v[2:3], v[10:11]
	v_mul_f32_e32 v7, 0xbfb8aa3b, v4
	v_exp_f32_e32 v7, v7
	v_cvt_pk_bf16_f32 v2, v2, v3
	v_add_f32_e32 v7, 1.0, v7
	v_rcp_f32_e32 v10, v7
	v_mul_f32_e32 v7, 0xbfb8aa3b, v5
	v_exp_f32_e32 v7, v7
	s_nop 0
	v_add_f32_e32 v7, 1.0, v7
	v_rcp_f32_e32 v11, v7
	s_nop 0
	v_pk_mul_f32 v[4:5], v[4:5], v[10:11]
	v_pk_mul_f32 v[10:11], v[190:191], v[88:89]
	v_pk_mul_f32 v[4:5], v[4:5], v[12:13]
	v_mul_f32_e32 v7, 0xbfb8aa3b, v10
	v_exp_f32_e32 v7, v7
	v_cvt_pk_bf16_f32 v4, v4, v5
	v_add_f32_e32 v7, 1.0, v7
	v_rcp_f32_e32 v12, v7
	v_mul_f32_e32 v7, 0xbfb8aa3b, v11
	v_exp_f32_e32 v7, v7
	s_nop 0
	v_add_f32_e32 v7, 1.0, v7
	v_rcp_f32_e32 v13, v7
	s_nop 0
	v_pk_mul_f32 v[10:11], v[10:11], v[12:13]
	v_pk_mul_f32 v[12:13], v[190:191], v[84:85]
	v_pk_mul_f32 v[10:11], v[10:11], v[14:15]
	v_mul_f32_e32 v7, 0xbfb8aa3b, v12
	v_exp_f32_e32 v7, v7
	v_cvt_pk_bf16_f32 v3, v10, v11
	v_mov_b64_e32 v[10:11], s[14:15]
	v_mad_i64_i32 v[10:11], s[8:9], v8, s40, v[10:11]
	v_add_f32_e32 v7, 1.0, v7
	v_rcp_f32_e32 v14, v7
	v_mul_f32_e32 v7, 0xbfb8aa3b, v13
	v_exp_f32_e32 v7, v7
	v_lshl_add_u64 v[10:11], s[86:87], 1, v[10:11]
	v_lshl_add_u64 v[10:11], v[10:11], 0, v[172:173]
	s_mov_b64 s[8:9], 0
	v_add_f32_e32 v7, 1.0, v7
	v_rcp_f32_e32 v15, v7
	s_nop 0
	v_pk_mul_f32 v[12:13], v[12:13], v[14:15]
	s_nop 0
	v_pk_mul_f32 v[12:13], v[12:13], v[16:17]
	s_nop 0
	v_cvt_pk_bf16_f32 v5, v12, v13
	global_store_dwordx4 v[10:11], v[2:5], off sc1

; __device__ __forceinline__ unsigned cvt_pk_bf16(float lo, float hi) { const f32x2_t v = {lo, hi}; return __builtin_bit_cast(unsigned, __builtin_convertvector(v, bf16x2_t)); }
; __device__ __forceinline__ float silu_f(float x) { return x * __builtin_amdgcn_rcpf(1.0f + __expf(-x)); }
;     __device__ __forceinline__ void operator()(const f32x4 (&acc)[2][2][4][2], const Unit& u, int wr, int wc, int fr, int fq) const {
;     ...
;             for (int m = 0; m < 4; ++m) { const int row = row0 + ai * HALF + m * 16;
;                 if (type == 0) { f32x4 p0, p1;
; #pragma unroll
;                     for (int j = 0; j < 4; ++j) { p0[j] = (acc[ai][0][m][0][j] * osc) * silu_f(acc[ai][1][m][0][j] * osc); p1[j] = (acc[ai][0][m][1][j] * osc) * silu_f(acc[ai][1][m][1][j] * osc); }
;                     u32x4 w; w.x = cvt_pk_bf16(p0[0], p0[1]); w.y = cvt_pk_bf16(p0[2], p0[3]); w.z = cvt_pk_bf16(p1[0], p1[1]); w.w = cvt_pk_bf16(p1[2], p1[3]);
;                     *(u32x4*)(P + (size_t)row * 5120 + pnl * HALF + lc) = w; }
.LBB0_806:
	s_waitcnt lgkmcnt(0)
	v_pk_mul_f32 v[2:3], v[190:191], v[70:71]
	v_pk_mul_f32 v[10:11], v[190:191], v[78:79]
	v_mul_f32_e32 v4, 0xbfb8aa3b, v2
	v_mul_f32_e32 v5, 0xbfb8aa3b, v3
	v_exp_f32_e32 v4, v4
	v_exp_f32_e32 v5, v5
	v_pk_mul_f32 v[12:13], v[190:191], v[74:75]
	v_pk_mul_f32 v[14:15], v[190:191], v[80:81]
	v_add_f32_e32 v4, 1.0, v4
	v_add_f32_e32 v5, 1.0, v5
	v_rcp_f32_e32 v4, v4
	v_rcp_f32_e32 v5, v5
	v_pk_mul_f32 v[16:17], v[190:191], v[76:77]
	v_pk_mul_f32 v[2:3], v[2:3], v[4:5]
	v_pk_mul_f32 v[4:5], v[190:191], v[66:67]
	v_pk_mul_f32 v[2:3], v[2:3], v[10:11]
	v_mul_f32_e32 v7, 0xbfb8aa3b, v4
	v_exp_f32_e32 v7, v7
	v_cvt_pk_bf16_f32 v2, v2, v3
	v_add_f32_e32 v7, 1.0, v7
	v_rcp_f32_e32 v10, v7
	v_mul_f32_e32 v7, 0xbfb8aa3b, v5
	v_exp_f32_e32 v7, v7
	s_nop 0
	v_add_f32_e32 v7, 1.0, v7
	v_rcp_f32_e32 v11, v7
	s_nop 0
	v_pk_mul_f32 v[4:5], v[4:5], v[10:11]
	v_pk_mul_f32 v[10:11], v[190:191], v[72:73]
	v_pk_mul_f32 v[4:5], v[4:5], v[12:13]
	v_mul_f32_e32 v7, 0xbfb8aa3b, v10
	v_exp_f32_e32 v7, v7
	v_cvt_pk_bf16_f32 v4, v4, v5
	v_add_f32_e32 v7, 1.0, v7
	v_rcp_f32_e32 v12, v7
	v_mul_f32_e32 v7, 0xbfb8aa3b, v11
	v_exp_f32_e32 v7, v7
	s_nop 0
	v_add_f32_e32 v7, 1.0, v7
	v_rcp_f32_e32 v13, v7
	s_nop 0
	v_pk_mul_f32 v[10:11], v[10:11], v[12:13]
	v_pk_mul_f32 v[12:13], v[190:191], v[68:69]
	v_pk_mul_f32 v[10:11], v[10:11], v[14:15]
	v_mul_f32_e32 v7, 0xbfb8aa3b, v12
	v_exp_f32_e32 v7, v7
	v_cvt_pk_bf16_f32 v3, v10, v11
	v_mov_b64_e32 v[10:11], s[14:15]
	v_mad_i64_i32 v[10:11], s[8:9], v8, s40, v[10:11]
	v_add_f32_e32 v7, 1.0, v7
	v_rcp_f32_e32 v14, v7
	v_mul_f32_e32 v7, 0xbfb8aa3b, v13
	v_exp_f32_e32 v7, v7
	v_lshl_add_u64 v[10:11], s[86:87], 1, v[10:11]
	v_lshl_add_u64 v[10:11], v[10:11], 0, v[172:173]
	s_mov_b64 s[8:9], 0
	v_add_f32_e32 v7, 1.0, v7
	v_rcp_f32_e32 v15, v7
	s_nop 0
	v_pk_mul_f32 v[12:13], v[12:13], v[14:15]
	s_nop 0
	v_pk_mul_f32 v[12:13], v[12:13], v[16:17]
	s_nop 0
	v_cvt_pk_bf16_f32 v5, v12, v13
	global_store_dwordx4 v[10:11], v[2:5], off sc1

; __device__ __forceinline__ unsigned cvt_pk_bf16(float lo, float hi) { const f32x2_t v = {lo, hi}; return __builtin_bit_cast(unsigned, __builtin_convertvector(v, bf16x2_t)); }
; __device__ __forceinline__ float silu_f(float x) { return x * __builtin_amdgcn_rcpf(1.0f + __expf(-x)); }
;     __device__ __forceinline__ void operator()(const f32x4 (&acc)[2][2][4][2], const Unit& u, int wr, int wc, int fr, int fq) const {
;     ...
;             for (int m = 0; m < 4; ++m) { const int row = row0 + ai * HALF + m * 16;
;                 if (type == 0) { f32x4 p0, p1;
; #pragma unroll
;                     for (int j = 0; j < 4; ++j) { p0[j] = (acc[ai][0][m][0][j] * osc) * silu_f(acc[ai][1][m][0][j] * osc); p1[j] = (acc[ai][0][m][1][j] * osc) * silu_f(acc[ai][1][m][1][j] * osc); }
;                     u32x4 w; w.x = cvt_pk_bf16(p0[0], p0[1]); w.y = cvt_pk_bf16(p0[2], p0[3]); w.z = cvt_pk_bf16(p1[0], p1[1]); w.w = cvt_pk_bf16(p1[2], p1[3]);
;                     *(u32x4*)(P + (size_t)row * 5120 + pnl * HALF + lc) = w; }
.LBB0_834:
	s_waitcnt lgkmcnt(0)
	v_pk_mul_f32 v[2:3], v[190:191], v[54:55]
	v_pk_mul_f32 v[10:11], v[190:191], v[62:63]
	v_mul_f32_e32 v4, 0xbfb8aa3b, v2
	v_mul_f32_e32 v5, 0xbfb8aa3b, v3
	v_exp_f32_e32 v4, v4
	v_exp_f32_e32 v5, v5
	v_pk_mul_f32 v[12:13], v[190:191], v[58:59]
	v_pk_mul_f32 v[14:15], v[190:191], v[64:65]
	v_add_f32_e32 v4, 1.0, v4
	v_add_f32_e32 v5, 1.0, v5
	v_rcp_f32_e32 v4, v4
	v_rcp_f32_e32 v5, v5
	v_pk_mul_f32 v[16:17], v[190:191], v[60:61]
	v_pk_mul_f32 v[2:3], v[2:3], v[4:5]
	v_pk_mul_f32 v[4:5], v[190:191], v[50:51]
	v_pk_mul_f32 v[2:3], v[2:3], v[10:11]
	v_mul_f32_e32 v7, 0xbfb8aa3b, v4
	v_exp_f32_e32 v7, v7
	v_cvt_pk_bf16_f32 v2, v2, v3
	v_add_f32_e32 v7, 1.0, v7
	v_rcp_f32_e32 v10, v7
	v_mul_f32_e32 v7, 0xbfb8aa3b, v5
	v_exp_f32_e32 v7, v7
	s_nop 0
	v_add_f32_e32 v7, 1.0, v7
	v_rcp_f32_e32 v11, v7
	s_nop 0
	v_pk_mul_f32 v[4:5], v[4:5], v[10:11]
	v_pk_mul_f32 v[10:11], v[190:191], v[56:57]
	v_pk_mul_f32 v[4:5], v[4:5], v[12:13]
	v_mul_f32_e32 v7, 0xbfb8aa3b, v10
	v_exp_f32_e32 v7, v7
	v_cvt_pk_bf16_f32 v4, v4, v5
	v_add_f32_e32 v7, 1.0, v7
	v_rcp_f32_e32 v12, v7
	v_mul_f32_e32 v7, 0xbfb8aa3b, v11
	v_exp_f32_e32 v7, v7
	s_nop 0
	v_add_f32_e32 v7, 1.0, v7
	v_rcp_f32_e32 v13, v7
	s_nop 0
	v_pk_mul_f32 v[10:11], v[10:11], v[12:13]
	v_pk_mul_f32 v[12:13], v[190:191], v[52:53]
	v_pk_mul_f32 v[10:11], v[10:11], v[14:15]
	v_mul_f32_e32 v7, 0xbfb8aa3b, v12
	v_exp_f32_e32 v7, v7
	v_cvt_pk_bf16_f32 v3, v10, v11
	v_mov_b64_e32 v[10:11], s[14:15]
	v_mad_i64_i32 v[10:11], s[8:9], v8, s40, v[10:11]
	v_add_f32_e32 v7, 1.0, v7
	v_rcp_f32_e32 v14, v7
	v_mul_f32_e32 v7, 0xbfb8aa3b, v13
	v_exp_f32_e32 v7, v7
	v_lshl_add_u64 v[10:11], s[86:87], 1, v[10:11]
	v_lshl_add_u64 v[10:11], v[10:11], 0, v[172:173]
	s_mov_b64 s[8:9], 0
	v_add_f32_e32 v7, 1.0, v7
	v_rcp_f32_e32 v15, v7
	s_nop 0
	v_pk_mul_f32 v[12:13], v[12:13], v[14:15]
	s_nop 0
	v_pk_mul_f32 v[12:13], v[12:13], v[16:17]
	s_nop 0
	v_cvt_pk_bf16_f32 v5, v12, v13
	global_store_dwordx4 v[10:11], v[2:5], off sc1

; __device__ __forceinline__ unsigned cvt_pk_bf16(float lo, float hi) { const f32x2_t v = {lo, hi}; return __builtin_bit_cast(unsigned, __builtin_convertvector(v, bf16x2_t)); }
; __device__ __forceinline__ float silu_f(float x) { return x * __builtin_amdgcn_rcpf(1.0f + __expf(-x)); }
;     __device__ __forceinline__ void operator()(const f32x4 (&acc)[2][2][4][2], const Unit& u, int wr, int wc, int fr, int fq) const {
;     ...
;             for (int m = 0; m < 4; ++m) { const int row = row0 + ai * HALF + m * 16;
;                 if (type == 0) { f32x4 p0, p1;
; #pragma unroll
;                     for (int j = 0; j < 4; ++j) { p0[j] = (acc[ai][0][m][0][j] * osc) * silu_f(acc[ai][1][m][0][j] * osc); p1[j] = (acc[ai][0][m][1][j] * osc) * silu_f(acc[ai][1][m][1][j] * osc); }
;                     u32x4 w; w.x = cvt_pk_bf16(p0[0], p0[1]); w.y = cvt_pk_bf16(p0[2], p0[3]); w.z = cvt_pk_bf16(p1[0], p1[1]); w.w = cvt_pk_bf16(p1[2], p1[3]);
;                     *(u32x4*)(P + (size_t)row * 5120 + pnl * HALF + lc) = w; }
.LBB0_862:
	s_waitcnt lgkmcnt(0)
	v_pk_mul_f32 v[2:3], v[190:191], v[38:39]
	v_pk_mul_f32 v[8:9], v[190:191], v[46:47]
	v_mul_f32_e32 v4, 0xbfb8aa3b, v2
	v_mul_f32_e32 v5, 0xbfb8aa3b, v3
	v_exp_f32_e32 v4, v4
	v_exp_f32_e32 v5, v5
	v_pk_mul_f32 v[10:11], v[190:191], v[42:43]
	v_pk_mul_f32 v[12:13], v[190:191], v[48:49]
	v_add_f32_e32 v4, 1.0, v4
	v_add_f32_e32 v5, 1.0, v5
	v_rcp_f32_e32 v4, v4
	v_rcp_f32_e32 v5, v5
	v_pk_mul_f32 v[14:15], v[190:191], v[44:45]
	v_pk_mul_f32 v[2:3], v[2:3], v[4:5]
	v_pk_mul_f32 v[4:5], v[190:191], v[34:35]
	v_pk_mul_f32 v[2:3], v[2:3], v[8:9]
	v_mul_f32_e32 v7, 0xbfb8aa3b, v4
	v_exp_f32_e32 v7, v7
	v_cvt_pk_bf16_f32 v2, v2, v3
	v_add_f32_e32 v7, 1.0, v7
	v_rcp_f32_e32 v8, v7
	v_mul_f32_e32 v7, 0xbfb8aa3b, v5
	v_exp_f32_e32 v7, v7
	s_nop 0
	v_add_f32_e32 v7, 1.0, v7
	v_rcp_f32_e32 v9, v7
	s_nop 0
	v_pk_mul_f32 v[4:5], v[4:5], v[8:9]
	v_pk_mul_f32 v[8:9], v[190:191], v[40:41]
	v_pk_mul_f32 v[4:5], v[4:5], v[10:11]
	v_mul_f32_e32 v7, 0xbfb8aa3b, v8
	v_exp_f32_e32 v7, v7
	v_cvt_pk_bf16_f32 v4, v4, v5
	v_add_f32_e32 v7, 1.0, v7
	v_rcp_f32_e32 v10, v7
	v_mul_f32_e32 v7, 0xbfb8aa3b, v9
	v_exp_f32_e32 v7, v7
	s_nop 0
	v_add_f32_e32 v7, 1.0, v7
	v_rcp_f32_e32 v11, v7
	s_nop 0
	v_pk_mul_f32 v[8:9], v[8:9], v[10:11]
	v_pk_mul_f32 v[10:11], v[190:191], v[36:37]
	v_pk_mul_f32 v[8:9], v[8:9], v[12:13]
	v_mul_f32_e32 v7, 0xbfb8aa3b, v10
	v_exp_f32_e32 v7, v7
	v_cvt_pk_bf16_f32 v3, v8, v9
	v_mov_b64_e32 v[8:9], s[14:15]
	v_mad_i64_i32 v[8:9], s[6:7], v6, s40, v[8:9]
	v_add_f32_e32 v7, 1.0, v7
	v_rcp_f32_e32 v12, v7
	v_mul_f32_e32 v7, 0xbfb8aa3b, v11
	v_exp_f32_e32 v7, v7
	v_lshl_add_u64 v[8:9], s[86:87], 1, v[8:9]
	v_lshl_add_u64 v[8:9], v[8:9], 0, v[172:173]
	s_mov_b64 s[6:7], 0
	v_add_f32_e32 v7, 1.0, v7
	v_rcp_f32_e32 v13, v7
	s_nop 0
	v_pk_mul_f32 v[10:11], v[10:11], v[12:13]
	s_nop 0
	v_pk_mul_f32 v[10:11], v[10:11], v[14:15]
	s_nop 0
	v_cvt_pk_bf16_f32 v5, v10, v11
	global_store_dwordx4 v[8:9], v[2:5], off sc1

; __device__ __forceinline__ unsigned cvt_pk_bf16(float lo, float hi) { const f32x2_t v = {lo, hi}; return __builtin_bit_cast(unsigned, __builtin_convertvector(v, bf16x2_t)); }
;     __device__ __forceinline__ void operator()(const f32x4 (&acc)[2][2][4][2], const Unit& u, int wr, int wc, int fr, int fq) const {
;     ...
;                         u32x4 w; w.x = cvt_pk_bf16(v0[0], v0[1]); w.y = cvt_pk_bf16(v0[2], v0[3]); w.z = cvt_pk_bf16(v1[0], v1[1]); w.w = cvt_pk_bf16(v1[2], v1[3]);
;                         if (type == 1) *(u32x4*)(P + (size_t)row * 5120 + 1024 + (pnl - 8) * BM + bj * HALF + lc) = w;
;                         else { const int cg = (pnl - (type == 3 ? 12 : 16)) * BM + bj * HALF + lc;
;                             *(u32x4*)((type == 3 ? XB : ZB) + ((size_t)(cg >> 4) * 8448 + row) * 16 + (cg & 8)) = w; } }
.LBB0_871:
	v_ashrrev_i32_e32 v7, 31, v6
	v_cvt_pk_bf16_f32 v2, v2, v3
	v_cvt_pk_bf16_f32 v3, v4, v5
	v_cvt_pk_bf16_f32 v4, v12, v13
	v_cvt_pk_bf16_f32 v5, v10, v11
	s_mov_b64 s[8:9], -1
	s_and_b64 vcc, exec, s[6:7]
	v_ashrrev_i32_e32 v18, 4, v18
	v_lshlrev_b32_e32 v10, 1, v174
	s_cbranch_vccnz .LBB0_873
	s_and_b64 s[8:9], s[78:79], exec
	v_mad_i64_i32 v[12:13], s[44:45], v18, s41, v[6:7]
	s_cselect_b32 s9, s29, s53
	s_cselect_b32 s8, s28, s52
	v_lshlrev_b64 v[12:13], 5, v[12:13]
	v_lshl_add_u64 v[12:13], s[8:9], 0, v[12:13]
	v_mov_b32_e32 v11, v173
	v_lshl_add_u64 v[12:13], v[12:13], 0, v[10:11]
	s_mov_b64 s[8:9], 0
	global_store_dwordx4 v[12:13], v[2:5], off sc1
.LBB0_873:
	v_mad_i64_i32 v[12:13], s[44:45], v6, s40, 0
	s_andn2_b64 vcc, exec, s[8:9]
	v_lshl_add_u64 v[12:13], s[14:15], 0, v[12:13]
	s_cbranch_vccnz .LBB0_875
	s_lshl_b32 s34, s67, 1
	v_lshl_add_u64 v[14:15], v[12:13], 0, s[34:35]
	v_lshl_add_u64 v[14:15], v[14:15], 0, v[172:173]
	global_store_dwordx4 v[14:15], v[2:5], off offset:-2048 sc1

; __device__ __forceinline__ unsigned cvt_pk_bf16(float lo, float hi) { const f32x2_t v = {lo, hi}; return __builtin_bit_cast(unsigned, __builtin_convertvector(v, bf16x2_t)); }
;     __device__ __forceinline__ void operator()(const f32x4 (&acc)[2][2][4][2], const Unit& u, int wr, int wc, int fr, int fq) const {
;     ...
;                         u32x4 w; w.x = cvt_pk_bf16(v0[0], v0[1]); w.y = cvt_pk_bf16(v0[2], v0[3]); w.z = cvt_pk_bf16(v1[0], v1[1]); w.w = cvt_pk_bf16(v1[2], v1[3]);
;                         if (type == 1) *(u32x4*)(P + (size_t)row * 5120 + 1024 + (pnl - 8) * BM + bj * HALF + lc) = w;
;                         else { const int cg = (pnl - (type == 3 ? 12 : 16)) * BM + bj * HALF + lc;
;                             *(u32x4*)((type == 3 ? XB : ZB) + ((size_t)(cg >> 4) * 8448 + row) * 16 + (cg & 8)) = w; } }
.LBB0_879:
	v_cvt_pk_bf16_f32 v2, v2, v3
	v_cvt_pk_bf16_f32 v3, v4, v5
	v_cvt_pk_bf16_f32 v4, v16, v17
	v_cvt_pk_bf16_f32 v5, v14, v15
	s_and_b64 vcc, exec, s[6:7]
	s_mov_b64 s[4:5], -1
	s_cbranch_vccnz .LBB0_887
	v_or_b32_e32 v11, 8, v18
	s_and_b64 s[4:5], s[78:79], exec
	v_mad_i64_i32 v[14:15], s[6:7], v11, s41, v[6:7]
	s_cselect_b32 s5, s29, s53
	s_cselect_b32 s4, s28, s52
	v_lshlrev_b64 v[14:15], 5, v[14:15]
	v_lshl_add_u64 v[14:15], s[4:5], 0, v[14:15]
	v_mov_b32_e32 v11, v173
	v_lshl_add_u64 v[10:11], v[14:15], 0, v[10:11]
	global_store_dwordx4 v[10:11], v[2:5], off sc1
	s_cbranch_execz .LBB0_888

; __device__ __forceinline__ unsigned cvt_pk_bf16(float lo, float hi) { const f32x2_t v = {lo, hi}; return __builtin_bit_cast(unsigned, __builtin_convertvector(v, bf16x2_t)); }
;     __device__ __forceinline__ void operator()(const f32x4 (&acc)[2][2][4][2], const Unit& u, int wr, int wc, int fr, int fq) const {
;     ...
;                         u32x4 w; w.x = cvt_pk_bf16(v0[0], v0[1]); w.y = cvt_pk_bf16(v0[2], v0[3]); w.z = cvt_pk_bf16(v1[0], v1[1]); w.w = cvt_pk_bf16(v1[2], v1[3]);
;                         if (type == 1) *(u32x4*)(P + (size_t)row * 5120 + 1024 + (pnl - 8) * BM + bj * HALF + lc) = w;
;                         else { const int cg = (pnl - (type == 3 ? 12 : 16)) * BM + bj * HALF + lc;
;                             *(u32x4*)((type == 3 ? XB : ZB) + ((size_t)(cg >> 4) * 8448 + row) * 16 + (cg & 8)) = w; } }
.LBB0_888:
	s_lshl_b32 s34, s67, 1
	v_lshl_add_u64 v[10:11], v[12:13], 0, s[34:35]
	v_lshl_add_u64 v[10:11], v[10:11], 0, v[172:173]
	global_store_dwordx4 v[10:11], v[2:5], off offset:-1792 sc1
	s_andn2_b64 vcc, exec, s[76:77]
	s_cbranch_vccz .LBB0_882

;     __device__ __forceinline__ void fused(f32x4 (&acc)[2][2][4][2], const Unit& u, int wr, int wc, int fr, int fq, PG8_LAS unsigned char* lds, int wid, int lane) const {
;     ...
;             for (int n = 0; n < 2; ++n) { const int cc = col0 + bj * HALF + n * 16; const float* mb = mod + (size_t)bidx * 6144;
;                 gg[bj][n] = *(const f32x4*)(mb + 4096 + cc) * *(const f32x4*)(gpost + cc);
;                 const f32x4 gs = *(const f32x4*)(gpre + cc) * (*(const f32x4*)(mb + 2048 + cc) + 1.0f);
; #pragma unroll
;                 for (int j = 0; j < 4; ++j) ia[bj][n][j] = __builtin_amdgcn_rcpf(gs[j]);
;                 sh[bj][n] = *(const f32x4*)(mb + cc); }
;         const float xr_row = (lane < 32) ? xrms[rowg0 + wid * 32 + (lane & 31)] : 0.f;
;         if (wid == 0) { const unsigned long long t0 = __builtin_amdgcn_s_memrealtime();
;             for (;;) { if ((unsigned)__builtin_amdgcn_readfirstlane(__hip_atomic_load(cnt + 64 * u.pm, __ATOMIC_RELAXED, __HIP_MEMORY_SCOPE_AGENT)) >= 64u) break;
;                 if (__builtin_amdgcn_s_memrealtime() - t0 > 2000000ull) { if (lane == 0) __hip_atomic_store(tmo, 1u, __ATOMIC_RELAXED, __HIP_MEMORY_SCOPE_AGENT); break; }
;                 __builtin_amdgcn_s_sleep(2); }
;             asm volatile("" ::: "memory");     }
;         asm volatile("s_waitcnt vmcnt(0) lgkmcnt(0)" ::: "memory"); __builtin_amdgcn_s_barrier(); asm volatile("" ::: "memory");
;         if (lane < 32) { const unsigned* slot = (const unsigned*)xbuf + (size_t)(u.pm * BM + row) * 8; float q = 0.f;
; #pragma unroll
;             for (int t = 0; t < 8; ++t) q += __uint_as_float(__hip_atomic_load(slot + t, __ATOMIC_RELAXED, __HIP_MEMORY_SCOPE_AGENT));
;             Sr[row] = __builtin_amdgcn_rsqf(q * (1.0f / 2048.0f) + 1e-6f); Sr[256 + row] = xr_row; }
;         asm volatile("s_waitcnt lgkmcnt(0)" ::: "memory"); __builtin_amdgcn_s_barrier(); asm volatile("" ::: "memory");
; #pragma unroll
;         for (int ai = 0; ai < 2; ++ai)
; #pragma unroll
;             for (int m = 0; m < 4; ++m) { const int r = ai * HALF + wr * 64 + m * 16 + fr; const float rs = Sr[r], rx = Sr[256 + r]; const size_t off = (rowg0 + r) * 2048 + col0;
; #pragma unroll
;                 for (int bj = 0; bj < 2; ++bj)
; #pragma unroll
;                     for (int n = 0; n < 2; ++n) { const int c8 = 16 * bj + 4 * wc + 2 * n + (fq >> 1);
.LBB0_1140:
	s_or_b64 exec, exec, s[4:5]
	s_waitcnt vmcnt(0)
	v_pk_mul_f32 v[30:31], v[34:35], v[30:31]
	v_add_f32_e32 v34, 1.0, v38
	v_mul_f32_e32 v22, v22, v34
	v_add_f32_e32 v34, 1.0, v39
	v_pk_mul_f32 v[20:21], v[28:29], v[20:21]
	v_pk_mul_f32 v[26:27], v[26:27], v[18:19]
	v_and_or_b32 v28, v163, 15, s29
	v_lshlrev_b32_e32 v18, 9, v163
	v_lshlrev_b32_e32 v1, 3, v1
	v_mul_f32_e32 v23, v23, v34
	v_add_f32_e32 v34, 1.0, v40
	v_and_b32_e32 v18, 0x200, v18
	v_and_b32_e32 v1, 8, v1
	v_lshlrev_b32_e32 v39, 9, v28
	v_add_f32_e32 v46, 1.0, v46
	v_mul_f32_e32 v24, v24, v34
	v_add_f32_e32 v34, 1.0, v41
	v_lshl_add_u32 v41, s25, 2, v221
	v_add3_u32 v38, 0, v18, v1
	v_and_b32_e32 v39, 0x7fff9c00, v39
	v_mul_f32_e32 v42, v42, v46
	v_add_f32_e32 v46, 1.0, v47
	v_add_u32_e32 v47, v38, v39
	v_bitop3_b32 v39, v41, v163, 15 bitop3:0x78
	v_mul_f32_e32 v43, v43, v46
	v_add_f32_e32 v46, 1.0, v48
	v_lshlrev_b32_e32 v39, 4, v39
	v_mul_f32_e32 v44, v44, v46
	v_add_f32_e32 v46, 1.0, v49
	s_waitcnt lgkmcnt(0)
	s_barrier
	s_add_i32 s0, 0, 0x21000
	v_add_u32_e32 v40, v47, v39
	v_mul_f32_e32 v45, v45, v46
	v_lshl_add_u32 v46, v28, 2, s0
	ds_read_b64 v[48:49], v40
	v_add_u32_e32 v1, 16, v41
	v_add_u32_e32 v18, 0x200, v46
	v_add_u32_e32 v40, 2, v41
	v_add_u32_e32 v41, 18, v41
	v_mul_f32_e32 v25, v25, v34
	v_bitop3_b32 v1, v1, v163, 15 bitop3:0x78
	ds_read2_b32 v[18:19], v18 offset0:48 offset1:128
	v_bitop3_b32 v40, v40, v163, 15 bitop3:0x78
	v_bitop3_b32 v41, v41, v163, 15 bitop3:0x78
	v_rcp_f32_e32 v22, v22
	v_rcp_f32_e32 v23, v23
	v_rcp_f32_e32 v24, v24
	v_rcp_f32_e32 v25, v25
	v_lshlrev_b32_e32 v1, 4, v1
	ds_read2st64_b32 v[34:35], v46 offset1:2
	v_lshlrev_b32_e32 v40, 4, v40
	v_lshlrev_b32_e32 v41, 4, v41
	v_add_f32_e32 v78, 1.0, v78
	v_add_f32_e32 v58, 1.0, v58
	v_add_f32_e32 v59, 1.0, v59
	v_add_f32_e32 v60, 1.0, v60
	v_add_f32_e32 v61, 1.0, v61
	v_pk_mul_f32 v[50:51], v[50:51], v[54:55]
	v_add_u32_e32 v54, v47, v40
	v_add_u32_e32 v55, v47, v1
	v_add_u32_e32 v47, v47, v41
	v_mul_f32_e32 v74, v74, v78
	v_add_f32_e32 v78, 1.0, v79
	v_pk_mul_f32 v[66:67], v[66:67], v[70:71]
	v_mul_f32_e32 v58, v62, v58
	v_mul_f32_e32 v59, v63, v59
	v_mul_f32_e32 v60, v64, v60
	v_mul_f32_e32 v61, v65, v61
	v_mov_b32_e32 v29, 0
	ds_read_b64 v[62:63], v54
	ds_read_b64 v[64:65], v55
	ds_read_b64 v[70:71], v47
	s_waitcnt lgkmcnt(0)
	v_lshlrev_b32_e32 v47, 16, v48
	v_and_b32_e32 v48, 0xffff0000, v48
	v_lshlrev_b32_e32 v54, 16, v49
	v_and_b32_e32 v55, 0xffff0000, v49
	v_mul_f32_e32 v75, v75, v78
	v_add_f32_e32 v78, 1.0, v80
	v_pk_mul_f32 v[32:33], v[36:37], v[32:33]
	v_lshl_add_u64 v[36:37], s[14:15], 0, v[28:29]
	v_sub_f32_e32 v49, v48, v15
	v_sub_f32_e32 v48, v47, v14
	v_sub_f32_e32 v55, v55, v17
	v_sub_f32_e32 v54, v54, v16
	v_mul_f32_e32 v76, v76, v78
	v_add_f32_e32 v78, 1.0, v81
	v_pk_mul_f32 v[68:69], v[68:69], v[72:73]
	v_lshlrev_b64 v[36:37], 13, v[36:37]
	v_pk_mul_f32 v[54:55], v[24:25], v[54:55]
	v_pk_mul_f32 v[48:49], v[22:23], v[48:49]
	v_mov_b32_e32 v72, v19
	v_mul_f32_e32 v77, v77, v78
	v_pk_mul_f32 v[52:53], v[52:53], v[56:57]
	v_rcp_f32_e32 v42, v42
	v_rcp_f32_e32 v43, v43
	v_rcp_f32_e32 v44, v44
	v_rcp_f32_e32 v45, v45
	v_pk_mul_f32 v[48:49], v[72:73], v[48:49] op_sel_hi:[0,1]
	v_pk_mul_f32 v[54:55], v[72:73], v[54:55] op_sel_hi:[0,1]
	v_pk_mul_f32 v[78:79], v[212:213], v[34:35] op_sel_hi:[1,0]
	v_pk_mul_f32 v[56:57], v[210:211], v[34:35] op_sel_hi:[1,0]
	v_lshl_add_u64 v[36:37], s[92:93], 0, v[36:37]
	v_pk_fma_f32 v[56:57], v[20:21], v[56:57], v[54:55]
	v_pk_fma_f32 v[54:55], v[26:27], v[78:79], v[48:49]
	v_lshl_add_u64 v[36:37], v[36:37], 0, v[146:147]
	global_store_dwordx4 v[36:37], v[54:57], off sc1
	v_lshlrev_b32_e32 v19, 16, v62
	v_and_b32_e32 v47, 0xffff0000, v62
	v_lshlrev_b32_e32 v54, 16, v63
	v_and_b32_e32 v55, 0xffff0000, v63
	v_sub_f32_e32 v49, v47, v11
	v_sub_f32_e32 v48, v19, v10
	v_sub_f32_e32 v55, v55, v13
	v_sub_f32_e32 v54, v54, v12
	v_pk_mul_f32 v[54:55], v[44:45], v[54:55]
	v_pk_mul_f32 v[48:49], v[42:43], v[48:49]
	v_rcp_f32_e32 v58, v58
	v_rcp_f32_e32 v59, v59
	v_rcp_f32_e32 v60, v60
	v_rcp_f32_e32 v61, v61
	v_pk_mul_f32 v[48:49], v[72:73], v[48:49] op_sel_hi:[0,1]
	v_pk_mul_f32 v[54:55], v[72:73], v[54:55] op_sel_hi:[0,1]
	v_pk_mul_f32 v[62:63], v[208:209], v[34:35] op_sel_hi:[1,0]
	v_pk_mul_f32 v[56:57], v[206:207], v[34:35] op_sel_hi:[1,0]
	v_lshlrev_b32_e32 v19, 16, v64
	v_pk_fma_f32 v[56:57], v[32:33], v[56:57], v[54:55]
	v_pk_fma_f32 v[54:55], v[30:31], v[62:63], v[48:49]
	global_store_dwordx4 v[36:37], v[54:57], off offset:64 sc1
	v_and_b32_e32 v47, 0xffff0000, v64
	v_sub_f32_e32 v49, v47, v7
	v_lshlrev_b32_e32 v54, 16, v65
	v_and_b32_e32 v55, 0xffff0000, v65
	v_sub_f32_e32 v48, v19, v6
	v_sub_f32_e32 v55, v55, v9
	v_sub_f32_e32 v54, v54, v8
	v_pk_mul_f32 v[54:55], v[60:61], v[54:55]
	v_pk_mul_f32 v[48:49], v[58:59], v[48:49]
	v_rcp_f32_e32 v74, v74
	v_rcp_f32_e32 v75, v75
	v_rcp_f32_e32 v76, v76
	v_rcp_f32_e32 v77, v77
	v_pk_mul_f32 v[48:49], v[72:73], v[48:49] op_sel_hi:[0,1]
	v_pk_mul_f32 v[54:55], v[72:73], v[54:55] op_sel_hi:[0,1]
	v_pk_mul_f32 v[62:63], v[204:205], v[34:35] op_sel_hi:[1,0]
	v_pk_mul_f32 v[56:57], v[202:203], v[34:35] op_sel_hi:[1,0]
	v_lshlrev_b32_e32 v19, 16, v70
	v_pk_fma_f32 v[56:57], v[52:53], v[56:57], v[54:55]
	v_pk_fma_f32 v[54:55], v[50:51], v[62:63], v[48:49]
	global_store_dwordx4 v[36:37], v[54:57], off offset:512 sc1
	v_and_b32_e32 v47, 0xffff0000, v70
	v_sub_f32_e32 v49, v47, v3
	v_lshlrev_b32_e32 v54, 16, v71
	v_and_b32_e32 v55, 0xffff0000, v71
	v_sub_f32_e32 v48, v19, v2
	v_sub_f32_e32 v55, v55, v5
	v_sub_f32_e32 v54, v54, v4
	v_pk_mul_f32 v[54:55], v[76:77], v[54:55]
	v_pk_mul_f32 v[48:49], v[74:75], v[48:49]
	v_pk_mul_f32 v[54:55], v[72:73], v[54:55] op_sel_hi:[0,1]
	v_pk_mul_f32 v[48:49], v[72:73], v[48:49] op_sel_hi:[0,1]
	v_pk_mul_f32 v[62:63], v[200:201], v[34:35] op_sel_hi:[1,0]
	v_pk_mul_f32 v[56:57], v[198:199], v[34:35] op_sel_hi:[1,0]
	s_nop 0
	v_pk_fma_f32 v[56:57], v[68:69], v[56:57], v[54:55]
	v_pk_fma_f32 v[54:55], v[66:67], v[62:63], v[48:49]
	global_store_dwordx4 v[36:37], v[54:57], off offset:576 sc1
	v_or_b32_e32 v36, 16, v28
	v_lshl_add_u32 v19, v36, 2, s0
	ds_read2st64_b32 v[48:49], v19 offset1:4
	v_lshlrev_b32_e32 v19, 9, v36
	v_and_b32_e32 v19, 0x7fffbc00, v19
	v_mov_b32_e32 v37, v29
	v_add_u32_e32 v19, v38, v19
	v_lshl_add_u64 v[54:55], s[14:15], 0, v[36:37]
	v_add_u32_e32 v34, v19, v39
	v_lshlrev_b64 v[36:37], 13, v[54:55]
	ds_read_b64 v[54:55], v34
	v_add_u32_e32 v34, v19, v40
	v_add_u32_e32 v47, v19, v1
	v_add_u32_e32 v19, v19, v41
	ds_read_b64 v[62:63], v34
	ds_read_b64 v[64:65], v47
	ds_read_b64 v[70:71], v19
	s_waitcnt lgkmcnt(3)
; #define PG8_LAS __attribute__((address_space(3)))
;     __device__ __forceinline__ void fused(f32x4 (&acc)[2][2][4][2], const Unit& u, int wr, int wc, int fr, int fq, PG8_LAS unsigned char* lds, int wid, int lane) const {
;     ...
;             for (int m = 0; m < 4; ++m) { const int r = ai * HALF + wr * 64 + m * 16 + fr; const float rs = Sr[r], rx = Sr[256 + r]; const size_t off = (rowg0 + r) * 2048 + col0;
; #pragma unroll
;                 for (int bj = 0; bj < 2; ++bj)
; #pragma unroll
;                     for (int n = 0; n < 2; ++n) { const int c8 = 16 * bj + 4 * wc + 2 * n + (fq >> 1);
;                         const u32x4 dummy = {0u, 0u, 0u, 0u}; (void)dummy;
;                         const unsigned long long hw = *(const PG8_LAS unsigned long long*)(lds + (r >> 1) * 1024 + (r & 1) * 512 + ((c8 ^ (r & 15)) * 16) + 8 * (fq & 1));
;                         const unsigned lo = (unsigned)hw, hi = (unsigned)(hw >> 32);
;                         const f32x4 h = (f32x4){__uint_as_float(lo << 16), __uint_as_float(lo & 0xffff0000u), __uint_as_float(hi << 16), __uint_as_float(hi & 0xffff0000u)};
;                         const f32x4 xr = (h - sh[bj][n]) * ia[bj][n] * rx;
;                         __builtin_nontemporal_store(xr + gg[bj][n] * (acc[ai][bj][m][n] * rs), (f32x4*)(out + off + bj * HALF + n * 16)); } }
	v_lshlrev_b32_e32 v19, 16, v54
	v_and_b32_e32 v34, 0xffff0000, v54
	v_lshlrev_b32_e32 v47, 16, v55
	v_and_b32_e32 v56, 0xffff0000, v55
	v_sub_f32_e32 v55, v34, v15
	v_sub_f32_e32 v54, v19, v14
	v_sub_f32_e32 v57, v56, v17
	v_sub_f32_e32 v56, v47, v16
	v_pk_mul_f32 v[56:57], v[24:25], v[56:57]
	v_pk_mul_f32 v[54:55], v[22:23], v[54:55]
	v_mov_b32_e32 v34, v49
	v_pk_mul_f32 v[54:55], v[34:35], v[54:55] op_sel_hi:[0,1]
	v_pk_mul_f32 v[56:57], v[34:35], v[56:57] op_sel_hi:[0,1]
	v_pk_mul_f32 v[72:73], v[196:197], v[48:49] op_sel_hi:[1,0]
	v_pk_mul_f32 v[78:79], v[194:195], v[48:49] op_sel_hi:[1,0]
	v_lshl_add_u64 v[36:37], s[92:93], 0, v[36:37]
	v_pk_fma_f32 v[56:57], v[20:21], v[78:79], v[56:57]
	v_pk_fma_f32 v[54:55], v[26:27], v[72:73], v[54:55]
	v_lshl_add_u64 v[36:37], v[36:37], 0, v[146:147]
	global_store_dwordx4 v[36:37], v[54:57], off sc1
	s_waitcnt lgkmcnt(2)
	v_lshlrev_b32_e32 v19, 16, v62
	v_and_b32_e32 v47, 0xffff0000, v62
	v_lshlrev_b32_e32 v49, 16, v63
	v_and_b32_e32 v56, 0xffff0000, v63
	v_sub_f32_e32 v55, v47, v11
	v_sub_f32_e32 v54, v19, v10
	v_sub_f32_e32 v57, v56, v13
	v_sub_f32_e32 v56, v49, v12
	v_pk_mul_f32 v[56:57], v[44:45], v[56:57]
	v_pk_mul_f32 v[54:55], v[42:43], v[54:55]
	v_pk_mul_f32 v[56:57], v[34:35], v[56:57] op_sel_hi:[0,1]
	v_pk_mul_f32 v[54:55], v[34:35], v[54:55] op_sel_hi:[0,1]
	v_pk_mul_f32 v[62:63], v[192:193], v[48:49] op_sel_hi:[1,0]
	v_pk_mul_f32 v[72:73], v[190:191], v[48:49] op_sel_hi:[1,0]
	v_pk_fma_f32 v[54:55], v[30:31], v[62:63], v[54:55]
	v_pk_fma_f32 v[56:57], v[32:33], v[72:73], v[56:57]
	global_store_dwordx4 v[36:37], v[54:57], off offset:64 sc1
	s_waitcnt lgkmcnt(1)
	v_lshlrev_b32_e32 v19, 16, v64
	v_and_b32_e32 v47, 0xffff0000, v64
	v_lshlrev_b32_e32 v49, 16, v65
	v_and_b32_e32 v56, 0xffff0000, v65
	v_sub_f32_e32 v55, v47, v7
	v_sub_f32_e32 v54, v19, v6
	v_sub_f32_e32 v57, v56, v9
	v_sub_f32_e32 v56, v49, v8
	v_pk_mul_f32 v[56:57], v[60:61], v[56:57]
	v_pk_mul_f32 v[54:55], v[58:59], v[54:55]
	v_pk_mul_f32 v[56:57], v[34:35], v[56:57] op_sel_hi:[0,1]
	v_pk_mul_f32 v[54:55], v[34:35], v[54:55] op_sel_hi:[0,1]
	v_pk_mul_f32 v[62:63], v[188:189], v[48:49] op_sel_hi:[1,0]
	v_pk_mul_f32 v[64:65], v[186:187], v[48:49] op_sel_hi:[1,0]
	v_pk_fma_f32 v[54:55], v[50:51], v[62:63], v[54:55]
	v_pk_fma_f32 v[56:57], v[52:53], v[64:65], v[56:57]
	global_store_dwordx4 v[36:37], v[54:57], off offset:512 sc1
	s_waitcnt lgkmcnt(0)
	v_lshlrev_b32_e32 v19, 16, v70
	v_and_b32_e32 v47, 0xffff0000, v70
	v_lshlrev_b32_e32 v49, 16, v71
	v_and_b32_e32 v56, 0xffff0000, v71
	v_sub_f32_e32 v55, v47, v3
	v_sub_f32_e32 v54, v19, v2
	v_sub_f32_e32 v57, v56, v5
	v_sub_f32_e32 v56, v49, v4
	v_pk_mul_f32 v[56:57], v[76:77], v[56:57]
	v_pk_mul_f32 v[54:55], v[74:75], v[54:55]
	v_pk_mul_f32 v[56:57], v[34:35], v[56:57] op_sel_hi:[0,1]
	v_pk_mul_f32 v[54:55], v[34:35], v[54:55] op_sel_hi:[0,1]
	v_pk_mul_f32 v[62:63], v[184:185], v[48:49] op_sel_hi:[1,0]
	v_pk_mul_f32 v[48:49], v[182:183], v[48:49] op_sel_hi:[1,0]
	v_pk_fma_f32 v[54:55], v[66:67], v[62:63], v[54:55]
	v_pk_fma_f32 v[56:57], v[68:69], v[48:49], v[56:57]
	global_store_dwordx4 v[36:37], v[54:57], off offset:576 sc1
	v_or_b32_e32 v36, 32, v28
	v_lshl_add_u32 v19, v36, 2, s0
	ds_read2st64_b32 v[48:49], v19 offset1:4
	v_lshlrev_b32_e32 v19, 9, v36
	v_and_b32_e32 v19, 0x7fffdc00, v19
	v_mov_b32_e32 v37, v29
	v_add_u32_e32 v19, v38, v19
	v_lshl_add_u64 v[54:55], s[14:15], 0, v[36:37]
	v_add_u32_e32 v34, v19, v39
	v_lshlrev_b64 v[36:37], 13, v[54:55]
	ds_read_b64 v[54:55], v34
	v_add_u32_e32 v34, v19, v40
	v_add_u32_e32 v47, v19, v1
	v_add_u32_e32 v19, v19, v41
	ds_read_b64 v[62:63], v34
	ds_read_b64 v[64:65], v47
	ds_read_b64 v[70:71], v19
	s_waitcnt lgkmcnt(3)
	v_lshlrev_b32_e32 v19, 16, v54
	v_and_b32_e32 v34, 0xffff0000, v54
	v_lshlrev_b32_e32 v47, 16, v55
	v_and_b32_e32 v56, 0xffff0000, v55
	v_sub_f32_e32 v55, v34, v15
	v_sub_f32_e32 v54, v19, v14
	v_sub_f32_e32 v57, v56, v17
	v_sub_f32_e32 v56, v47, v16
	v_pk_mul_f32 v[56:57], v[24:25], v[56:57]
	v_pk_mul_f32 v[54:55], v[22:23], v[54:55]
	v_mov_b32_e32 v34, v49
	v_pk_mul_f32 v[54:55], v[34:35], v[54:55] op_sel_hi:[0,1]
	v_pk_mul_f32 v[56:57], v[34:35], v[56:57] op_sel_hi:[0,1]
	v_pk_mul_f32 v[72:73], v[180:181], v[48:49] op_sel_hi:[1,0]
	v_pk_mul_f32 v[78:79], v[178:179], v[48:49] op_sel_hi:[1,0]
	v_lshl_add_u64 v[36:37], s[92:93], 0, v[36:37]
	v_pk_fma_f32 v[56:57], v[20:21], v[78:79], v[56:57]
	v_pk_fma_f32 v[54:55], v[26:27], v[72:73], v[54:55]
	v_lshl_add_u64 v[36:37], v[36:37], 0, v[146:147]
	global_store_dwordx4 v[36:37], v[54:57], off sc1
	s_waitcnt lgkmcnt(2)
	v_lshlrev_b32_e32 v19, 16, v62
	v_and_b32_e32 v47, 0xffff0000, v62
	v_lshlrev_b32_e32 v49, 16, v63
	v_and_b32_e32 v56, 0xffff0000, v63
	v_sub_f32_e32 v55, v47, v11
	v_sub_f32_e32 v54, v19, v10
	v_sub_f32_e32 v57, v56, v13
	v_sub_f32_e32 v56, v49, v12
	v_pk_mul_f32 v[56:57], v[44:45], v[56:57]
	v_pk_mul_f32 v[54:55], v[42:43], v[54:55]
	v_pk_mul_f32 v[56:57], v[34:35], v[56:57] op_sel_hi:[0,1]
	v_pk_mul_f32 v[54:55], v[34:35], v[54:55] op_sel_hi:[0,1]
	v_pk_mul_f32 v[62:63], v[176:177], v[48:49] op_sel_hi:[1,0]
	v_pk_mul_f32 v[72:73], v[174:175], v[48:49] op_sel_hi:[1,0]
	v_pk_fma_f32 v[54:55], v[30:31], v[62:63], v[54:55]
	v_pk_fma_f32 v[56:57], v[32:33], v[72:73], v[56:57]
	global_store_dwordx4 v[36:37], v[54:57], off offset:64 sc1
	s_waitcnt lgkmcnt(1)
; #define PG8_LAS __attribute__((address_space(3)))
;     __device__ __forceinline__ void fused(f32x4 (&acc)[2][2][4][2], const Unit& u, int wr, int wc, int fr, int fq, PG8_LAS unsigned char* lds, int wid, int lane) const {
;     ...
;             for (int m = 0; m < 4; ++m) { const int r = ai * HALF + wr * 64 + m * 16 + fr; const float rs = Sr[r], rx = Sr[256 + r]; const size_t off = (rowg0 + r) * 2048 + col0;
; #pragma unroll
;                 for (int bj = 0; bj < 2; ++bj)
; #pragma unroll
;                     for (int n = 0; n < 2; ++n) { const int c8 = 16 * bj + 4 * wc + 2 * n + (fq >> 1);
;                         const u32x4 dummy = {0u, 0u, 0u, 0u}; (void)dummy;
;                         const unsigned long long hw = *(const PG8_LAS unsigned long long*)(lds + (r >> 1) * 1024 + (r & 1) * 512 + ((c8 ^ (r & 15)) * 16) + 8 * (fq & 1));
;                         const unsigned lo = (unsigned)hw, hi = (unsigned)(hw >> 32);
;                         const f32x4 h = (f32x4){__uint_as_float(lo << 16), __uint_as_float(lo & 0xffff0000u), __uint_as_float(hi << 16), __uint_as_float(hi & 0xffff0000u)};
;                         const f32x4 xr = (h - sh[bj][n]) * ia[bj][n] * rx;
;                         __builtin_nontemporal_store(xr + gg[bj][n] * (acc[ai][bj][m][n] * rs), (f32x4*)(out + off + bj * HALF + n * 16)); } }
	v_lshlrev_b32_e32 v19, 16, v64
	v_and_b32_e32 v47, 0xffff0000, v64
	v_lshlrev_b32_e32 v49, 16, v65
	v_and_b32_e32 v56, 0xffff0000, v65
	v_sub_f32_e32 v55, v47, v7
	v_sub_f32_e32 v54, v19, v6
	v_sub_f32_e32 v57, v56, v9
	v_sub_f32_e32 v56, v49, v8
	v_pk_mul_f32 v[56:57], v[60:61], v[56:57]
	v_pk_mul_f32 v[54:55], v[58:59], v[54:55]
	v_pk_mul_f32 v[56:57], v[34:35], v[56:57] op_sel_hi:[0,1]
	v_pk_mul_f32 v[54:55], v[34:35], v[54:55] op_sel_hi:[0,1]
	v_pk_mul_f32 v[62:63], v[172:173], v[48:49] op_sel_hi:[1,0]
	v_pk_mul_f32 v[64:65], v[170:171], v[48:49] op_sel_hi:[1,0]
	v_pk_fma_f32 v[54:55], v[50:51], v[62:63], v[54:55]
	v_pk_fma_f32 v[56:57], v[52:53], v[64:65], v[56:57]
	global_store_dwordx4 v[36:37], v[54:57], off offset:512 sc1
	s_waitcnt lgkmcnt(0)
	v_lshlrev_b32_e32 v19, 16, v70
	v_and_b32_e32 v47, 0xffff0000, v70
	v_lshlrev_b32_e32 v49, 16, v71
	v_and_b32_e32 v56, 0xffff0000, v71
	v_sub_f32_e32 v55, v47, v3
	v_sub_f32_e32 v54, v19, v2
	v_sub_f32_e32 v57, v56, v5
	v_sub_f32_e32 v56, v49, v4
	v_pk_mul_f32 v[56:57], v[76:77], v[56:57]
	v_pk_mul_f32 v[54:55], v[74:75], v[54:55]
	v_pk_mul_f32 v[56:57], v[34:35], v[56:57] op_sel_hi:[0,1]
	v_pk_mul_f32 v[54:55], v[34:35], v[54:55] op_sel_hi:[0,1]
	v_pk_mul_f32 v[62:63], v[168:169], v[48:49] op_sel_hi:[1,0]
	v_pk_mul_f32 v[48:49], v[166:167], v[48:49] op_sel_hi:[1,0]
	v_pk_fma_f32 v[54:55], v[66:67], v[62:63], v[54:55]
	v_pk_fma_f32 v[56:57], v[68:69], v[48:49], v[56:57]
	global_store_dwordx4 v[36:37], v[54:57], off offset:576 sc1
	v_or_b32_e32 v36, 48, v28
	v_lshl_add_u32 v19, v36, 2, s0
	ds_read2st64_b32 v[48:49], v19 offset1:4
	v_lshlrev_b32_e32 v19, 9, v36
	v_and_b32_e32 v19, 0x7ffffc00, v19
	v_mov_b32_e32 v37, v29
	v_add_u32_e32 v19, v38, v19
	v_lshl_add_u64 v[54:55], s[14:15], 0, v[36:37]
	v_add_u32_e32 v34, v19, v39
	v_lshlrev_b64 v[36:37], 13, v[54:55]
	ds_read_b64 v[54:55], v34
	v_add_u32_e32 v34, v19, v40
	v_add_u32_e32 v47, v19, v1
	v_add_u32_e32 v19, v19, v41
	ds_read_b64 v[62:63], v34
	ds_read_b64 v[64:65], v47
	ds_read_b64 v[70:71], v19
	s_waitcnt lgkmcnt(3)
	v_lshlrev_b32_e32 v19, 16, v54
	v_and_b32_e32 v34, 0xffff0000, v54
	v_lshlrev_b32_e32 v47, 16, v55
	v_and_b32_e32 v56, 0xffff0000, v55
	v_sub_f32_e32 v55, v34, v15
	v_sub_f32_e32 v54, v19, v14
	v_sub_f32_e32 v57, v56, v17
	v_sub_f32_e32 v56, v47, v16
	v_pk_mul_f32 v[56:57], v[24:25], v[56:57]
	v_pk_mul_f32 v[54:55], v[22:23], v[54:55]
	v_mov_b32_e32 v34, v49
	v_pk_mul_f32 v[54:55], v[34:35], v[54:55] op_sel_hi:[0,1]
	v_pk_mul_f32 v[56:57], v[34:35], v[56:57] op_sel_hi:[0,1]
	v_pk_mul_f32 v[72:73], v[164:165], v[48:49] op_sel_hi:[1,0]
	v_pk_mul_f32 v[78:79], v[160:161], v[48:49] op_sel_hi:[1,0]
	v_lshl_add_u64 v[36:37], s[92:93], 0, v[36:37]
	v_pk_fma_f32 v[56:57], v[20:21], v[78:79], v[56:57]
	v_pk_fma_f32 v[54:55], v[26:27], v[72:73], v[54:55]
	v_lshl_add_u64 v[36:37], v[36:37], 0, v[146:147]
	global_store_dwordx4 v[36:37], v[54:57], off sc1
	s_waitcnt lgkmcnt(2)
	v_lshlrev_b32_e32 v19, 16, v62
	v_and_b32_e32 v47, 0xffff0000, v62
	v_lshlrev_b32_e32 v49, 16, v63
	v_and_b32_e32 v56, 0xffff0000, v63
	v_sub_f32_e32 v55, v47, v11
	v_sub_f32_e32 v54, v19, v10
	v_sub_f32_e32 v57, v56, v13
	v_sub_f32_e32 v56, v49, v12
	v_pk_mul_f32 v[56:57], v[44:45], v[56:57]
	v_pk_mul_f32 v[54:55], v[42:43], v[54:55]
	v_pk_mul_f32 v[56:57], v[34:35], v[56:57] op_sel_hi:[0,1]
	v_pk_mul_f32 v[54:55], v[34:35], v[54:55] op_sel_hi:[0,1]
	v_pk_mul_f32 v[62:63], v[158:159], v[48:49] op_sel_hi:[1,0]
	v_pk_mul_f32 v[72:73], v[156:157], v[48:49] op_sel_hi:[1,0]
	v_pk_fma_f32 v[54:55], v[30:31], v[62:63], v[54:55]
	v_pk_fma_f32 v[56:57], v[32:33], v[72:73], v[56:57]
	global_store_dwordx4 v[36:37], v[54:57], off offset:64 sc1
	s_waitcnt lgkmcnt(1)
	v_lshlrev_b32_e32 v19, 16, v64
	v_and_b32_e32 v47, 0xffff0000, v64
	v_lshlrev_b32_e32 v49, 16, v65
	v_and_b32_e32 v56, 0xffff0000, v65
	v_sub_f32_e32 v55, v47, v7
	v_sub_f32_e32 v54, v19, v6
	v_sub_f32_e32 v57, v56, v9
	v_sub_f32_e32 v56, v49, v8
	v_pk_mul_f32 v[56:57], v[60:61], v[56:57]
	v_pk_mul_f32 v[54:55], v[58:59], v[54:55]
	v_pk_mul_f32 v[56:57], v[34:35], v[56:57] op_sel_hi:[0,1]
	v_pk_mul_f32 v[54:55], v[34:35], v[54:55] op_sel_hi:[0,1]
	v_pk_mul_f32 v[62:63], v[154:155], v[48:49] op_sel_hi:[1,0]
	v_pk_mul_f32 v[64:65], v[152:153], v[48:49] op_sel_hi:[1,0]
	v_pk_fma_f32 v[54:55], v[50:51], v[62:63], v[54:55]
	v_pk_fma_f32 v[56:57], v[52:53], v[64:65], v[56:57]
	global_store_dwordx4 v[36:37], v[54:57], off offset:512 sc1
	s_waitcnt lgkmcnt(0)
	v_lshlrev_b32_e32 v49, 16, v71
	v_lshlrev_b32_e32 v19, 16, v70
	v_and_b32_e32 v56, 0xffff0000, v71
	v_sub_f32_e32 v57, v56, v5
	v_sub_f32_e32 v56, v49, v4
	v_and_b32_e32 v47, 0xffff0000, v70
	v_pk_mul_f32 v[56:57], v[76:77], v[56:57]
	v_sub_f32_e32 v55, v47, v3
	v_sub_f32_e32 v54, v19, v2
	v_pk_mul_f32 v[56:57], v[34:35], v[56:57] op_sel_hi:[0,1]
	v_pk_mul_f32 v[62:63], v[150:151], v[48:49] op_sel_hi:[1,0]
	v_pk_mul_f32 v[48:49], v[148:149], v[48:49] op_sel_hi:[1,0]
	v_pk_mul_f32 v[54:55], v[74:75], v[54:55]
	v_pk_fma_f32 v[56:57], v[68:69], v[48:49], v[56:57]
	v_add_u32_e32 v48, 0x80, v28
	v_pk_mul_f32 v[54:55], v[34:35], v[54:55] op_sel_hi:[0,1]
	v_lshlrev_b32_e32 v34, 9, v48
	v_and_b32_e32 v34, 0x7fff9c00, v34
	v_pk_fma_f32 v[54:55], v[66:67], v[62:63], v[54:55]
	v_mov_b32_e32 v49, v29
	v_add_u32_e32 v34, v38, v34
	global_store_dwordx4 v[36:37], v[54:57], off offset:576 sc1
	v_add_u32_e32 v47, v34, v39
	v_add_u32_e32 v19, 0x400, v46
	v_lshl_add_u64 v[54:55], s[14:15], 0, v[48:49]
	v_lshlrev_b64 v[48:49], 13, v[54:55]
	ds_read_b64 v[54:55], v47
	ds_read2_b32 v[36:37], v19 offset0:128 offset1:144
	v_add_u32_e32 v47, v34, v40
	v_add_u32_e32 v56, v34, v1
	v_add_u32_e32 v34, v34, v41
	ds_read_b64 v[62:63], v47
	ds_read_b64 v[64:65], v56
	ds_read_b64 v[70:71], v34
	s_waitcnt lgkmcnt(4)
; #define PG8_LAS __attribute__((address_space(3)))
;     __device__ __forceinline__ void fused(f32x4 (&acc)[2][2][4][2], const Unit& u, int wr, int wc, int fr, int fq, PG8_LAS unsigned char* lds, int wid, int lane) const {
;     ...
;             for (int m = 0; m < 4; ++m) { const int r = ai * HALF + wr * 64 + m * 16 + fr; const float rs = Sr[r], rx = Sr[256 + r]; const size_t off = (rowg0 + r) * 2048 + col0;
; #pragma unroll
;                 for (int bj = 0; bj < 2; ++bj)
; #pragma unroll
;                     for (int n = 0; n < 2; ++n) { const int c8 = 16 * bj + 4 * wc + 2 * n + (fq >> 1);
;                         const u32x4 dummy = {0u, 0u, 0u, 0u}; (void)dummy;
;                         const unsigned long long hw = *(const PG8_LAS unsigned long long*)(lds + (r >> 1) * 1024 + (r & 1) * 512 + ((c8 ^ (r & 15)) * 16) + 8 * (fq & 1));
;                         const unsigned lo = (unsigned)hw, hi = (unsigned)(hw >> 32);
;                         const f32x4 h = (f32x4){__uint_as_float(lo << 16), __uint_as_float(lo & 0xffff0000u), __uint_as_float(hi << 16), __uint_as_float(hi & 0xffff0000u)};
;                         const f32x4 xr = (h - sh[bj][n]) * ia[bj][n] * rx;
;                         __builtin_nontemporal_store(xr + gg[bj][n] * (acc[ai][bj][m][n] * rs), (f32x4*)(out + off + bj * HALF + n * 16)); } }
	v_lshlrev_b32_e32 v34, 16, v54
	v_and_b32_e32 v47, 0xffff0000, v54
	v_lshlrev_b32_e32 v56, 16, v55
	v_and_b32_e32 v57, 0xffff0000, v55
	v_sub_f32_e32 v55, v47, v15
	v_sub_f32_e32 v54, v34, v14
	v_sub_f32_e32 v57, v57, v17
	v_sub_f32_e32 v56, v56, v16
	v_pk_mul_f32 v[56:57], v[24:25], v[56:57]
	v_pk_mul_f32 v[54:55], v[22:23], v[54:55]
	v_mov_b32_e32 v34, v35
	s_waitcnt lgkmcnt(3)
	v_pk_mul_f32 v[54:55], v[36:37], v[54:55] op_sel_hi:[0,1]
	v_pk_mul_f32 v[56:57], v[36:37], v[56:57] op_sel_hi:[0,1]
	v_pk_mul_f32 v[72:73], v[144:145], v[34:35] op_sel_hi:[1,0]
	v_pk_mul_f32 v[78:79], v[142:143], v[34:35] op_sel_hi:[1,0]
	v_lshl_add_u64 v[48:49], s[92:93], 0, v[48:49]
	v_pk_fma_f32 v[56:57], v[20:21], v[78:79], v[56:57]
	v_pk_fma_f32 v[54:55], v[26:27], v[72:73], v[54:55]
	v_lshl_add_u64 v[48:49], v[48:49], 0, v[146:147]
	global_store_dwordx4 v[48:49], v[54:57], off sc1
	s_waitcnt lgkmcnt(2)
	v_lshlrev_b32_e32 v35, 16, v62
	v_and_b32_e32 v47, 0xffff0000, v62
	v_lshlrev_b32_e32 v56, 16, v63
	v_and_b32_e32 v57, 0xffff0000, v63
	v_sub_f32_e32 v55, v47, v11
	v_sub_f32_e32 v54, v35, v10
	v_sub_f32_e32 v57, v57, v13
	v_sub_f32_e32 v56, v56, v12
	v_pk_mul_f32 v[56:57], v[44:45], v[56:57]
	v_pk_mul_f32 v[54:55], v[42:43], v[54:55]
	v_pk_mul_f32 v[56:57], v[36:37], v[56:57] op_sel_hi:[0,1]
	v_pk_mul_f32 v[54:55], v[36:37], v[54:55] op_sel_hi:[0,1]
	v_pk_mul_f32 v[62:63], v[140:141], v[34:35] op_sel_hi:[1,0]
	v_pk_mul_f32 v[72:73], v[138:139], v[34:35] op_sel_hi:[1,0]
	v_pk_fma_f32 v[54:55], v[30:31], v[62:63], v[54:55]
	v_pk_fma_f32 v[56:57], v[32:33], v[72:73], v[56:57]
	global_store_dwordx4 v[48:49], v[54:57], off offset:64 sc1
	s_waitcnt lgkmcnt(1)
	v_lshlrev_b32_e32 v35, 16, v64
	v_and_b32_e32 v47, 0xffff0000, v64
	v_lshlrev_b32_e32 v56, 16, v65
	v_and_b32_e32 v57, 0xffff0000, v65
	v_sub_f32_e32 v55, v47, v7
	v_sub_f32_e32 v54, v35, v6
	v_sub_f32_e32 v57, v57, v9
	v_sub_f32_e32 v56, v56, v8
	v_pk_mul_f32 v[56:57], v[60:61], v[56:57]
	v_pk_mul_f32 v[54:55], v[58:59], v[54:55]
	v_pk_mul_f32 v[56:57], v[36:37], v[56:57] op_sel_hi:[0,1]
	v_pk_mul_f32 v[54:55], v[36:37], v[54:55] op_sel_hi:[0,1]
	v_pk_mul_f32 v[62:63], v[136:137], v[34:35] op_sel_hi:[1,0]
	v_pk_mul_f32 v[64:65], v[134:135], v[34:35] op_sel_hi:[1,0]
	v_pk_fma_f32 v[54:55], v[50:51], v[62:63], v[54:55]
	v_pk_fma_f32 v[56:57], v[52:53], v[64:65], v[56:57]
	global_store_dwordx4 v[48:49], v[54:57], off offset:512 sc1
	s_waitcnt lgkmcnt(0)
	v_lshlrev_b32_e32 v35, 16, v70
	v_and_b32_e32 v47, 0xffff0000, v70
	v_lshlrev_b32_e32 v56, 16, v71
	v_and_b32_e32 v57, 0xffff0000, v71
	v_sub_f32_e32 v55, v47, v3
	v_sub_f32_e32 v54, v35, v2
	v_sub_f32_e32 v57, v57, v5
	v_sub_f32_e32 v56, v56, v4
	v_pk_mul_f32 v[56:57], v[76:77], v[56:57]
	v_pk_mul_f32 v[54:55], v[74:75], v[54:55]
	v_pk_mul_f32 v[56:57], v[36:37], v[56:57] op_sel_hi:[0,1]
	v_pk_mul_f32 v[54:55], v[36:37], v[54:55] op_sel_hi:[0,1]
	v_pk_mul_f32 v[62:63], v[132:133], v[34:35] op_sel_hi:[1,0]
	v_pk_mul_f32 v[34:35], v[130:131], v[34:35] op_sel_hi:[1,0]
	v_pk_fma_f32 v[54:55], v[66:67], v[62:63], v[54:55]
	v_pk_fma_f32 v[56:57], v[68:69], v[34:35], v[56:57]
	global_store_dwordx4 v[48:49], v[54:57], off offset:576 sc1
	v_add_u32_e32 v48, 0x90, v28
	v_lshlrev_b32_e32 v36, 9, v48
	v_mov_b32_e32 v49, v29
	v_and_b32_e32 v36, 0x7fffbc00, v36
	ds_read2_b32 v[34:35], v46 offset0:144 offset1:160
	v_lshl_add_u64 v[46:47], s[14:15], 0, v[48:49]
	v_add_u32_e32 v36, v38, v36
	v_lshlrev_b64 v[54:55], 13, v[46:47]
	v_add_u32_e32 v46, v36, v39
	ds_read_b64 v[46:47], v46
	v_add_u32_e32 v48, v36, v40
	v_add_u32_e32 v49, v36, v1
	v_add_u32_e32 v36, v36, v41
	ds_read_b64 v[56:57], v48
	ds_read_b64 v[62:63], v49
	ds_read_b64 v[64:65], v36
	s_waitcnt lgkmcnt(3)
	v_lshlrev_b32_e32 v36, 16, v46
	v_and_b32_e32 v46, 0xffff0000, v46
	v_lshlrev_b32_e32 v48, 16, v47
	v_and_b32_e32 v49, 0xffff0000, v47
	v_sub_f32_e32 v47, v46, v15
	v_sub_f32_e32 v46, v36, v14
	v_sub_f32_e32 v49, v49, v17
	v_sub_f32_e32 v48, v48, v16
	v_pk_mul_f32 v[48:49], v[24:25], v[48:49]
	v_pk_mul_f32 v[46:47], v[22:23], v[46:47]
	v_mov_b32_e32 v36, v37
	v_pk_mul_f32 v[46:47], v[36:37], v[46:47] op_sel_hi:[0,1]
	v_pk_mul_f32 v[48:49], v[36:37], v[48:49] op_sel_hi:[0,1]
	v_pk_mul_f32 v[70:71], v[128:129], v[34:35] op_sel_hi:[1,0]
	v_pk_mul_f32 v[72:73], v[126:127], v[34:35] op_sel_hi:[1,0]
	v_lshl_add_u64 v[54:55], s[92:93], 0, v[54:55]
	v_pk_fma_f32 v[48:49], v[20:21], v[72:73], v[48:49]
	v_pk_fma_f32 v[46:47], v[26:27], v[70:71], v[46:47]
	v_lshl_add_u64 v[54:55], v[54:55], 0, v[146:147]
	global_store_dwordx4 v[54:55], v[46:49], off sc1
	s_waitcnt lgkmcnt(2)
	v_lshlrev_b32_e32 v37, 16, v56
	v_pk_mul_f32 v[70:71], v[122:123], v[34:35] op_sel_hi:[1,0]
	v_and_b32_e32 v46, 0xffff0000, v56
	v_lshlrev_b32_e32 v48, 16, v57
	v_and_b32_e32 v49, 0xffff0000, v57
	v_sub_f32_e32 v47, v46, v11
	v_sub_f32_e32 v46, v37, v10
	v_sub_f32_e32 v49, v49, v13
	v_sub_f32_e32 v48, v48, v12
	v_pk_mul_f32 v[48:49], v[44:45], v[48:49]
	v_pk_mul_f32 v[46:47], v[42:43], v[46:47]
	v_pk_mul_f32 v[48:49], v[36:37], v[48:49] op_sel_hi:[0,1]
	v_pk_mul_f32 v[46:47], v[36:37], v[46:47] op_sel_hi:[0,1]
	v_pk_mul_f32 v[56:57], v[124:125], v[34:35] op_sel_hi:[1,0]
	v_pk_fma_f32 v[48:49], v[32:33], v[70:71], v[48:49]
	v_pk_fma_f32 v[46:47], v[30:31], v[56:57], v[46:47]
	global_store_dwordx4 v[54:55], v[46:49], off offset:64 sc1
	s_waitcnt lgkmcnt(1)
; #define PG8_LAS __attribute__((address_space(3)))
;     __device__ __forceinline__ void fused(f32x4 (&acc)[2][2][4][2], const Unit& u, int wr, int wc, int fr, int fq, PG8_LAS unsigned char* lds, int wid, int lane) const {
;     ...
;             for (int m = 0; m < 4; ++m) { const int r = ai * HALF + wr * 64 + m * 16 + fr; const float rs = Sr[r], rx = Sr[256 + r]; const size_t off = (rowg0 + r) * 2048 + col0;
; #pragma unroll
;                 for (int bj = 0; bj < 2; ++bj)
; #pragma unroll
;                     for (int n = 0; n < 2; ++n) { const int c8 = 16 * bj + 4 * wc + 2 * n + (fq >> 1);
;                         const u32x4 dummy = {0u, 0u, 0u, 0u}; (void)dummy;
;                         const unsigned long long hw = *(const PG8_LAS unsigned long long*)(lds + (r >> 1) * 1024 + (r & 1) * 512 + ((c8 ^ (r & 15)) * 16) + 8 * (fq & 1));
;                         const unsigned lo = (unsigned)hw, hi = (unsigned)(hw >> 32);
;                         const f32x4 h = (f32x4){__uint_as_float(lo << 16), __uint_as_float(lo & 0xffff0000u), __uint_as_float(hi << 16), __uint_as_float(hi & 0xffff0000u)};
;                         const f32x4 xr = (h - sh[bj][n]) * ia[bj][n] * rx;
;                         __builtin_nontemporal_store(xr + gg[bj][n] * (acc[ai][bj][m][n] * rs), (f32x4*)(out + off + bj * HALF + n * 16)); } }
	v_lshlrev_b32_e32 v37, 16, v62
	v_pk_mul_f32 v[56:57], v[120:121], v[34:35] op_sel_hi:[1,0]
	v_and_b32_e32 v46, 0xffff0000, v62
	v_lshlrev_b32_e32 v48, 16, v63
	v_and_b32_e32 v49, 0xffff0000, v63
	v_sub_f32_e32 v47, v46, v7
	v_sub_f32_e32 v46, v37, v6
	v_sub_f32_e32 v49, v49, v9
	v_sub_f32_e32 v48, v48, v8
	v_pk_mul_f32 v[48:49], v[60:61], v[48:49]
	v_pk_mul_f32 v[46:47], v[58:59], v[46:47]
	v_pk_mul_f32 v[48:49], v[36:37], v[48:49] op_sel_hi:[0,1]
	v_pk_mul_f32 v[46:47], v[36:37], v[46:47] op_sel_hi:[0,1]
	v_pk_mul_f32 v[62:63], v[118:119], v[34:35] op_sel_hi:[1,0]
	v_pk_fma_f32 v[46:47], v[50:51], v[56:57], v[46:47]
	v_pk_fma_f32 v[48:49], v[52:53], v[62:63], v[48:49]
	global_store_dwordx4 v[54:55], v[46:49], off offset:512 sc1
	s_waitcnt lgkmcnt(0)
	v_lshlrev_b32_e32 v37, 16, v64
	v_pk_mul_f32 v[56:57], v[116:117], v[34:35] op_sel_hi:[1,0]
	v_and_b32_e32 v46, 0xffff0000, v64
	v_lshlrev_b32_e32 v48, 16, v65
	v_and_b32_e32 v49, 0xffff0000, v65
	v_sub_f32_e32 v47, v46, v3
	v_sub_f32_e32 v46, v37, v2
	v_sub_f32_e32 v49, v49, v5
	v_sub_f32_e32 v48, v48, v4
	v_pk_mul_f32 v[48:49], v[76:77], v[48:49]
	v_pk_mul_f32 v[46:47], v[74:75], v[46:47]
	s_nop 0
	v_pk_mul_f32 v[46:47], v[36:37], v[46:47] op_sel_hi:[0,1]
	v_pk_mul_f32 v[36:37], v[36:37], v[48:49] op_sel_hi:[0,1]
	v_pk_mul_f32 v[48:49], v[114:115], v[34:35] op_sel_hi:[1,0]
	v_pk_fma_f32 v[46:47], v[66:67], v[56:57], v[46:47]
	v_pk_fma_f32 v[48:49], v[68:69], v[48:49], v[36:37]
	global_store_dwordx4 v[54:55], v[46:49], off offset:576 sc1
	ds_read2_b32 v[36:37], v19 offset0:160 offset1:176
	s_nop 0
	v_add_u32_e32 v46, 0xa0, v28
	v_lshlrev_b32_e32 v19, 9, v46
	v_and_b32_e32 v19, 0x7fffdc00, v19
	v_add_u32_e32 v19, v38, v19
	v_mov_b32_e32 v47, v29
	v_add_u32_e32 v34, v19, v39
	v_lshl_add_u64 v[48:49], s[14:15], 0, v[46:47]
	ds_read_b64 v[46:47], v34
	v_lshlrev_b64 v[54:55], 13, v[48:49]
	v_add_u32_e32 v34, v19, v40
	v_add_u32_e32 v48, v19, v1
	v_add_u32_e32 v19, v19, v41
	ds_read_b64 v[56:57], v34
	ds_read_b64 v[62:63], v48
	ds_read_b64 v[64:65], v19
	s_waitcnt lgkmcnt(3)
	v_lshlrev_b32_e32 v19, 16, v46
	v_and_b32_e32 v34, 0xffff0000, v46
	v_lshlrev_b32_e32 v48, 16, v47
	v_and_b32_e32 v49, 0xffff0000, v47
	v_sub_f32_e32 v47, v34, v15
	v_sub_f32_e32 v46, v19, v14
	v_sub_f32_e32 v49, v49, v17
	v_sub_f32_e32 v48, v48, v16
	v_pk_mul_f32 v[48:49], v[24:25], v[48:49]
	v_pk_mul_f32 v[46:47], v[22:23], v[46:47]
	v_mov_b32_e32 v34, v35
	v_pk_mul_f32 v[46:47], v[36:37], v[46:47] op_sel_hi:[0,1]
	v_pk_mul_f32 v[48:49], v[36:37], v[48:49] op_sel_hi:[0,1]
	v_pk_mul_f32 v[70:71], v[112:113], v[34:35] op_sel_hi:[1,0]
	v_pk_mul_f32 v[72:73], v[110:111], v[34:35] op_sel_hi:[1,0]
	v_lshl_add_u64 v[54:55], s[92:93], 0, v[54:55]
	v_pk_fma_f32 v[48:49], v[20:21], v[72:73], v[48:49]
	v_pk_fma_f32 v[46:47], v[26:27], v[70:71], v[46:47]
	v_lshl_add_u64 v[54:55], v[54:55], 0, v[146:147]
	global_store_dwordx4 v[54:55], v[46:49], off sc1
	s_waitcnt lgkmcnt(2)
	v_lshlrev_b32_e32 v19, 16, v56
	v_and_b32_e32 v35, 0xffff0000, v56
	v_lshlrev_b32_e32 v48, 16, v57
	v_and_b32_e32 v49, 0xffff0000, v57
	v_sub_f32_e32 v47, v35, v11
	v_sub_f32_e32 v46, v19, v10
	v_sub_f32_e32 v49, v49, v13
	v_sub_f32_e32 v48, v48, v12
	v_pk_mul_f32 v[48:49], v[44:45], v[48:49]
	v_pk_mul_f32 v[46:47], v[42:43], v[46:47]
	v_pk_mul_f32 v[48:49], v[36:37], v[48:49] op_sel_hi:[0,1]
	v_pk_mul_f32 v[46:47], v[36:37], v[46:47] op_sel_hi:[0,1]
	v_pk_mul_f32 v[56:57], v[108:109], v[34:35] op_sel_hi:[1,0]
	v_pk_mul_f32 v[70:71], v[106:107], v[34:35] op_sel_hi:[1,0]
	v_pk_fma_f32 v[46:47], v[30:31], v[56:57], v[46:47]
	v_pk_fma_f32 v[48:49], v[32:33], v[70:71], v[48:49]
	global_store_dwordx4 v[54:55], v[46:49], off offset:64 sc1
	s_waitcnt lgkmcnt(1)
	v_lshlrev_b32_e32 v19, 16, v62
	v_and_b32_e32 v35, 0xffff0000, v62
	v_lshlrev_b32_e32 v48, 16, v63
	v_and_b32_e32 v49, 0xffff0000, v63
	v_sub_f32_e32 v47, v35, v7
	v_sub_f32_e32 v46, v19, v6
	v_sub_f32_e32 v49, v49, v9
	v_sub_f32_e32 v48, v48, v8
	v_pk_mul_f32 v[48:49], v[60:61], v[48:49]
	v_pk_mul_f32 v[46:47], v[58:59], v[46:47]
	v_pk_mul_f32 v[48:49], v[36:37], v[48:49] op_sel_hi:[0,1]
	v_pk_mul_f32 v[46:47], v[36:37], v[46:47] op_sel_hi:[0,1]
	v_pk_mul_f32 v[56:57], v[104:105], v[34:35] op_sel_hi:[1,0]
	v_pk_mul_f32 v[62:63], v[102:103], v[34:35] op_sel_hi:[1,0]
	v_pk_fma_f32 v[46:47], v[50:51], v[56:57], v[46:47]
	v_pk_fma_f32 v[48:49], v[52:53], v[62:63], v[48:49]
	global_store_dwordx4 v[54:55], v[46:49], off offset:512 sc1
	s_waitcnt lgkmcnt(0)
; #define PG8_LAS __attribute__((address_space(3)))
;     __device__ __forceinline__ void fused(f32x4 (&acc)[2][2][4][2], const Unit& u, int wr, int wc, int fr, int fq, PG8_LAS unsigned char* lds, int wid, int lane) const {
;     ...
;             for (int m = 0; m < 4; ++m) { const int r = ai * HALF + wr * 64 + m * 16 + fr; const float rs = Sr[r], rx = Sr[256 + r]; const size_t off = (rowg0 + r) * 2048 + col0;
; #pragma unroll
;                 for (int bj = 0; bj < 2; ++bj)
; #pragma unroll
;                     for (int n = 0; n < 2; ++n) { const int c8 = 16 * bj + 4 * wc + 2 * n + (fq >> 1);
;                         const u32x4 dummy = {0u, 0u, 0u, 0u}; (void)dummy;
;                         const unsigned long long hw = *(const PG8_LAS unsigned long long*)(lds + (r >> 1) * 1024 + (r & 1) * 512 + ((c8 ^ (r & 15)) * 16) + 8 * (fq & 1));
;                         const unsigned lo = (unsigned)hw, hi = (unsigned)(hw >> 32);
;                         const f32x4 h = (f32x4){__uint_as_float(lo << 16), __uint_as_float(lo & 0xffff0000u), __uint_as_float(hi << 16), __uint_as_float(hi & 0xffff0000u)};
;                         const f32x4 xr = (h - sh[bj][n]) * ia[bj][n] * rx;
;                         __builtin_nontemporal_store(xr + gg[bj][n] * (acc[ai][bj][m][n] * rs), (f32x4*)(out + off + bj * HALF + n * 16)); } }
; __global__ void __launch_bounds__(NWAVES * 64, 2) hymba_fwd(Args args) {
;     ...
;         { const int bx = (int)blockIdx.x, sel = (bx >> 3) & 3; if (sel == 1 || sel == 2) { __syncthreads(); p6_row(args, C, (bx >> 5) * 16 + (sel - 1) * 8 + (bx & 7)); } }
	v_lshlrev_b32_e32 v19, 16, v64
	v_add_u32_e32 v28, 0xb0, v28
	v_lshlrev_b32_e32 v48, 16, v65
	v_and_b32_e32 v49, 0xffff0000, v65
	v_sub_f32_e32 v49, v49, v5
	v_sub_f32_e32 v48, v48, v4
	v_and_b32_e32 v35, 0xffff0000, v64
	v_sub_f32_e32 v46, v19, v2
	v_pk_mul_f32 v[48:49], v[76:77], v[48:49]
	v_lshlrev_b32_e32 v19, 9, v28
	v_sub_f32_e32 v47, v35, v3
	v_pk_mul_f32 v[48:49], v[36:37], v[48:49] op_sel_hi:[0,1]
	v_pk_mul_f32 v[56:57], v[100:101], v[34:35] op_sel_hi:[1,0]
	v_pk_mul_f32 v[34:35], v[98:99], v[34:35] op_sel_hi:[1,0]
	v_and_b32_e32 v19, 0x7ffffc00, v19
	v_pk_fma_f32 v[48:49], v[68:69], v[34:35], v[48:49]
	v_lshl_add_u64 v[34:35], s[14:15], 0, v[28:29]
	v_add_u32_e32 v19, v38, v19
	v_lshlrev_b64 v[28:29], 13, v[34:35]
	v_add_u32_e32 v34, v19, v39
	ds_read_b64 v[34:35], v34
	v_pk_mul_f32 v[46:47], v[74:75], v[46:47]
	v_add_u32_e32 v1, v19, v1
	v_pk_mul_f32 v[46:47], v[36:37], v[46:47] op_sel_hi:[0,1]
	v_pk_fma_f32 v[46:47], v[66:67], v[56:57], v[46:47]
	global_store_dwordx4 v[54:55], v[46:49], off offset:576 sc1
	v_add_u32_e32 v36, v19, v40
	v_add_u32_e32 v19, v19, v41
	ds_read_b64 v[38:39], v36
	ds_read_b64 v[40:41], v1
	ds_read_b64 v[46:47], v19
	s_waitcnt lgkmcnt(3)
	v_lshlrev_b32_e32 v1, 16, v34
	v_and_b32_e32 v19, 0xffff0000, v34
	v_lshlrev_b32_e32 v34, 16, v35
	v_and_b32_e32 v35, 0xffff0000, v35
	v_sub_f32_e32 v15, v19, v15
	v_sub_f32_e32 v14, v1, v14
	v_sub_f32_e32 v17, v35, v17
	v_sub_f32_e32 v16, v34, v16
	v_pk_mul_f32 v[16:17], v[24:25], v[16:17]
	v_pk_mul_f32 v[14:15], v[22:23], v[14:15]
	v_mov_b32_e32 v22, v37
	v_pk_mul_f32 v[16:17], v[22:23], v[16:17] op_sel_hi:[0,1]
	v_pk_mul_f32 v[34:35], v[94:95], v[18:19] op_sel_hi:[1,0]
	v_pk_mul_f32 v[14:15], v[22:23], v[14:15] op_sel_hi:[0,1]
	v_pk_mul_f32 v[24:25], v[96:97], v[18:19] op_sel_hi:[1,0]
	v_pk_fma_f32 v[16:17], v[20:21], v[34:35], v[16:17]
	v_lshl_add_u64 v[20:21], s[92:93], 0, v[28:29]
	v_pk_fma_f32 v[14:15], v[26:27], v[24:25], v[14:15]
	v_lshl_add_u64 v[20:21], v[20:21], 0, v[146:147]
	global_store_dwordx4 v[20:21], v[14:17], off sc1
	s_waitcnt lgkmcnt(2)
	v_lshlrev_b32_e32 v1, 16, v38
	v_sub_f32_e32 v10, v1, v10
	v_and_b32_e32 v14, 0xffff0000, v38
	v_lshlrev_b32_e32 v15, 16, v39
	v_and_b32_e32 v16, 0xffff0000, v39
	v_sub_f32_e32 v11, v14, v11
	v_sub_f32_e32 v13, v16, v13
	v_sub_f32_e32 v12, v15, v12
	v_pk_mul_f32 v[12:13], v[44:45], v[12:13]
	v_pk_mul_f32 v[10:11], v[42:43], v[10:11]
	v_pk_mul_f32 v[12:13], v[22:23], v[12:13] op_sel_hi:[0,1]
	v_pk_mul_f32 v[10:11], v[22:23], v[10:11] op_sel_hi:[0,1]
	v_pk_mul_f32 v[14:15], v[92:93], v[18:19] op_sel_hi:[1,0]
	v_pk_mul_f32 v[16:17], v[90:91], v[18:19] op_sel_hi:[1,0]
	v_pk_fma_f32 v[10:11], v[30:31], v[14:15], v[10:11]
	v_pk_fma_f32 v[12:13], v[32:33], v[16:17], v[12:13]
	global_store_dwordx4 v[20:21], v[10:13], off offset:64 sc1
	s_waitcnt lgkmcnt(1)
	v_lshlrev_b32_e32 v1, 16, v40
	v_sub_f32_e32 v6, v1, v6
	v_and_b32_e32 v10, 0xffff0000, v40
	v_lshlrev_b32_e32 v11, 16, v41
	v_and_b32_e32 v12, 0xffff0000, v41
	v_sub_f32_e32 v7, v10, v7
	v_sub_f32_e32 v9, v12, v9
	v_sub_f32_e32 v8, v11, v8
	v_pk_mul_f32 v[8:9], v[60:61], v[8:9]
	v_pk_mul_f32 v[6:7], v[58:59], v[6:7]
	v_pk_mul_f32 v[8:9], v[22:23], v[8:9] op_sel_hi:[0,1]
	v_pk_mul_f32 v[6:7], v[22:23], v[6:7] op_sel_hi:[0,1]
	v_pk_mul_f32 v[10:11], v[88:89], v[18:19] op_sel_hi:[1,0]
	v_pk_mul_f32 v[12:13], v[86:87], v[18:19] op_sel_hi:[1,0]
	v_pk_fma_f32 v[6:7], v[50:51], v[10:11], v[6:7]
	v_pk_fma_f32 v[8:9], v[52:53], v[12:13], v[8:9]
	global_store_dwordx4 v[20:21], v[6:9], off offset:512 sc1
	s_waitcnt lgkmcnt(0)
	v_lshlrev_b32_e32 v1, 16, v46
	v_sub_f32_e32 v2, v1, v2
	v_and_b32_e32 v6, 0xffff0000, v46
	v_lshlrev_b32_e32 v7, 16, v47
	v_and_b32_e32 v8, 0xffff0000, v47
	v_sub_f32_e32 v3, v6, v3
	v_sub_f32_e32 v5, v8, v5
	v_sub_f32_e32 v4, v7, v4
	v_pk_mul_f32 v[4:5], v[76:77], v[4:5]
	v_pk_mul_f32 v[2:3], v[74:75], v[2:3]
	v_pk_mul_f32 v[4:5], v[22:23], v[4:5] op_sel_hi:[0,1]
	v_pk_mul_f32 v[2:3], v[22:23], v[2:3] op_sel_hi:[0,1]
	v_pk_mul_f32 v[6:7], v[84:85], v[18:19] op_sel_hi:[1,0]
	v_pk_mul_f32 v[8:9], v[82:83], v[18:19] op_sel_hi:[1,0]
	v_pk_fma_f32 v[2:3], v[66:67], v[6:7], v[2:3]
	v_pk_fma_f32 v[4:5], v[68:69], v[8:9], v[4:5]
	global_store_dwordx4 v[20:21], v[2:5], off offset:576 sc1
	s_bfe_u32 s2, s83, 0x20003
	s_add_i32 s0, s2, -1
	s_cmp_gt_u32 s0, 1
	s_cbranch_scc0 .LBB0_1052
